# Loop-edge edit (asm guide 7.11): GEMM K-loop counter/pointer/exit-test SALU moved in front of the closing barrier; plus dil 4th branch-test site; on top of v32
# baseline (speedup 1.0000x reference)
; #define PG8_STAGE(bufoff, gbase, voff) do { _Pragma("unroll") for (int _i = 0; _i < 2; ++_i) \
;         __builtin_amdgcn_global_load_lds((const unsigned*)((const char*)(gbase) + (voff)[_i]), (PG8_LAS unsigned*)(lds + (bufoff) + ldsw + _i * 8192), 16, 0, 0); } while (0)
; #define PG8_LDA(dst, b, h) do { _Pragma("unroll") for (int m = 0; m < 4; ++m) _Pragma("unroll") for (int k = 0; k < 2; ++k) dst[m][k] = *(const PG8_LAS bf16x8*)(lds + PG8_SA(b, h) + aoff + m * 2048 + k * 1024); } while (0)
; #define PG8_LDB(dst, b, h) do { _Pragma("unroll") for (int n = 0; n < 2; ++n) _Pragma("unroll") for (int k = 0; k < 2; ++k) dst[n][k] = *(const PG8_LAS bf16x8*)(lds + PG8_SB(b, h) + boff + n * 2048 + k * 1024); } while (0)
; #define PG8_MMA(ai, bj, At, Bt) do { __builtin_amdgcn_s_setprio(1); _Pragma("unroll") for (int m = 0; m < 4; ++m) _Pragma("unroll") for (int n = 0; n < 2; ++n) _Pragma("unroll") for (int k = 0; k < 2; ++k) \
;         acc[ai][bj][m][n] = __builtin_amdgcn_mfma_f32_16x16x32_bf16(Bt[n][k], At[m][k], acc[ai][bj][m][n], 0, 0, 0); __builtin_amdgcn_s_setprio(0); } while (0)
; #define PG8_WAIT_V(n) asm volatile("s_waitcnt vmcnt(" #n ")" ::: "memory")
; #define PG8_WAIT_L(n) asm volatile("s_waitcnt lgkmcnt(" #n ")" ::: "memory")
; template <class Epi, class Sched, bool ALIGN_EPI = false, bool SP2 = false>
; __device__ __forceinline__ void gemm_phase(PG8_LAS unsigned char* lds, const Gemm g, const Sched& S, const Epi& E) {
;     ...
;             const bool last = (t == nt - 2);
;             const char* a1 = cA + (size_t)(t + 1) * kstep;
;             const char* a2 = last ? nA : cA + (size_t)(t + 2) * kstep; const char* b2 = last ? nB : cB + (size_t)(t + 2) * kstep;
;             const char* a3 = a2 + kstep; const char* b3 = b2 + kstep;
;             if (last && has_next) S.a_ready(nxt);
;             if constexpr (SP2) {
;             PG8_LDB(B0, 0, 0); PG8_LDB(B1, 0, 1); PG8_SCHED; PG8_LDA(At, 0, 0); PG8_STAGE(PG8_SA(1, 1), a1 + hstepA, voffA);
;             PG8_WAIT_V(8); PG8_WAIT_L(0); PG8_BAR; PG8_MMA(0, 0, At, B0); PG8_MMA(0, 1, At, B1); PG8_BAR; PG8_SCHED;
;             PG8_LDA(At, 0, 1); PG8_STAGE(PG8_SB(0, 0), b2, voffB); PG8_STAGE(PG8_SB(0, 1), b2 + hstepB, voffB); PG8_STAGE(PG8_SA(0, 0), a2, voffA);
;             PG8_WAIT_V(8); PG8_WAIT_L(0); PG8_BAR; PG8_MMA(1, 0, At, B0); PG8_MMA(1, 1, At, B1); PG8_BAR; PG8_SCHED;
.LBB0_254:
	s_add_u32 s28, s26, 0xfffc0080
	s_addc_u32 s29, s27, -1
	s_add_i32 s53, 0, 0x10000
	s_cmp_eq_u32 s52, 12
	s_cselect_b32 s31, s7, s29
	s_cselect_b32 s30, s9, s28
	v_add_u32_e32 v150, s53, v153
	s_cselect_b32 s29, s19, s51
	s_cselect_b32 s28, s21, s50
	s_add_i32 s56, 0, 0x14000
	ds_read_b128 v[142:145], v150
	ds_read_b128 v[146:149], v150 offset:1024
	ds_read_b128 v[158:161], v150 offset:2048
	ds_read_b128 v[162:165], v150 offset:3072
	v_add_u32_e32 v150, s56, v153
	ds_read_b128 v[166:169], v150
	ds_read_b128 v[170:173], v150 offset:1024
	ds_read_b128 v[174:177], v150 offset:2048
	ds_read_b128 v[178:181], v150 offset:3072
	v_lshl_add_u64 v[150:151], s[26:27], 0, v[138:139]
	s_add_i32 m0, s40, 0xc000
	ds_read_b128 v[182:185], v156
	ds_read_b128 v[202:205], v156 offset:1024
	ds_read_b128 v[206:209], v156 offset:2048
	ds_read_b128 v[210:213], v156 offset:3072
	ds_read_b128 v[232:235], v156 offset:4096
	ds_read_b128 v[236:239], v156 offset:5120
	ds_read_b128 v[240:243], v156 offset:6144
	ds_read_b128 v[244:247], v156 offset:7168
	global_load_lds_dwordx4 v[150:151], off
	v_lshl_add_u64 v[150:151], s[26:27], 0, v[140:141]
	s_add_i32 m0, s40, 0xe000
	s_nop 0
	global_load_lds_dwordx4 v[150:151], off
	s_waitcnt vmcnt(8)
	s_waitcnt lgkmcnt(0)
	s_barrier
	s_setprio 1
	s_waitcnt lgkmcnt(0)
	v_mfma_f32_16x16x32_bf16 v[126:129], v[142:145], v[182:185], v[126:129]
	v_mfma_f32_16x16x32_bf16 v[122:125], v[158:161], v[182:185], v[122:125]
	v_mfma_f32_16x16x32_bf16 v[110:113], v[142:145], v[206:209], v[110:113]
	v_mfma_f32_16x16x32_bf16 v[106:109], v[158:161], v[206:209], v[106:109]
	v_mfma_f32_16x16x32_bf16 v[94:97], v[142:145], v[232:235], v[94:97]
	v_mfma_f32_16x16x32_bf16 v[90:93], v[158:161], v[232:235], v[90:93]
	v_mfma_f32_16x16x32_bf16 v[78:81], v[142:145], v[240:243], v[78:81]
	v_mfma_f32_16x16x32_bf16 v[74:77], v[158:161], v[240:243], v[74:77]
	v_mfma_f32_16x16x32_bf16 v[126:129], v[146:149], v[202:205], v[126:129]
	v_mfma_f32_16x16x32_bf16 v[122:125], v[162:165], v[202:205], v[122:125]
	v_mfma_f32_16x16x32_bf16 v[110:113], v[146:149], v[210:213], v[110:113]
	v_mfma_f32_16x16x32_bf16 v[106:109], v[162:165], v[210:213], v[106:109]
	v_mfma_f32_16x16x32_bf16 v[94:97], v[146:149], v[236:239], v[94:97]
	v_mfma_f32_16x16x32_bf16 v[90:93], v[162:165], v[236:239], v[90:93]
	v_mfma_f32_16x16x32_bf16 v[78:81], v[146:149], v[244:247], v[78:81]
	v_mfma_f32_16x16x32_bf16 v[74:77], v[162:165], v[244:247], v[74:77]
	s_setprio 0
	s_setprio 1
	v_mfma_f32_16x16x32_bf16 v[118:121], v[166:169], v[182:185], v[118:121]
	v_mfma_f32_16x16x32_bf16 v[114:117], v[174:177], v[182:185], v[114:117]
	v_mfma_f32_16x16x32_bf16 v[102:105], v[166:169], v[206:209], v[102:105]
	v_mfma_f32_16x16x32_bf16 v[98:101], v[174:177], v[206:209], v[98:101]
	v_mfma_f32_16x16x32_bf16 v[86:89], v[166:169], v[232:235], v[86:89]
	v_mfma_f32_16x16x32_bf16 v[82:85], v[174:177], v[232:235], v[82:85]
	v_mfma_f32_16x16x32_bf16 v[70:73], v[166:169], v[240:243], v[70:73]
	v_mfma_f32_16x16x32_bf16 v[66:69], v[174:177], v[240:243], v[66:69]
	v_mfma_f32_16x16x32_bf16 v[118:121], v[170:173], v[202:205], v[118:121]
	v_mfma_f32_16x16x32_bf16 v[114:117], v[178:181], v[202:205], v[114:117]
	v_mfma_f32_16x16x32_bf16 v[102:105], v[170:173], v[210:213], v[102:105]
	v_mfma_f32_16x16x32_bf16 v[98:101], v[178:181], v[210:213], v[98:101]
	v_mfma_f32_16x16x32_bf16 v[86:89], v[170:173], v[236:239], v[86:89]
	v_mfma_f32_16x16x32_bf16 v[82:85], v[178:181], v[236:239], v[82:85]
	v_mfma_f32_16x16x32_bf16 v[70:73], v[170:173], v[244:247], v[70:73]
	v_mfma_f32_16x16x32_bf16 v[66:69], v[178:181], v[244:247], v[66:69]
	s_setprio 0
	s_barrier
	s_add_i32 s53, s53, s39
	v_lshl_add_u64 v[150:151], s[28:29], 0, v[132:133]
	s_mov_b32 m0, s53
	ds_read_b128 v[182:185], v156 offset:16384
	ds_read_b128 v[202:205], v156 offset:17408
	ds_read_b128 v[206:209], v156 offset:18432
	ds_read_b128 v[210:213], v156 offset:19456
	ds_read_b128 v[232:235], v156 offset:20480
	ds_read_b128 v[236:239], v156 offset:21504
	ds_read_b128 v[240:243], v156 offset:22528
	ds_read_b128 v[244:247], v156 offset:23552
	global_load_lds_dwordx4 v[150:151], off
	s_add_i32 m0, s53, 0x2000
	s_add_u32 s54, s28, 0x40000
	v_lshl_add_u64 v[186:187], s[28:29], 0, v[136:137]
	s_addc_u32 s55, s29, 0
	s_add_i32 s53, s56, s39
	global_load_lds_dwordx4 v[186:187], off
	v_lshl_add_u64 v[214:215], s[54:55], 0, v[132:133]
	s_mov_b32 m0, s53
	v_lshl_add_u64 v[248:249], s[30:31], 0, v[134:135]
	global_load_lds_dwordx4 v[214:215], off
	v_lshl_add_u64 v[214:215], s[54:55], 0, v[136:137]
	s_add_i32 m0, s53, 0x2000
	s_nop 0
	global_load_lds_dwordx4 v[214:215], off
	v_lshl_add_u64 v[214:215], s[30:31], 0, v[130:131]
	s_mov_b32 m0, s40
	s_nop 0
	global_load_lds_dwordx4 v[214:215], off
	s_mov_b32 m0, s41
	s_nop 0
	global_load_lds_dwordx4 v[248:249], off
	s_waitcnt vmcnt(8)
	s_waitcnt lgkmcnt(0)
	s_barrier
; #define PG8_STAGE(bufoff, gbase, voff) do { _Pragma("unroll") for (int _i = 0; _i < 2; ++_i) \
;         __builtin_amdgcn_global_load_lds((const unsigned*)((const char*)(gbase) + (voff)[_i]), (PG8_LAS unsigned*)(lds + (bufoff) + ldsw + _i * 8192), 16, 0, 0); } while (0)
; #define PG8_LDA(dst, b, h) do { _Pragma("unroll") for (int m = 0; m < 4; ++m) _Pragma("unroll") for (int k = 0; k < 2; ++k) dst[m][k] = *(const PG8_LAS bf16x8*)(lds + PG8_SA(b, h) + aoff + m * 2048 + k * 1024); } while (0)
; #define PG8_LDB(dst, b, h) do { _Pragma("unroll") for (int n = 0; n < 2; ++n) _Pragma("unroll") for (int k = 0; k < 2; ++k) dst[n][k] = *(const PG8_LAS bf16x8*)(lds + PG8_SB(b, h) + boff + n * 2048 + k * 1024); } while (0)
; #define PG8_MMA(ai, bj, At, Bt) do { __builtin_amdgcn_s_setprio(1); _Pragma("unroll") for (int m = 0; m < 4; ++m) _Pragma("unroll") for (int n = 0; n < 2; ++n) _Pragma("unroll") for (int k = 0; k < 2; ++k) \
;         acc[ai][bj][m][n] = __builtin_amdgcn_mfma_f32_16x16x32_bf16(Bt[n][k], At[m][k], acc[ai][bj][m][n], 0, 0, 0); __builtin_amdgcn_s_setprio(0); } while (0)
; #define PG8_WAIT_V(n) asm volatile("s_waitcnt vmcnt(" #n ")" ::: "memory")
; #define PG8_WAIT_L(n) asm volatile("s_waitcnt lgkmcnt(" #n ")" ::: "memory")
; #define PG8_BAR __builtin_amdgcn_s_barrier()
; #define PG8_SCHED __builtin_amdgcn_sched_barrier(0)
; template <class Epi, class Sched, bool ALIGN_EPI = false, bool SP2 = false>
; __device__ __forceinline__ void gemm_phase(PG8_LAS unsigned char* lds, const Gemm g, const Sched& S, const Epi& E) {
;     ...
;             PG8_WAIT_V(8); PG8_WAIT_L(0); PG8_BAR; PG8_MMA(1, 0, At, B0); PG8_MMA(1, 1, At, B1); PG8_BAR; PG8_SCHED;
;             PG8_LDB(B0, 1, 0); PG8_LDB(B1, 1, 1); PG8_SCHED; PG8_LDA(At, 1, 0); PG8_STAGE(PG8_SA(0, 1), a2 + hstepA, voffA);
;             PG8_WAIT_V(8); PG8_WAIT_L(0); PG8_BAR; PG8_MMA(0, 0, At, B0); PG8_MMA(0, 1, At, B1); PG8_BAR; PG8_SCHED;
;             PG8_LDA(At, 1, 1); PG8_STAGE(PG8_SB(1, 0), b3, voffB); PG8_STAGE(PG8_SB(1, 1), b3 + hstepB, voffB); PG8_STAGE(PG8_SA(1, 0), a3, voffA);
	s_setprio 1
	s_waitcnt lgkmcnt(0)
	v_mfma_f32_16x16x32_bf16 v[62:65], v[142:145], v[182:185], v[62:65]
	v_mfma_f32_16x16x32_bf16 v[58:61], v[158:161], v[182:185], v[58:61]
	v_mfma_f32_16x16x32_bf16 v[46:49], v[142:145], v[206:209], v[46:49]
	v_mfma_f32_16x16x32_bf16 v[42:45], v[158:161], v[206:209], v[42:45]
	v_mfma_f32_16x16x32_bf16 v[30:33], v[142:145], v[232:235], v[30:33]
	v_mfma_f32_16x16x32_bf16 v[26:29], v[158:161], v[232:235], v[26:29]
	v_mfma_f32_16x16x32_bf16 v[14:17], v[142:145], v[240:243], v[14:17]
	v_mfma_f32_16x16x32_bf16 v[10:13], v[158:161], v[240:243], v[10:13]
	v_mfma_f32_16x16x32_bf16 v[62:65], v[146:149], v[202:205], v[62:65]
	v_mfma_f32_16x16x32_bf16 v[58:61], v[162:165], v[202:205], v[58:61]
	v_mfma_f32_16x16x32_bf16 v[46:49], v[146:149], v[210:213], v[46:49]
	v_mfma_f32_16x16x32_bf16 v[42:45], v[162:165], v[210:213], v[42:45]
	v_mfma_f32_16x16x32_bf16 v[30:33], v[146:149], v[236:239], v[30:33]
	v_mfma_f32_16x16x32_bf16 v[26:29], v[162:165], v[236:239], v[26:29]
	v_mfma_f32_16x16x32_bf16 v[14:17], v[146:149], v[244:247], v[14:17]
	v_mfma_f32_16x16x32_bf16 v[10:13], v[162:165], v[244:247], v[10:13]
	s_setprio 0
	s_setprio 1
	v_mfma_f32_16x16x32_bf16 v[54:57], v[166:169], v[182:185], v[54:57]
	v_mfma_f32_16x16x32_bf16 v[50:53], v[174:177], v[182:185], v[50:53]
	v_mfma_f32_16x16x32_bf16 v[38:41], v[166:169], v[206:209], v[38:41]
	v_mfma_f32_16x16x32_bf16 v[34:37], v[174:177], v[206:209], v[34:37]
	v_mfma_f32_16x16x32_bf16 v[22:25], v[166:169], v[232:235], v[22:25]
	v_mfma_f32_16x16x32_bf16 v[18:21], v[174:177], v[232:235], v[18:21]
	v_mfma_f32_16x16x32_bf16 v[6:9], v[166:169], v[240:243], v[6:9]
	v_mfma_f32_16x16x32_bf16 v[2:5], v[174:177], v[240:243], v[2:5]
	v_mfma_f32_16x16x32_bf16 v[54:57], v[170:173], v[202:205], v[54:57]
	v_mfma_f32_16x16x32_bf16 v[50:53], v[178:181], v[202:205], v[50:53]
	v_mfma_f32_16x16x32_bf16 v[38:41], v[170:173], v[210:213], v[38:41]
	v_mfma_f32_16x16x32_bf16 v[34:37], v[178:181], v[210:213], v[34:37]
	v_mfma_f32_16x16x32_bf16 v[22:25], v[170:173], v[236:239], v[22:25]
	v_mfma_f32_16x16x32_bf16 v[18:21], v[178:181], v[236:239], v[18:21]
	v_mfma_f32_16x16x32_bf16 v[6:9], v[170:173], v[244:247], v[6:9]
	v_mfma_f32_16x16x32_bf16 v[2:5], v[178:181], v[244:247], v[2:5]
	s_setprio 0
	s_barrier
	s_add_i32 s53, 0, 0x18000
	v_add_u32_e32 v157, s53, v153
	s_add_i32 s54, 0, 0x1c000
	ds_read_b128 v[142:145], v157
	ds_read_b128 v[146:149], v157 offset:1024
	ds_read_b128 v[158:161], v157 offset:2048
	ds_read_b128 v[162:165], v157 offset:3072
	v_add_u32_e32 v157, s54, v153
	ds_read_b128 v[166:169], v157
	ds_read_b128 v[170:173], v157 offset:1024
	ds_read_b128 v[174:177], v157 offset:2048
	ds_read_b128 v[178:181], v157 offset:3072
	s_add_u32 s30, s30, 0x40000
	s_addc_u32 s31, s31, 0
	s_mov_b32 m0, s42
	v_lshl_add_u64 v[250:251], s[30:31], 0, v[130:131]
	ds_read_b128 v[182:185], v156 offset:32768
	ds_read_b128 v[202:205], v156 offset:33792
	ds_read_b128 v[206:209], v156 offset:34816
	ds_read_b128 v[210:213], v156 offset:35840
	ds_read_b128 v[232:235], v156 offset:36864
	ds_read_b128 v[236:239], v156 offset:37888
	ds_read_b128 v[240:243], v156 offset:38912
	ds_read_b128 v[244:247], v156 offset:39936
	global_load_lds_dwordx4 v[250:251], off
	v_lshl_add_u64 v[250:251], s[30:31], 0, v[134:135]
	s_mov_b32 m0, s43
	s_nop 0
	global_load_lds_dwordx4 v[250:251], off
	s_waitcnt vmcnt(8)
	s_waitcnt lgkmcnt(0)
	s_barrier
	s_setprio 1
	s_waitcnt lgkmcnt(0)
	v_mfma_f32_16x16x32_bf16 v[126:129], v[142:145], v[182:185], v[126:129]
	v_mfma_f32_16x16x32_bf16 v[122:125], v[158:161], v[182:185], v[122:125]
	v_mfma_f32_16x16x32_bf16 v[110:113], v[142:145], v[206:209], v[110:113]
	v_mfma_f32_16x16x32_bf16 v[106:109], v[158:161], v[206:209], v[106:109]
	v_mfma_f32_16x16x32_bf16 v[94:97], v[142:145], v[232:235], v[94:97]
	v_mfma_f32_16x16x32_bf16 v[90:93], v[158:161], v[232:235], v[90:93]
	v_mfma_f32_16x16x32_bf16 v[78:81], v[142:145], v[240:243], v[78:81]
	v_mfma_f32_16x16x32_bf16 v[74:77], v[158:161], v[240:243], v[74:77]
	v_mfma_f32_16x16x32_bf16 v[126:129], v[146:149], v[202:205], v[126:129]
	v_mfma_f32_16x16x32_bf16 v[122:125], v[162:165], v[202:205], v[122:125]
	v_mfma_f32_16x16x32_bf16 v[110:113], v[146:149], v[210:213], v[110:113]
	v_mfma_f32_16x16x32_bf16 v[106:109], v[162:165], v[210:213], v[106:109]
	v_mfma_f32_16x16x32_bf16 v[94:97], v[146:149], v[236:239], v[94:97]
	v_mfma_f32_16x16x32_bf16 v[90:93], v[162:165], v[236:239], v[90:93]
	v_mfma_f32_16x16x32_bf16 v[78:81], v[146:149], v[244:247], v[78:81]
	v_mfma_f32_16x16x32_bf16 v[74:77], v[162:165], v[244:247], v[74:77]
	s_setprio 0
	s_setprio 1
	v_mfma_f32_16x16x32_bf16 v[118:121], v[166:169], v[182:185], v[118:121]
	v_mfma_f32_16x16x32_bf16 v[114:117], v[174:177], v[182:185], v[114:117]
	v_mfma_f32_16x16x32_bf16 v[102:105], v[166:169], v[206:209], v[102:105]
	v_mfma_f32_16x16x32_bf16 v[98:101], v[174:177], v[206:209], v[98:101]
	v_mfma_f32_16x16x32_bf16 v[86:89], v[166:169], v[232:235], v[86:89]
	v_mfma_f32_16x16x32_bf16 v[82:85], v[174:177], v[232:235], v[82:85]
	v_mfma_f32_16x16x32_bf16 v[70:73], v[166:169], v[240:243], v[70:73]
	v_mfma_f32_16x16x32_bf16 v[66:69], v[174:177], v[240:243], v[66:69]
	v_mfma_f32_16x16x32_bf16 v[118:121], v[170:173], v[202:205], v[118:121]
	v_mfma_f32_16x16x32_bf16 v[114:117], v[178:181], v[202:205], v[114:117]
	v_mfma_f32_16x16x32_bf16 v[102:105], v[170:173], v[210:213], v[102:105]
	v_mfma_f32_16x16x32_bf16 v[98:101], v[178:181], v[210:213], v[98:101]
	v_mfma_f32_16x16x32_bf16 v[86:89], v[170:173], v[236:239], v[86:89]
	v_mfma_f32_16x16x32_bf16 v[82:85], v[178:181], v[236:239], v[82:85]
	v_mfma_f32_16x16x32_bf16 v[70:73], v[170:173], v[244:247], v[70:73]
	v_mfma_f32_16x16x32_bf16 v[66:69], v[178:181], v[244:247], v[66:69]
	s_setprio 0
	s_barrier
; #define PG8_STAGE(bufoff, gbase, voff) do { _Pragma("unroll") for (int _i = 0; _i < 2; ++_i) \
;         __builtin_amdgcn_global_load_lds((const unsigned*)((const char*)(gbase) + (voff)[_i]), (PG8_LAS unsigned*)(lds + (bufoff) + ldsw + _i * 8192), 16, 0, 0); } while (0)
; #define PG8_LDA(dst, b, h) do { _Pragma("unroll") for (int m = 0; m < 4; ++m) _Pragma("unroll") for (int k = 0; k < 2; ++k) dst[m][k] = *(const PG8_LAS bf16x8*)(lds + PG8_SA(b, h) + aoff + m * 2048 + k * 1024); } while (0)
; #define PG8_MMA(ai, bj, At, Bt) do { __builtin_amdgcn_s_setprio(1); _Pragma("unroll") for (int m = 0; m < 4; ++m) _Pragma("unroll") for (int n = 0; n < 2; ++n) _Pragma("unroll") for (int k = 0; k < 2; ++k) \
;         acc[ai][bj][m][n] = __builtin_amdgcn_mfma_f32_16x16x32_bf16(Bt[n][k], At[m][k], acc[ai][bj][m][n], 0, 0, 0); __builtin_amdgcn_s_setprio(0); } while (0)
; #define PG8_WAIT_V(n) asm volatile("s_waitcnt vmcnt(" #n ")" ::: "memory")
; #define PG8_WAIT_L(n) asm volatile("s_waitcnt lgkmcnt(" #n ")" ::: "memory")
; #define PG8_BAR __builtin_amdgcn_s_barrier()
; #define PG8_SCHED __builtin_amdgcn_sched_barrier(0)
; template <class Epi, class Sched, bool ALIGN_EPI = false, bool SP2 = false>
; __device__ __forceinline__ void gemm_phase(PG8_LAS unsigned char* lds, const Gemm g, const Sched& S, const Epi& E) {
;     ...
;         for (int t = 0; t < nt; t += 2) {
;     ...
;             PG8_LDA(At, 1, 1); PG8_STAGE(PG8_SB(1, 0), b3, voffB); PG8_STAGE(PG8_SB(1, 1), b3 + hstepB, voffB); PG8_STAGE(PG8_SA(1, 0), a3, voffA);
;             PG8_WAIT_V(8); PG8_WAIT_L(0); PG8_BAR; PG8_MMA(1, 0, At, B0); PG8_MMA(1, 1, At, B1); PG8_BAR; PG8_SCHED;
	s_add_i32 s30, s53, s39
	v_lshl_add_u64 v[150:151], v[150:151], 0, s[96:97]
	s_mov_b32 m0, s30
	ds_read_b128 v[182:185], v156 offset:49152
	ds_read_b128 v[202:205], v156 offset:50176
	ds_read_b128 v[206:209], v156 offset:51200
	ds_read_b128 v[210:213], v156 offset:52224
	ds_read_b128 v[232:235], v156 offset:53248
	ds_read_b128 v[236:239], v156 offset:54272
	ds_read_b128 v[240:243], v156 offset:55296
	ds_read_b128 v[244:247], v156 offset:56320
	global_load_lds_dwordx4 v[150:151], off
	s_add_i32 m0, s30, 0x2000
	s_add_u32 s28, s28, 0x40080
	v_lshl_add_u64 v[150:151], v[186:187], 0, s[96:97]
	s_addc_u32 s29, s29, 0
	s_add_i32 s30, s54, s39
	global_load_lds_dwordx4 v[150:151], off
	v_lshl_add_u64 v[150:151], s[28:29], 0, v[132:133]
	s_mov_b32 m0, s30
	s_nop 0
	global_load_lds_dwordx4 v[150:151], off
	v_lshl_add_u64 v[150:151], s[28:29], 0, v[136:137]
	s_add_i32 m0, s30, 0x2000
	s_nop 0
	global_load_lds_dwordx4 v[150:151], off
	v_lshl_add_u64 v[150:151], v[214:215], 0, s[96:97]
	s_mov_b32 m0, s45
	s_nop 0
	global_load_lds_dwordx4 v[150:151], off
	v_lshl_add_u64 v[150:151], v[248:249], 0, s[96:97]
	s_mov_b32 m0, s46
	s_nop 0
	global_load_lds_dwordx4 v[150:151], off
	s_waitcnt vmcnt(8)
	s_waitcnt lgkmcnt(0)
	s_barrier
	s_setprio 1
	s_waitcnt lgkmcnt(0)
	v_mfma_f32_16x16x32_bf16 v[62:65], v[142:145], v[182:185], v[62:65]
	v_mfma_f32_16x16x32_bf16 v[58:61], v[158:161], v[182:185], v[58:61]
	v_mfma_f32_16x16x32_bf16 v[46:49], v[142:145], v[206:209], v[46:49]
	v_mfma_f32_16x16x32_bf16 v[42:45], v[158:161], v[206:209], v[42:45]
	v_mfma_f32_16x16x32_bf16 v[30:33], v[142:145], v[232:235], v[30:33]
	v_mfma_f32_16x16x32_bf16 v[26:29], v[158:161], v[232:235], v[26:29]
	v_mfma_f32_16x16x32_bf16 v[14:17], v[142:145], v[240:243], v[14:17]
	v_mfma_f32_16x16x32_bf16 v[10:13], v[158:161], v[240:243], v[10:13]
	v_mfma_f32_16x16x32_bf16 v[62:65], v[146:149], v[202:205], v[62:65]
	v_mfma_f32_16x16x32_bf16 v[58:61], v[162:165], v[202:205], v[58:61]
	v_mfma_f32_16x16x32_bf16 v[46:49], v[146:149], v[210:213], v[46:49]
	v_mfma_f32_16x16x32_bf16 v[42:45], v[162:165], v[210:213], v[42:45]
	v_mfma_f32_16x16x32_bf16 v[30:33], v[146:149], v[236:239], v[30:33]
	v_mfma_f32_16x16x32_bf16 v[26:29], v[162:165], v[236:239], v[26:29]
	v_mfma_f32_16x16x32_bf16 v[14:17], v[146:149], v[244:247], v[14:17]
	v_mfma_f32_16x16x32_bf16 v[10:13], v[162:165], v[244:247], v[10:13]
	s_setprio 0
	s_setprio 1
	v_mfma_f32_16x16x32_bf16 v[54:57], v[166:169], v[182:185], v[54:57]
	v_mfma_f32_16x16x32_bf16 v[50:53], v[174:177], v[182:185], v[50:53]
	v_mfma_f32_16x16x32_bf16 v[38:41], v[166:169], v[206:209], v[38:41]
	v_mfma_f32_16x16x32_bf16 v[34:37], v[174:177], v[206:209], v[34:37]
	v_mfma_f32_16x16x32_bf16 v[22:25], v[166:169], v[232:235], v[22:25]
	v_mfma_f32_16x16x32_bf16 v[18:21], v[174:177], v[232:235], v[18:21]
	v_mfma_f32_16x16x32_bf16 v[6:9], v[166:169], v[240:243], v[6:9]
	v_mfma_f32_16x16x32_bf16 v[2:5], v[174:177], v[240:243], v[2:5]
	v_mfma_f32_16x16x32_bf16 v[54:57], v[170:173], v[202:205], v[54:57]
	v_mfma_f32_16x16x32_bf16 v[50:53], v[178:181], v[202:205], v[50:53]
	v_mfma_f32_16x16x32_bf16 v[38:41], v[170:173], v[210:213], v[38:41]
	v_mfma_f32_16x16x32_bf16 v[34:37], v[178:181], v[210:213], v[34:37]
	v_mfma_f32_16x16x32_bf16 v[22:25], v[170:173], v[236:239], v[22:25]
	v_mfma_f32_16x16x32_bf16 v[18:21], v[178:181], v[236:239], v[18:21]
	v_mfma_f32_16x16x32_bf16 v[6:9], v[170:173], v[244:247], v[6:9]
	v_mfma_f32_16x16x32_bf16 v[2:5], v[178:181], v[244:247], v[2:5]
	s_setprio 0
	s_add_i32 s52, s52, 2
	s_add_u32 s26, s26, 0x100
	s_addc_u32 s27, s27, 0
	s_add_u32 s50, s50, 0x100
	s_addc_u32 s51, s51, 0
	s_cmp_gt_u32 s52, 13
	s_barrier
	s_cbranch_scc0 .LBB0_254
	s_and_b64 vcc, exec, s[16:17]
	s_cbranch_vccz .LBB0_257
	s_barrier

; #define PG8_STAGE(bufoff, gbase, voff) do { _Pragma("unroll") for (int _i = 0; _i < 2; ++_i) \
;         __builtin_amdgcn_global_load_lds((const unsigned*)((const char*)(gbase) + (voff)[_i]), (PG8_LAS unsigned*)(lds + (bufoff) + ldsw + _i * 8192), 16, 0, 0); } while (0)
; #define PG8_LDA(dst, b, h) do { _Pragma("unroll") for (int m = 0; m < 4; ++m) _Pragma("unroll") for (int k = 0; k < 2; ++k) dst[m][k] = *(const PG8_LAS bf16x8*)(lds + PG8_SA(b, h) + aoff + m * 2048 + k * 1024); } while (0)
; #define PG8_LDB(dst, b, h) do { _Pragma("unroll") for (int n = 0; n < 2; ++n) _Pragma("unroll") for (int k = 0; k < 2; ++k) dst[n][k] = *(const PG8_LAS bf16x8*)(lds + PG8_SB(b, h) + boff + n * 2048 + k * 1024); } while (0)
; #define PG8_MMA(ai, bj, At, Bt) do { __builtin_amdgcn_s_setprio(1); _Pragma("unroll") for (int m = 0; m < 4; ++m) _Pragma("unroll") for (int n = 0; n < 2; ++n) _Pragma("unroll") for (int k = 0; k < 2; ++k) \
;         acc[ai][bj][m][n] = __builtin_amdgcn_mfma_f32_16x16x32_bf16(Bt[n][k], At[m][k], acc[ai][bj][m][n], 0, 0, 0); __builtin_amdgcn_s_setprio(0); } while (0)
; #define PG8_WAIT_V(n) asm volatile("s_waitcnt vmcnt(" #n ")" ::: "memory")
; #define PG8_WAIT_L(n) asm volatile("s_waitcnt lgkmcnt(" #n ")" ::: "memory")
; template <class Epi, class Sched, bool ALIGN_EPI = false, bool SP2 = false>
; __device__ __forceinline__ void gemm_phase(PG8_LAS unsigned char* lds, const Gemm g, const Sched& S, const Epi& E) {
;     ...
;             const bool last = (t == nt - 2);
;             const char* a1 = cA + (size_t)(t + 1) * kstep;
;             const char* a2 = last ? nA : cA + (size_t)(t + 2) * kstep; const char* b2 = last ? nB : cB + (size_t)(t + 2) * kstep;
;             const char* a3 = a2 + kstep; const char* b3 = b2 + kstep;
;             if (last && has_next) S.a_ready(nxt);
;             if constexpr (SP2) {
;             PG8_LDB(B0, 0, 0); PG8_LDB(B1, 0, 1); PG8_SCHED; PG8_LDA(At, 0, 0); PG8_STAGE(PG8_SA(1, 1), a1 + hstepA, voffA);
;             PG8_WAIT_V(8); PG8_WAIT_L(0); PG8_BAR; PG8_MMA(0, 0, At, B0); PG8_MMA(0, 1, At, B1); PG8_BAR; PG8_SCHED;
;             PG8_LDA(At, 0, 1); PG8_STAGE(PG8_SB(0, 0), b2, voffB); PG8_STAGE(PG8_SB(0, 1), b2 + hstepB, voffB); PG8_STAGE(PG8_SA(0, 0), a2, voffA);
;             PG8_WAIT_V(8); PG8_WAIT_L(0); PG8_BAR; PG8_MMA(1, 0, At, B0); PG8_MMA(1, 1, At, B1); PG8_BAR; PG8_SCHED;
.LBB0_530:
	s_add_u32 s12, s1, s8
	s_addc_u32 s13, s28, s9
	s_add_u32 s12, s12, 0xfe00100
	s_addc_u32 s13, s13, 0
	s_add_u32 s34, s29, s8
	s_addc_u32 s35, s30, s9
	s_add_i32 s36, 0, 0x10000
	s_cmpk_eq_i32 s8, 0x700
	s_cselect_b32 s15, s7, s13
	s_cselect_b32 s14, s6, s12
	v_add_u32_e32 v145, s36, v143
	s_cselect_b32 s13, s5, s35
	s_cselect_b32 s12, s4, s34
	s_add_i32 s37, 0, 0x14000
	ds_read_b128 v[146:149], v145
	ds_read_b128 v[150:153], v145 offset:1024
	ds_read_b128 v[154:157], v145 offset:2048
	ds_read_b128 v[158:161], v145 offset:3072
	v_add_u32_e32 v145, s37, v143
	ds_read_b128 v[162:165], v145
	ds_read_b128 v[166:169], v145 offset:1024
	ds_read_b128 v[170:173], v145 offset:2048
	ds_read_b128 v[174:177], v145 offset:3072
	v_lshl_add_u64 v[186:187], v[138:139], 0, s[8:9]
	s_add_i32 m0, s21, 0xc000
	ds_read_b128 v[178:181], v144
	ds_read_b128 v[182:185], v144 offset:1024
	ds_read_b128 v[202:205], v144 offset:2048
	ds_read_b128 v[206:209], v144 offset:3072
	ds_read_b128 v[210:213], v144 offset:4096
	ds_read_b128 v[232:235], v144 offset:5120
	ds_read_b128 v[236:239], v144 offset:6144
	ds_read_b128 v[240:243], v144 offset:7168
	global_load_lds_dwordx4 v[186:187], off
	v_lshl_add_u64 v[186:187], v[140:141], 0, s[8:9]
	s_add_i32 m0, s21, 0xe000
	s_nop 0
	global_load_lds_dwordx4 v[186:187], off
	s_waitcnt vmcnt(8)
	s_waitcnt lgkmcnt(0)
	s_barrier
	s_setprio 1
	s_waitcnt lgkmcnt(0)
	v_mfma_f32_16x16x32_bf16 v[126:129], v[146:149], v[178:181], v[126:129]
	v_mfma_f32_16x16x32_bf16 v[122:125], v[154:157], v[178:181], v[122:125]
	v_mfma_f32_16x16x32_bf16 v[118:121], v[146:149], v[202:205], v[118:121]
	v_mfma_f32_16x16x32_bf16 v[114:117], v[154:157], v[202:205], v[114:117]
	v_mfma_f32_16x16x32_bf16 v[110:113], v[146:149], v[210:213], v[110:113]
	v_mfma_f32_16x16x32_bf16 v[106:109], v[154:157], v[210:213], v[106:109]
	v_mfma_f32_16x16x32_bf16 v[102:105], v[146:149], v[236:239], v[102:105]
	v_mfma_f32_16x16x32_bf16 v[98:101], v[154:157], v[236:239], v[98:101]
	v_mfma_f32_16x16x32_bf16 v[126:129], v[150:153], v[182:185], v[126:129]
	v_mfma_f32_16x16x32_bf16 v[122:125], v[158:161], v[182:185], v[122:125]
	v_mfma_f32_16x16x32_bf16 v[118:121], v[150:153], v[206:209], v[118:121]
	v_mfma_f32_16x16x32_bf16 v[114:117], v[158:161], v[206:209], v[114:117]
	v_mfma_f32_16x16x32_bf16 v[110:113], v[150:153], v[232:235], v[110:113]
	v_mfma_f32_16x16x32_bf16 v[106:109], v[158:161], v[232:235], v[106:109]
	v_mfma_f32_16x16x32_bf16 v[102:105], v[150:153], v[240:243], v[102:105]
	v_mfma_f32_16x16x32_bf16 v[98:101], v[158:161], v[240:243], v[98:101]
	s_setprio 0
	s_setprio 1
	v_mfma_f32_16x16x32_bf16 v[94:97], v[162:165], v[178:181], v[94:97]
	v_mfma_f32_16x16x32_bf16 v[86:89], v[170:173], v[178:181], v[86:89]
	v_mfma_f32_16x16x32_bf16 v[78:81], v[162:165], v[202:205], v[78:81]
	v_mfma_f32_16x16x32_bf16 v[74:77], v[170:173], v[202:205], v[74:77]
	v_mfma_f32_16x16x32_bf16 v[70:73], v[162:165], v[210:213], v[70:73]
	v_mfma_f32_16x16x32_bf16 v[62:65], v[170:173], v[210:213], v[62:65]
	v_mfma_f32_16x16x32_bf16 v[54:57], v[162:165], v[236:239], v[54:57]
	v_mfma_f32_16x16x32_bf16 v[50:53], v[170:173], v[236:239], v[50:53]
	v_mfma_f32_16x16x32_bf16 v[94:97], v[166:169], v[182:185], v[94:97]
	v_mfma_f32_16x16x32_bf16 v[86:89], v[174:177], v[182:185], v[86:89]
	v_mfma_f32_16x16x32_bf16 v[78:81], v[166:169], v[206:209], v[78:81]
	v_mfma_f32_16x16x32_bf16 v[74:77], v[174:177], v[206:209], v[74:77]
	v_mfma_f32_16x16x32_bf16 v[70:73], v[166:169], v[232:235], v[70:73]
	v_mfma_f32_16x16x32_bf16 v[62:65], v[174:177], v[232:235], v[62:65]
	v_mfma_f32_16x16x32_bf16 v[54:57], v[166:169], v[240:243], v[54:57]
	v_mfma_f32_16x16x32_bf16 v[50:53], v[174:177], v[240:243], v[50:53]
	s_setprio 0
	s_barrier
	s_add_i32 s34, s36, s20
	v_lshl_add_u64 v[186:187], s[12:13], 0, v[134:135]
	s_mov_b32 m0, s34
	ds_read_b128 v[178:181], v144 offset:16384
	ds_read_b128 v[182:185], v144 offset:17408
	ds_read_b128 v[202:205], v144 offset:18432
	ds_read_b128 v[206:209], v144 offset:19456
	ds_read_b128 v[210:213], v144 offset:20480
	ds_read_b128 v[232:235], v144 offset:21504
	ds_read_b128 v[236:239], v144 offset:22528
	ds_read_b128 v[240:243], v144 offset:23552
	global_load_lds_dwordx4 v[186:187], off
	s_add_i32 m0, s34, 0x2000
	s_add_u32 s34, s12, 0x80000
	v_lshl_add_u64 v[214:215], s[12:13], 0, v[130:131]
	s_addc_u32 s35, s13, 0
	s_add_i32 s36, s37, s20
	global_load_lds_dwordx4 v[214:215], off
	v_lshl_add_u64 v[244:245], s[34:35], 0, v[134:135]
	s_mov_b32 m0, s36
	v_lshl_add_u64 v[246:247], s[14:15], 0, v[132:133]
	global_load_lds_dwordx4 v[244:245], off
	v_lshl_add_u64 v[244:245], s[34:35], 0, v[130:131]
	s_add_i32 m0, s36, 0x2000
	s_nop 0
	global_load_lds_dwordx4 v[244:245], off
	v_lshl_add_u64 v[244:245], s[14:15], 0, v[136:137]
	s_mov_b32 m0, s21
	s_nop 0
	global_load_lds_dwordx4 v[244:245], off
	s_mov_b32 m0, s22
	s_nop 0
	global_load_lds_dwordx4 v[246:247], off
	s_waitcnt vmcnt(8)
	s_waitcnt lgkmcnt(0)
	s_barrier
; #define PG8_STAGE(bufoff, gbase, voff) do { _Pragma("unroll") for (int _i = 0; _i < 2; ++_i) \
;         __builtin_amdgcn_global_load_lds((const unsigned*)((const char*)(gbase) + (voff)[_i]), (PG8_LAS unsigned*)(lds + (bufoff) + ldsw + _i * 8192), 16, 0, 0); } while (0)
; #define PG8_LDA(dst, b, h) do { _Pragma("unroll") for (int m = 0; m < 4; ++m) _Pragma("unroll") for (int k = 0; k < 2; ++k) dst[m][k] = *(const PG8_LAS bf16x8*)(lds + PG8_SA(b, h) + aoff + m * 2048 + k * 1024); } while (0)
; #define PG8_LDB(dst, b, h) do { _Pragma("unroll") for (int n = 0; n < 2; ++n) _Pragma("unroll") for (int k = 0; k < 2; ++k) dst[n][k] = *(const PG8_LAS bf16x8*)(lds + PG8_SB(b, h) + boff + n * 2048 + k * 1024); } while (0)
; #define PG8_MMA(ai, bj, At, Bt) do { __builtin_amdgcn_s_setprio(1); _Pragma("unroll") for (int m = 0; m < 4; ++m) _Pragma("unroll") for (int n = 0; n < 2; ++n) _Pragma("unroll") for (int k = 0; k < 2; ++k) \
;         acc[ai][bj][m][n] = __builtin_amdgcn_mfma_f32_16x16x32_bf16(Bt[n][k], At[m][k], acc[ai][bj][m][n], 0, 0, 0); __builtin_amdgcn_s_setprio(0); } while (0)
; #define PG8_WAIT_V(n) asm volatile("s_waitcnt vmcnt(" #n ")" ::: "memory")
; #define PG8_WAIT_L(n) asm volatile("s_waitcnt lgkmcnt(" #n ")" ::: "memory")
; #define PG8_BAR __builtin_amdgcn_s_barrier()
; #define PG8_SCHED __builtin_amdgcn_sched_barrier(0)
; template <class Epi, class Sched, bool ALIGN_EPI = false, bool SP2 = false>
; __device__ __forceinline__ void gemm_phase(PG8_LAS unsigned char* lds, const Gemm g, const Sched& S, const Epi& E) {
;     ...
;             PG8_WAIT_V(8); PG8_WAIT_L(0); PG8_BAR; PG8_MMA(1, 0, At, B0); PG8_MMA(1, 1, At, B1); PG8_BAR; PG8_SCHED;
;             PG8_LDB(B0, 1, 0); PG8_LDB(B1, 1, 1); PG8_SCHED; PG8_LDA(At, 1, 0); PG8_STAGE(PG8_SA(0, 1), a2 + hstepA, voffA);
;             PG8_WAIT_V(8); PG8_WAIT_L(0); PG8_BAR; PG8_MMA(0, 0, At, B0); PG8_MMA(0, 1, At, B1); PG8_BAR; PG8_SCHED;
;             PG8_LDA(At, 1, 1); PG8_STAGE(PG8_SB(1, 0), b3, voffB); PG8_STAGE(PG8_SB(1, 1), b3 + hstepB, voffB); PG8_STAGE(PG8_SA(1, 0), a3, voffA);
	s_setprio 1
	s_waitcnt lgkmcnt(0)
	v_mfma_f32_16x16x32_bf16 v[90:93], v[146:149], v[178:181], v[90:93]
	v_mfma_f32_16x16x32_bf16 v[82:85], v[154:157], v[178:181], v[82:85]
	v_mfma_f32_16x16x32_bf16 v[66:69], v[146:149], v[202:205], v[66:69]
	v_mfma_f32_16x16x32_bf16 v[58:61], v[154:157], v[202:205], v[58:61]
	v_mfma_f32_16x16x32_bf16 v[46:49], v[146:149], v[210:213], v[46:49]
	v_mfma_f32_16x16x32_bf16 v[42:45], v[154:157], v[210:213], v[42:45]
	v_mfma_f32_16x16x32_bf16 v[38:41], v[146:149], v[236:239], v[38:41]
	v_mfma_f32_16x16x32_bf16 v[34:37], v[154:157], v[236:239], v[34:37]
	v_mfma_f32_16x16x32_bf16 v[90:93], v[150:153], v[182:185], v[90:93]
	v_mfma_f32_16x16x32_bf16 v[82:85], v[158:161], v[182:185], v[82:85]
	v_mfma_f32_16x16x32_bf16 v[66:69], v[150:153], v[206:209], v[66:69]
	v_mfma_f32_16x16x32_bf16 v[58:61], v[158:161], v[206:209], v[58:61]
	v_mfma_f32_16x16x32_bf16 v[46:49], v[150:153], v[232:235], v[46:49]
	v_mfma_f32_16x16x32_bf16 v[42:45], v[158:161], v[232:235], v[42:45]
	v_mfma_f32_16x16x32_bf16 v[38:41], v[150:153], v[240:243], v[38:41]
	v_mfma_f32_16x16x32_bf16 v[34:37], v[158:161], v[240:243], v[34:37]
	s_setprio 0
	s_setprio 1
	v_mfma_f32_16x16x32_bf16 v[30:33], v[162:165], v[178:181], v[30:33]
	v_mfma_f32_16x16x32_bf16 v[26:29], v[170:173], v[178:181], v[26:29]
	v_mfma_f32_16x16x32_bf16 v[22:25], v[162:165], v[202:205], v[22:25]
	v_mfma_f32_16x16x32_bf16 v[18:21], v[170:173], v[202:205], v[18:21]
	v_mfma_f32_16x16x32_bf16 v[14:17], v[162:165], v[210:213], v[14:17]
	v_mfma_f32_16x16x32_bf16 v[10:13], v[170:173], v[210:213], v[10:13]
	v_mfma_f32_16x16x32_bf16 v[6:9], v[162:165], v[236:239], v[6:9]
	v_mfma_f32_16x16x32_bf16 v[2:5], v[170:173], v[236:239], v[2:5]
	v_mfma_f32_16x16x32_bf16 v[30:33], v[166:169], v[182:185], v[30:33]
	v_mfma_f32_16x16x32_bf16 v[26:29], v[174:177], v[182:185], v[26:29]
	v_mfma_f32_16x16x32_bf16 v[22:25], v[166:169], v[206:209], v[22:25]
	v_mfma_f32_16x16x32_bf16 v[18:21], v[174:177], v[206:209], v[18:21]
	v_mfma_f32_16x16x32_bf16 v[14:17], v[166:169], v[232:235], v[14:17]
	v_mfma_f32_16x16x32_bf16 v[10:13], v[174:177], v[232:235], v[10:13]
	v_mfma_f32_16x16x32_bf16 v[6:9], v[166:169], v[240:243], v[6:9]
	v_mfma_f32_16x16x32_bf16 v[2:5], v[174:177], v[240:243], v[2:5]
	s_setprio 0
	s_barrier
	s_add_i32 s34, 0, 0x18000
	v_add_u32_e32 v145, s34, v143
	s_add_i32 s35, 0, 0x1c000
	ds_read_b128 v[146:149], v145
	ds_read_b128 v[150:153], v145 offset:1024
	ds_read_b128 v[154:157], v145 offset:2048
	ds_read_b128 v[158:161], v145 offset:3072
	v_add_u32_e32 v145, s35, v143
	ds_read_b128 v[162:165], v145
	ds_read_b128 v[166:169], v145 offset:1024
	ds_read_b128 v[170:173], v145 offset:2048
	ds_read_b128 v[174:177], v145 offset:3072
	s_add_u32 s14, s14, 0x40000
	s_addc_u32 s15, s15, 0
	s_mov_b32 m0, s23
	v_lshl_add_u64 v[248:249], s[14:15], 0, v[136:137]
	ds_read_b128 v[178:181], v144 offset:32768
	ds_read_b128 v[182:185], v144 offset:33792
	ds_read_b128 v[202:205], v144 offset:34816
	ds_read_b128 v[206:209], v144 offset:35840
	ds_read_b128 v[210:213], v144 offset:36864
	ds_read_b128 v[232:235], v144 offset:37888
	ds_read_b128 v[236:239], v144 offset:38912
	ds_read_b128 v[240:243], v144 offset:39936
	global_load_lds_dwordx4 v[248:249], off
	v_lshl_add_u64 v[248:249], s[14:15], 0, v[132:133]
	s_mov_b32 m0, s24
	s_nop 0
	global_load_lds_dwordx4 v[248:249], off
	s_waitcnt vmcnt(8)
	s_waitcnt lgkmcnt(0)
	s_barrier
	s_setprio 1
	s_waitcnt lgkmcnt(0)
	v_mfma_f32_16x16x32_bf16 v[126:129], v[146:149], v[178:181], v[126:129]
	v_mfma_f32_16x16x32_bf16 v[122:125], v[154:157], v[178:181], v[122:125]
	v_mfma_f32_16x16x32_bf16 v[118:121], v[146:149], v[202:205], v[118:121]
	v_mfma_f32_16x16x32_bf16 v[114:117], v[154:157], v[202:205], v[114:117]
	v_mfma_f32_16x16x32_bf16 v[110:113], v[146:149], v[210:213], v[110:113]
	v_mfma_f32_16x16x32_bf16 v[106:109], v[154:157], v[210:213], v[106:109]
	v_mfma_f32_16x16x32_bf16 v[102:105], v[146:149], v[236:239], v[102:105]
	v_mfma_f32_16x16x32_bf16 v[98:101], v[154:157], v[236:239], v[98:101]
	v_mfma_f32_16x16x32_bf16 v[126:129], v[150:153], v[182:185], v[126:129]
	v_mfma_f32_16x16x32_bf16 v[122:125], v[158:161], v[182:185], v[122:125]
	v_mfma_f32_16x16x32_bf16 v[118:121], v[150:153], v[206:209], v[118:121]
	v_mfma_f32_16x16x32_bf16 v[114:117], v[158:161], v[206:209], v[114:117]
	v_mfma_f32_16x16x32_bf16 v[110:113], v[150:153], v[232:235], v[110:113]
	v_mfma_f32_16x16x32_bf16 v[106:109], v[158:161], v[232:235], v[106:109]
	v_mfma_f32_16x16x32_bf16 v[102:105], v[150:153], v[240:243], v[102:105]
	v_mfma_f32_16x16x32_bf16 v[98:101], v[158:161], v[240:243], v[98:101]
	s_setprio 0
	s_setprio 1
	v_mfma_f32_16x16x32_bf16 v[94:97], v[162:165], v[178:181], v[94:97]
	v_mfma_f32_16x16x32_bf16 v[86:89], v[170:173], v[178:181], v[86:89]
	v_mfma_f32_16x16x32_bf16 v[78:81], v[162:165], v[202:205], v[78:81]
	v_mfma_f32_16x16x32_bf16 v[74:77], v[170:173], v[202:205], v[74:77]
	v_mfma_f32_16x16x32_bf16 v[70:73], v[162:165], v[210:213], v[70:73]
	v_mfma_f32_16x16x32_bf16 v[62:65], v[170:173], v[210:213], v[62:65]
	v_mfma_f32_16x16x32_bf16 v[54:57], v[162:165], v[236:239], v[54:57]
	v_mfma_f32_16x16x32_bf16 v[50:53], v[170:173], v[236:239], v[50:53]
	v_mfma_f32_16x16x32_bf16 v[94:97], v[166:169], v[182:185], v[94:97]
	v_mfma_f32_16x16x32_bf16 v[86:89], v[174:177], v[182:185], v[86:89]
	v_mfma_f32_16x16x32_bf16 v[78:81], v[166:169], v[206:209], v[78:81]
	v_mfma_f32_16x16x32_bf16 v[74:77], v[174:177], v[206:209], v[74:77]
	v_mfma_f32_16x16x32_bf16 v[70:73], v[166:169], v[232:235], v[70:73]
	v_mfma_f32_16x16x32_bf16 v[62:65], v[174:177], v[232:235], v[62:65]
	v_mfma_f32_16x16x32_bf16 v[54:57], v[166:169], v[240:243], v[54:57]
	v_mfma_f32_16x16x32_bf16 v[50:53], v[174:177], v[240:243], v[50:53]
	s_setprio 0
	s_barrier
; #define PG8_STAGE(bufoff, gbase, voff) do { _Pragma("unroll") for (int _i = 0; _i < 2; ++_i) \
;         __builtin_amdgcn_global_load_lds((const unsigned*)((const char*)(gbase) + (voff)[_i]), (PG8_LAS unsigned*)(lds + (bufoff) + ldsw + _i * 8192), 16, 0, 0); } while (0)
; #define PG8_LDA(dst, b, h) do { _Pragma("unroll") for (int m = 0; m < 4; ++m) _Pragma("unroll") for (int k = 0; k < 2; ++k) dst[m][k] = *(const PG8_LAS bf16x8*)(lds + PG8_SA(b, h) + aoff + m * 2048 + k * 1024); } while (0)
; #define PG8_MMA(ai, bj, At, Bt) do { __builtin_amdgcn_s_setprio(1); _Pragma("unroll") for (int m = 0; m < 4; ++m) _Pragma("unroll") for (int n = 0; n < 2; ++n) _Pragma("unroll") for (int k = 0; k < 2; ++k) \
;         acc[ai][bj][m][n] = __builtin_amdgcn_mfma_f32_16x16x32_bf16(Bt[n][k], At[m][k], acc[ai][bj][m][n], 0, 0, 0); __builtin_amdgcn_s_setprio(0); } while (0)
; #define PG8_WAIT_V(n) asm volatile("s_waitcnt vmcnt(" #n ")" ::: "memory")
; #define PG8_WAIT_L(n) asm volatile("s_waitcnt lgkmcnt(" #n ")" ::: "memory")
; #define PG8_BAR __builtin_amdgcn_s_barrier()
; #define PG8_SCHED __builtin_amdgcn_sched_barrier(0)
; template <class Epi, class Sched, bool ALIGN_EPI = false, bool SP2 = false>
; __device__ __forceinline__ void gemm_phase(PG8_LAS unsigned char* lds, const Gemm g, const Sched& S, const Epi& E) {
;     ...
;         for (int t = 0; t < nt; t += 2) {
;     ...
;             PG8_LDA(At, 1, 1); PG8_STAGE(PG8_SB(1, 0), b3, voffB); PG8_STAGE(PG8_SB(1, 1), b3 + hstepB, voffB); PG8_STAGE(PG8_SA(1, 0), a3, voffA);
;             PG8_WAIT_V(8); PG8_WAIT_L(0); PG8_BAR; PG8_MMA(1, 0, At, B0); PG8_MMA(1, 1, At, B1); PG8_BAR; PG8_SCHED;
	s_add_i32 s14, s34, s20
	v_lshl_add_u64 v[186:187], v[186:187], 0, s[96:97]
	s_mov_b32 m0, s14
	ds_read_b128 v[178:181], v144 offset:49152
	ds_read_b128 v[182:185], v144 offset:50176
	ds_read_b128 v[202:205], v144 offset:51200
	ds_read_b128 v[206:209], v144 offset:52224
	ds_read_b128 v[210:213], v144 offset:53248
	ds_read_b128 v[232:235], v144 offset:54272
	ds_read_b128 v[236:239], v144 offset:55296
	ds_read_b128 v[240:243], v144 offset:56320
	global_load_lds_dwordx4 v[186:187], off
	s_add_i32 m0, s14, 0x2000
	s_add_u32 s12, s12, 0x80080
	v_lshl_add_u64 v[186:187], v[214:215], 0, s[96:97]
	s_addc_u32 s13, s13, 0
	s_add_i32 s14, s35, s20
	global_load_lds_dwordx4 v[186:187], off
	v_lshl_add_u64 v[186:187], s[12:13], 0, v[134:135]
	s_mov_b32 m0, s14
	s_nop 0
	global_load_lds_dwordx4 v[186:187], off
	v_lshl_add_u64 v[186:187], s[12:13], 0, v[130:131]
	s_add_i32 m0, s14, 0x2000
	s_nop 0
	global_load_lds_dwordx4 v[186:187], off
	v_lshl_add_u64 v[186:187], v[244:245], 0, s[96:97]
	s_mov_b32 m0, s26
	s_nop 0
	global_load_lds_dwordx4 v[186:187], off
	v_lshl_add_u64 v[186:187], v[246:247], 0, s[96:97]
	s_mov_b32 m0, s27
	s_nop 0
	global_load_lds_dwordx4 v[186:187], off
	s_waitcnt vmcnt(8)
	s_waitcnt lgkmcnt(0)
	s_barrier
	s_setprio 1
	s_waitcnt lgkmcnt(0)
	v_mfma_f32_16x16x32_bf16 v[90:93], v[146:149], v[178:181], v[90:93]
	v_mfma_f32_16x16x32_bf16 v[82:85], v[154:157], v[178:181], v[82:85]
	v_mfma_f32_16x16x32_bf16 v[66:69], v[146:149], v[202:205], v[66:69]
	v_mfma_f32_16x16x32_bf16 v[58:61], v[154:157], v[202:205], v[58:61]
	v_mfma_f32_16x16x32_bf16 v[46:49], v[146:149], v[210:213], v[46:49]
	v_mfma_f32_16x16x32_bf16 v[42:45], v[154:157], v[210:213], v[42:45]
	v_mfma_f32_16x16x32_bf16 v[38:41], v[146:149], v[236:239], v[38:41]
	v_mfma_f32_16x16x32_bf16 v[34:37], v[154:157], v[236:239], v[34:37]
	v_mfma_f32_16x16x32_bf16 v[90:93], v[150:153], v[182:185], v[90:93]
	v_mfma_f32_16x16x32_bf16 v[82:85], v[158:161], v[182:185], v[82:85]
	v_mfma_f32_16x16x32_bf16 v[66:69], v[150:153], v[206:209], v[66:69]
	v_mfma_f32_16x16x32_bf16 v[58:61], v[158:161], v[206:209], v[58:61]
	v_mfma_f32_16x16x32_bf16 v[46:49], v[150:153], v[232:235], v[46:49]
	v_mfma_f32_16x16x32_bf16 v[42:45], v[158:161], v[232:235], v[42:45]
	v_mfma_f32_16x16x32_bf16 v[38:41], v[150:153], v[240:243], v[38:41]
	v_mfma_f32_16x16x32_bf16 v[34:37], v[158:161], v[240:243], v[34:37]
	s_setprio 0
	s_setprio 1
	v_mfma_f32_16x16x32_bf16 v[30:33], v[162:165], v[178:181], v[30:33]
	v_mfma_f32_16x16x32_bf16 v[26:29], v[170:173], v[178:181], v[26:29]
	v_mfma_f32_16x16x32_bf16 v[22:25], v[162:165], v[202:205], v[22:25]
	v_mfma_f32_16x16x32_bf16 v[18:21], v[170:173], v[202:205], v[18:21]
	v_mfma_f32_16x16x32_bf16 v[14:17], v[162:165], v[210:213], v[14:17]
	v_mfma_f32_16x16x32_bf16 v[10:13], v[170:173], v[210:213], v[10:13]
	v_mfma_f32_16x16x32_bf16 v[6:9], v[162:165], v[236:239], v[6:9]
	v_mfma_f32_16x16x32_bf16 v[2:5], v[170:173], v[236:239], v[2:5]
	v_mfma_f32_16x16x32_bf16 v[30:33], v[166:169], v[182:185], v[30:33]
	v_mfma_f32_16x16x32_bf16 v[26:29], v[174:177], v[182:185], v[26:29]
	v_mfma_f32_16x16x32_bf16 v[22:25], v[166:169], v[206:209], v[22:25]
	v_mfma_f32_16x16x32_bf16 v[18:21], v[174:177], v[206:209], v[18:21]
	v_mfma_f32_16x16x32_bf16 v[14:17], v[166:169], v[232:235], v[14:17]
	v_mfma_f32_16x16x32_bf16 v[10:13], v[174:177], v[232:235], v[10:13]
	v_mfma_f32_16x16x32_bf16 v[6:9], v[166:169], v[240:243], v[6:9]
	v_mfma_f32_16x16x32_bf16 v[2:5], v[174:177], v[240:243], v[2:5]
	s_setprio 0
	s_add_i32 s31, s31, 2
	s_add_u32 s8, s8, 0x100
	s_addc_u32 s9, s9, 0
	s_cmp_gt_u32 s31, 13
	s_barrier
	s_cbranch_scc0 .LBB0_530
	s_cmpk_lt_u32 s19, 0x100
	s_cbranch_scc0 .LBB0_533
	s_barrier

; DI float fast_exp2(float x) { return __builtin_amdgcn_exp2f(x); }
; #define MFMA32(a, b, c) __builtin_amdgcn_mfma_f32_32x32x16_bf16((a), (b), (c), 0, 0, 0)
; DI int crow(int r, int hi) { return (r & 3) + 8 * (r >> 2) + 4 * hi; }
; DI float xhalf_max(float v) { const auto rr = __builtin_amdgcn_permlane32_swap(__float_as_uint(v), __float_as_uint(v), false, false); return fmaxf(__uint_as_float(rr[0]), __uint_as_float(rr[1])); }
; DI int ccol(int r) { return (r & 3) + 8 * (r >> 2); }
; DI void frag_scores(f32x16& x0, const KFrag& K0, const bf16x8 (&qf)[4], float sk, float aref, int p0, bool needmask, int lo, int hip, int hi) {
;     const float B = fmaf(sk, (float)(p0 + 4 * hi), -aref);
; #pragma unroll
;     for (int r = 0; r < 16; ++r) x0[r] = fmaf(sk, (float)ccol(r), B);
; #pragma unroll
;     for (int d0 = 0; d0 < 4; ++d0) x0 = MFMA32(K0.k[d0], qf[d0], x0);
;     if (needmask) {
; #pragma unroll
;         for (int r = 0; r < 16; ++r) { const int pos = p0 + crow(r, hi); if (pos < lo || pos > hip) x0[r] = -1e30f; }
;     }
; }
; DI void soft_update1(Soft& f, f32x16& x0) {
;     float mx = x0[0];
; #pragma unroll
;     for (int r = 1; r < 16; ++r) mx = fmaxf(mx, x0[r]);
;     mx = xhalf_max(mx);
;     const bool valid = mx > -1e20f;
;     const bool need = valid && (mx > 8.f || !f.seen);
;     if (__builtin_amdgcn_ballot_w64(need)) {
;         const float delta = need ? fmaxf(mx, -60.f) : 0.f; const float sc = fast_exp2(-delta);
;         f.mref += delta; f.l *= sc;
; #pragma unroll
;         for (int r = 0; r < 16; ++r) { f.o0[r] *= sc; f.o1[r] *= sc; x0[r] -= delta; }
;     }
.LBB0_1071:
	s_waitcnt vmcnt(25)
	v_add_u32_e32 v66, 0xffffff80, v181
	v_cvt_f32_u32_e32 v35, v66
	v_add_f32_e32 v34, v182, v183
	v_cmp_lt_i32_e32 vcc, v66, v175
	v_cmp_gt_i32_e64 s[40:41], v66, v180
	v_fma_f32 v48, v168, v35, -v34
	v_fma_f32 v34, 0, v168, v48
	v_add_f32_e32 v35, v168, v48
	v_pk_fma_f32 v[36:37], v[168:169], s[82:83], v[48:49] op_sel_hi:[1,1,0]
	v_pk_fma_f32 v[38:39], v[168:169], s[84:85], v[48:49] op_sel_hi:[1,1,0]
	v_pk_fma_f32 v[40:41], v[168:169], s[86:87], v[48:49] op_sel_hi:[1,1,0]
	v_pk_fma_f32 v[42:43], v[168:169], s[80:81], v[48:49] op_sel_hi:[1,1,0]
	v_pk_fma_f32 v[44:45], v[168:169], s[88:89], v[48:49] op_sel_hi:[1,1,0]
	v_pk_fma_f32 v[46:47], v[168:169], s[90:91], v[48:49] op_sel_hi:[1,1,0]
	v_pk_fma_f32 v[48:49], v[168:169], s[92:93], v[48:49] op_sel_hi:[1,1,0]
	s_or_b64 vcc, vcc, s[40:41]
	v_cmp_ge_i32_e64 s[40:41], v66, v180
	s_waitcnt vmcnt(11)
	v_mfma_f32_32x32x16_bf16 v[34:49], v[146:149], v[50:53], v[34:49]
	v_add_u32_e32 v50, 0xffffff81, v181
	s_mov_b64 s[4:5], 0
	s_waitcnt vmcnt(10)
	v_mfma_f32_32x32x16_bf16 v[34:49], v[150:153], v[54:57], v[34:49]
	s_waitcnt vmcnt(9)
	v_mfma_f32_32x32x16_bf16 v[34:49], v[154:157], v[58:61], v[34:49]
	s_waitcnt vmcnt(8)
	v_mfma_f32_32x32x16_bf16 v[34:49], v[158:161], v[62:65], v[34:49]
	s_nop 11
	v_cndmask_b32_e32 v34, v34, v222, vcc
	v_cmp_lt_i32_e32 vcc, v50, v175
	s_or_b64 vcc, s[40:41], vcc
	v_add_u32_e32 v50, 0xffffff82, v181
	v_cndmask_b32_e32 v35, v35, v222, vcc
	v_cmp_lt_i32_e32 vcc, v50, v175
	v_cmp_gt_i32_e64 s[40:41], v50, v180
	s_or_b64 vcc, vcc, s[40:41]
	v_add_u32_e32 v50, 0xffffff83, v181
	v_cndmask_b32_e32 v36, v36, v222, vcc
	v_cmp_lt_i32_e32 vcc, v50, v175
	v_cmp_gt_i32_e64 s[40:41], v50, v180
	s_or_b64 vcc, vcc, s[40:41]
	v_add_u32_e32 v50, 0xffffff88, v181
	v_cndmask_b32_e32 v37, v37, v222, vcc
	v_cmp_lt_i32_e32 vcc, v50, v175
	v_cmp_gt_i32_e64 s[40:41], v50, v180
	s_or_b64 vcc, vcc, s[40:41]
	v_cndmask_b32_e32 v50, v38, v222, vcc
	v_add_u32_e32 v38, 0xffffff89, v181
	v_cmp_lt_i32_e32 vcc, v38, v175
	v_cmp_gt_i32_e64 s[40:41], v38, v180
	s_or_b64 vcc, vcc, s[40:41]
	v_add_u32_e32 v38, 0xffffff8a, v181
	v_cndmask_b32_e32 v51, v39, v222, vcc
	v_cmp_lt_i32_e32 vcc, v38, v175
	v_cmp_gt_i32_e64 s[40:41], v38, v180
	s_or_b64 vcc, vcc, s[40:41]
	v_add_u32_e32 v38, 0xffffff8b, v181
	v_cndmask_b32_e32 v52, v40, v222, vcc
	v_cmp_lt_i32_e32 vcc, v38, v175
	v_cmp_gt_i32_e64 s[40:41], v38, v180
	s_or_b64 vcc, vcc, s[40:41]
	v_add_u32_e32 v38, 0xffffff90, v181
	v_cndmask_b32_e32 v53, v41, v222, vcc
	v_cmp_lt_i32_e32 vcc, v38, v175
	v_cmp_gt_i32_e64 s[40:41], v38, v180
	s_or_b64 vcc, vcc, s[40:41]
	v_add_u32_e32 v38, 0xffffff91, v181
	v_cndmask_b32_e32 v54, v42, v222, vcc
	v_cmp_lt_i32_e32 vcc, v38, v175
	v_cmp_gt_i32_e64 s[40:41], v38, v180
	s_or_b64 vcc, vcc, s[40:41]
	v_add_u32_e32 v38, 0xffffff92, v181
	v_cndmask_b32_e32 v55, v43, v222, vcc
	v_cmp_lt_i32_e32 vcc, v38, v175
	v_cmp_gt_i32_e64 s[40:41], v38, v180
	s_or_b64 vcc, vcc, s[40:41]
	v_add_u32_e32 v39, 0xffffff93, v181
	v_cndmask_b32_e32 v38, v44, v222, vcc
	v_cmp_lt_i32_e32 vcc, v39, v175
	v_cmp_gt_i32_e64 s[40:41], v39, v180
	s_or_b64 vcc, vcc, s[40:41]
	v_add_u32_e32 v40, 0xffffff98, v181
	v_cndmask_b32_e32 v39, v45, v222, vcc
	v_cmp_lt_i32_e32 vcc, v40, v175
	v_cmp_gt_i32_e64 s[40:41], v40, v180
	s_or_b64 vcc, vcc, s[40:41]
	v_add_u32_e32 v41, 0xffffff99, v181
	v_max_f32_e32 v44, v35, v35
	v_max_f32_e32 v45, v34, v34
	v_cndmask_b32_e32 v40, v46, v222, vcc
	v_cmp_lt_i32_e32 vcc, v41, v175
	v_cmp_gt_i32_e64 s[40:41], v41, v180
	v_max_f32_e32 v44, v45, v44
	s_or_b64 vcc, vcc, s[40:41]
	v_add_u32_e32 v42, 0xffffff9a, v181
	v_max3_f32 v44, v44, v36, v37
	v_cndmask_b32_e32 v41, v47, v222, vcc
	v_cmp_lt_i32_e32 vcc, v42, v175
	v_cmp_gt_i32_e64 s[40:41], v42, v180
	v_max3_f32 v44, v44, v50, v51
	s_or_b64 vcc, vcc, s[40:41]
	v_add_u32_e32 v43, 0xffffff9b, v181
	v_max3_f32 v44, v44, v52, v53
	v_cndmask_b32_e32 v42, v48, v222, vcc
	v_cmp_lt_i32_e32 vcc, v43, v175
	v_cmp_gt_i32_e64 s[40:41], v43, v180
	v_max3_f32 v44, v44, v54, v55
	s_or_b64 vcc, vcc, s[40:41]
	v_max3_f32 v44, v44, v38, v39
	v_cndmask_b32_e32 v43, v49, v222, vcc
	v_max3_f32 v44, v44, v40, v41
	v_max3_f32 v44, v44, v42, v43
	v_mov_b32_e32 v45, v44
	s_nop 1
	v_permlane32_swap_b32_e32 v44, v45
	v_max_f32_e32 v45, v45, v45
	v_max_f32_e32 v44, v44, v44
	v_max_f32_e32 v44, v44, v45
	v_cmp_lt_f32_e64 s[40:41], s70, v44
	v_cmp_lt_f32_e64 s[4:5], s84, v44
	s_orn2_b64 s[4:5], s[4:5], s[38:39]
	s_and_b64 s[4:5], s[4:5], s[40:41]
	s_cbranch_scc0 .LBB0_1077
	v_max_f32_e32 v44, v44, v44
	v_max_f32_e32 v44, 0xc2700000, v44
	v_cndmask_b32_e64 v44, 0, v44, s[4:5]
	v_exp_f32_e64 v46, -v44
	v_add_f32_e32 v183, v183, v44
	v_pk_add_f32 v[34:35], v[34:35], v[44:45] op_sel_hi:[1,0] neg_lo:[0,1] neg_hi:[0,1]
	v_pk_add_f32 v[36:37], v[36:37], v[44:45] op_sel_hi:[1,0] neg_lo:[0,1] neg_hi:[0,1]
	v_mul_f32_e32 v1, v1, v46
	v_pk_add_f32 v[50:51], v[50:51], v[44:45] op_sel_hi:[1,0] neg_lo:[0,1] neg_hi:[0,1]
	v_pk_add_f32 v[52:53], v[52:53], v[44:45] op_sel_hi:[1,0] neg_lo:[0,1] neg_hi:[0,1]
	v_pk_add_f32 v[54:55], v[54:55], v[44:45] op_sel_hi:[1,0] neg_lo:[0,1] neg_hi:[0,1]
	v_pk_add_f32 v[38:39], v[38:39], v[44:45] op_sel_hi:[1,0] neg_lo:[0,1] neg_hi:[0,1]
	v_pk_add_f32 v[40:41], v[40:41], v[44:45] op_sel_hi:[1,0] neg_lo:[0,1] neg_hi:[0,1]
	v_pk_mul_f32 v[32:33], v[32:33], v[46:47] op_sel_hi:[1,0]
	v_pk_mul_f32 v[30:31], v[30:31], v[46:47] op_sel_hi:[1,0]
	v_pk_mul_f32 v[28:29], v[28:29], v[46:47] op_sel_hi:[1,0]
	v_pk_mul_f32 v[26:27], v[26:27], v[46:47] op_sel_hi:[1,0]
	v_pk_mul_f32 v[24:25], v[24:25], v[46:47] op_sel_hi:[1,0]
	v_pk_mul_f32 v[22:23], v[22:23], v[46:47] op_sel_hi:[1,0]
	v_pk_mul_f32 v[20:21], v[20:21], v[46:47] op_sel_hi:[1,0]
	v_pk_mul_f32 v[18:19], v[18:19], v[46:47] op_sel_hi:[1,0]
	v_pk_mul_f32 v[16:17], v[16:17], v[46:47] op_sel_hi:[1,0]
	v_pk_mul_f32 v[14:15], v[14:15], v[46:47] op_sel_hi:[1,0]
	v_pk_mul_f32 v[12:13], v[12:13], v[46:47] op_sel_hi:[1,0]
	v_pk_mul_f32 v[10:11], v[10:11], v[46:47] op_sel_hi:[1,0]
	v_pk_mul_f32 v[8:9], v[8:9], v[46:47] op_sel_hi:[1,0]
	v_pk_mul_f32 v[6:7], v[6:7], v[46:47] op_sel_hi:[1,0]
	v_pk_mul_f32 v[4:5], v[4:5], v[46:47] op_sel_hi:[1,0]
	v_pk_mul_f32 v[2:3], v[2:3], v[46:47] op_sel_hi:[1,0]
	v_pk_add_f32 v[42:43], v[42:43], v[44:45] op_sel_hi:[1,0] neg_lo:[0,1] neg_hi:[0,1]

; #define PG8_STAGE(bufoff, gbase, voff) do { _Pragma("unroll") for (int _i = 0; _i < 2; ++_i) \
;         __builtin_amdgcn_global_load_lds((const unsigned*)((const char*)(gbase) + (voff)[_i]), (PG8_LAS unsigned*)(lds + (bufoff) + ldsw + _i * 8192), 16, 0, 0); } while (0)
; #define PG8_LDA(dst, b, h) do { _Pragma("unroll") for (int m = 0; m < 4; ++m) _Pragma("unroll") for (int k = 0; k < 2; ++k) dst[m][k] = *(const PG8_LAS bf16x8*)(lds + PG8_SA(b, h) + aoff + m * 2048 + k * 1024); } while (0)
; #define PG8_LDB(dst, b, h) do { _Pragma("unroll") for (int n = 0; n < 2; ++n) _Pragma("unroll") for (int k = 0; k < 2; ++k) dst[n][k] = *(const PG8_LAS bf16x8*)(lds + PG8_SB(b, h) + boff + n * 2048 + k * 1024); } while (0)
; #define PG8_MMA(ai, bj, At, Bt) do { __builtin_amdgcn_s_setprio(1); _Pragma("unroll") for (int m = 0; m < 4; ++m) _Pragma("unroll") for (int n = 0; n < 2; ++n) _Pragma("unroll") for (int k = 0; k < 2; ++k) \
;         acc[ai][bj][m][n] = __builtin_amdgcn_mfma_f32_16x16x32_bf16(Bt[n][k], At[m][k], acc[ai][bj][m][n], 0, 0, 0); __builtin_amdgcn_s_setprio(0); } while (0)
; #define PG8_WAIT_V(n) asm volatile("s_waitcnt vmcnt(" #n ")" ::: "memory")
; #define PG8_WAIT_L(n) asm volatile("s_waitcnt lgkmcnt(" #n ")" ::: "memory")
; template <class Epi, class Sched, bool ALIGN_EPI = false, bool SP2 = false>
; __device__ __forceinline__ void gemm_phase(PG8_LAS unsigned char* lds, const Gemm g, const Sched& S, const Epi& E) {
;     ...
;             const bool last = (t == nt - 2);
;             const char* a1 = cA + (size_t)(t + 1) * kstep;
;             const char* a2 = last ? nA : cA + (size_t)(t + 2) * kstep; const char* b2 = last ? nB : cB + (size_t)(t + 2) * kstep;
;             const char* a3 = a2 + kstep; const char* b3 = b2 + kstep;
;             if (last && has_next) S.a_ready(nxt);
;             if constexpr (SP2) {
;             PG8_LDB(B0, 0, 0); PG8_LDB(B1, 0, 1); PG8_SCHED; PG8_LDA(At, 0, 0); PG8_STAGE(PG8_SA(1, 1), a1 + hstepA, voffA);
;             PG8_WAIT_V(8); PG8_WAIT_L(0); PG8_BAR; PG8_MMA(0, 0, At, B0); PG8_MMA(0, 1, At, B1); PG8_BAR; PG8_SCHED;
;             PG8_LDA(At, 0, 1); PG8_STAGE(PG8_SB(0, 0), b2, voffB); PG8_STAGE(PG8_SB(0, 1), b2 + hstepB, voffB); PG8_STAGE(PG8_SA(0, 0), a2, voffA);
;             PG8_WAIT_V(8); PG8_WAIT_L(0); PG8_BAR; PG8_MMA(1, 0, At, B0); PG8_MMA(1, 1, At, B1); PG8_BAR; PG8_SCHED;
.LBB0_1160:
	s_add_u32 s24, s22, 0x100
	s_addc_u32 s25, s23, 0
	s_add_i32 s57, 0, 0x10000
	s_cmp_eq_u32 s56, 4
	s_cselect_b32 s29, s17, s25
	s_cselect_b32 s28, s16, s24
	v_add_u32_e32 v145, s57, v142
	s_cselect_b32 s27, s52, s55
	s_cselect_b32 s26, s53, s54
	s_add_i32 s58, 0, 0x14000
	ds_read_b128 v[146:149], v145
	ds_read_b128 v[150:153], v145 offset:1024
	ds_read_b128 v[154:157], v145 offset:2048
	ds_read_b128 v[158:161], v145 offset:3072
	v_add_u32_e32 v145, s58, v142
	ds_read_b128 v[162:165], v145
	ds_read_b128 v[166:169], v145 offset:1024
	ds_read_b128 v[170:173], v145 offset:2048
	ds_read_b128 v[174:177], v145 offset:3072
	v_lshl_add_u64 v[186:187], s[22:23], 0, v[138:139]
	s_add_i32 m0, s39, 0xc000
	ds_read_b128 v[178:181], v143
	ds_read_b128 v[182:185], v143 offset:1024
	ds_read_b128 v[202:205], v143 offset:2048
	ds_read_b128 v[206:209], v143 offset:3072
	ds_read_b128 v[210:213], v143 offset:4096
	ds_read_b128 v[232:235], v143 offset:5120
	ds_read_b128 v[236:239], v143 offset:6144
	ds_read_b128 v[240:243], v143 offset:7168
	global_load_lds_dwordx4 v[186:187], off
	v_lshl_add_u64 v[186:187], s[22:23], 0, v[140:141]
	s_add_i32 m0, s39, 0xe000
	s_nop 0
	global_load_lds_dwordx4 v[186:187], off
	s_waitcnt vmcnt(8)
	s_waitcnt lgkmcnt(0)
	s_barrier
	s_setprio 1
	s_waitcnt lgkmcnt(0)
	v_mfma_f32_16x16x32_bf16 v[126:129], v[146:149], v[178:181], v[126:129]
	v_mfma_f32_16x16x32_bf16 v[122:125], v[154:157], v[178:181], v[122:125]
	v_mfma_f32_16x16x32_bf16 v[118:121], v[146:149], v[202:205], v[118:121]
	v_mfma_f32_16x16x32_bf16 v[114:117], v[154:157], v[202:205], v[114:117]
	v_mfma_f32_16x16x32_bf16 v[110:113], v[146:149], v[210:213], v[110:113]
	v_mfma_f32_16x16x32_bf16 v[106:109], v[154:157], v[210:213], v[106:109]
	v_mfma_f32_16x16x32_bf16 v[102:105], v[146:149], v[236:239], v[102:105]
	v_mfma_f32_16x16x32_bf16 v[98:101], v[154:157], v[236:239], v[98:101]
	v_mfma_f32_16x16x32_bf16 v[126:129], v[150:153], v[182:185], v[126:129]
	v_mfma_f32_16x16x32_bf16 v[122:125], v[158:161], v[182:185], v[122:125]
	v_mfma_f32_16x16x32_bf16 v[118:121], v[150:153], v[206:209], v[118:121]
	v_mfma_f32_16x16x32_bf16 v[114:117], v[158:161], v[206:209], v[114:117]
	v_mfma_f32_16x16x32_bf16 v[110:113], v[150:153], v[232:235], v[110:113]
	v_mfma_f32_16x16x32_bf16 v[106:109], v[158:161], v[232:235], v[106:109]
	v_mfma_f32_16x16x32_bf16 v[102:105], v[150:153], v[240:243], v[102:105]
	v_mfma_f32_16x16x32_bf16 v[98:101], v[158:161], v[240:243], v[98:101]
	s_setprio 0
	s_setprio 1
	v_mfma_f32_16x16x32_bf16 v[78:81], v[162:165], v[178:181], v[78:81]
	v_mfma_f32_16x16x32_bf16 v[70:73], v[170:173], v[178:181], v[70:73]
	v_mfma_f32_16x16x32_bf16 v[62:65], v[162:165], v[202:205], v[62:65]
	v_mfma_f32_16x16x32_bf16 v[54:57], v[170:173], v[202:205], v[54:57]
	v_mfma_f32_16x16x32_bf16 v[46:49], v[162:165], v[210:213], v[46:49]
	v_mfma_f32_16x16x32_bf16 v[42:45], v[170:173], v[210:213], v[42:45]
	v_mfma_f32_16x16x32_bf16 v[38:41], v[162:165], v[236:239], v[38:41]
	v_mfma_f32_16x16x32_bf16 v[34:37], v[170:173], v[236:239], v[34:37]
	v_mfma_f32_16x16x32_bf16 v[78:81], v[166:169], v[182:185], v[78:81]
	v_mfma_f32_16x16x32_bf16 v[70:73], v[174:177], v[182:185], v[70:73]
	v_mfma_f32_16x16x32_bf16 v[62:65], v[166:169], v[206:209], v[62:65]
	v_mfma_f32_16x16x32_bf16 v[54:57], v[174:177], v[206:209], v[54:57]
	v_mfma_f32_16x16x32_bf16 v[46:49], v[166:169], v[232:235], v[46:49]
	v_mfma_f32_16x16x32_bf16 v[42:45], v[174:177], v[232:235], v[42:45]
	v_mfma_f32_16x16x32_bf16 v[38:41], v[166:169], v[240:243], v[38:41]
	v_mfma_f32_16x16x32_bf16 v[34:37], v[174:177], v[240:243], v[34:37]
	s_setprio 0
	s_barrier
	s_add_i32 s22, s57, s38
	v_lshl_add_u64 v[186:187], s[26:27], 0, v[134:135]
	s_mov_b32 m0, s22
	ds_read_b128 v[178:181], v143 offset:16384
	ds_read_b128 v[182:185], v143 offset:17408
	ds_read_b128 v[202:205], v143 offset:18432
	ds_read_b128 v[206:209], v143 offset:19456
	ds_read_b128 v[210:213], v143 offset:20480
	ds_read_b128 v[232:235], v143 offset:21504
	ds_read_b128 v[236:239], v143 offset:22528
	ds_read_b128 v[240:243], v143 offset:23552
	global_load_lds_dwordx4 v[186:187], off
	s_add_i32 m0, s22, 0x2000
	s_add_u32 s22, s26, 0x20000
	v_lshl_add_u64 v[214:215], s[26:27], 0, v[130:131]
	s_addc_u32 s23, s27, 0
	s_add_i32 s57, s58, s38
	global_load_lds_dwordx4 v[214:215], off
	v_lshl_add_u64 v[244:245], s[22:23], 0, v[134:135]
	s_mov_b32 m0, s57
	v_lshl_add_u64 v[246:247], s[28:29], 0, v[132:133]
	global_load_lds_dwordx4 v[244:245], off
	v_lshl_add_u64 v[244:245], s[22:23], 0, v[130:131]
	s_add_i32 m0, s57, 0x2000
	s_nop 0
	global_load_lds_dwordx4 v[244:245], off
	v_lshl_add_u64 v[244:245], s[28:29], 0, v[136:137]
	s_mov_b32 m0, s39
	s_nop 0
	global_load_lds_dwordx4 v[244:245], off
	s_mov_b32 m0, s40
	s_nop 0
	global_load_lds_dwordx4 v[246:247], off
	s_waitcnt vmcnt(8)
	s_waitcnt lgkmcnt(0)
	s_barrier
; #define PG8_STAGE(bufoff, gbase, voff) do { _Pragma("unroll") for (int _i = 0; _i < 2; ++_i) \
;         __builtin_amdgcn_global_load_lds((const unsigned*)((const char*)(gbase) + (voff)[_i]), (PG8_LAS unsigned*)(lds + (bufoff) + ldsw + _i * 8192), 16, 0, 0); } while (0)
; #define PG8_LDA(dst, b, h) do { _Pragma("unroll") for (int m = 0; m < 4; ++m) _Pragma("unroll") for (int k = 0; k < 2; ++k) dst[m][k] = *(const PG8_LAS bf16x8*)(lds + PG8_SA(b, h) + aoff + m * 2048 + k * 1024); } while (0)
; #define PG8_LDB(dst, b, h) do { _Pragma("unroll") for (int n = 0; n < 2; ++n) _Pragma("unroll") for (int k = 0; k < 2; ++k) dst[n][k] = *(const PG8_LAS bf16x8*)(lds + PG8_SB(b, h) + boff + n * 2048 + k * 1024); } while (0)
; #define PG8_MMA(ai, bj, At, Bt) do { __builtin_amdgcn_s_setprio(1); _Pragma("unroll") for (int m = 0; m < 4; ++m) _Pragma("unroll") for (int n = 0; n < 2; ++n) _Pragma("unroll") for (int k = 0; k < 2; ++k) \
;         acc[ai][bj][m][n] = __builtin_amdgcn_mfma_f32_16x16x32_bf16(Bt[n][k], At[m][k], acc[ai][bj][m][n], 0, 0, 0); __builtin_amdgcn_s_setprio(0); } while (0)
; #define PG8_WAIT_V(n) asm volatile("s_waitcnt vmcnt(" #n ")" ::: "memory")
; #define PG8_WAIT_L(n) asm volatile("s_waitcnt lgkmcnt(" #n ")" ::: "memory")
; #define PG8_BAR __builtin_amdgcn_s_barrier()
; #define PG8_SCHED __builtin_amdgcn_sched_barrier(0)
; template <class Epi, class Sched, bool ALIGN_EPI = false, bool SP2 = false>
; __device__ __forceinline__ void gemm_phase(PG8_LAS unsigned char* lds, const Gemm g, const Sched& S, const Epi& E) {
;     ...
;             PG8_WAIT_V(8); PG8_WAIT_L(0); PG8_BAR; PG8_MMA(1, 0, At, B0); PG8_MMA(1, 1, At, B1); PG8_BAR; PG8_SCHED;
;             PG8_LDB(B0, 1, 0); PG8_LDB(B1, 1, 1); PG8_SCHED; PG8_LDA(At, 1, 0); PG8_STAGE(PG8_SA(0, 1), a2 + hstepA, voffA);
;             PG8_WAIT_V(8); PG8_WAIT_L(0); PG8_BAR; PG8_MMA(0, 0, At, B0); PG8_MMA(0, 1, At, B1); PG8_BAR; PG8_SCHED;
;             PG8_LDA(At, 1, 1); PG8_STAGE(PG8_SB(1, 0), b3, voffB); PG8_STAGE(PG8_SB(1, 1), b3 + hstepB, voffB); PG8_STAGE(PG8_SA(1, 0), a3, voffA);
	s_setprio 1
	s_waitcnt lgkmcnt(0)
	v_mfma_f32_16x16x32_bf16 v[94:97], v[146:149], v[178:181], v[94:97]
	v_mfma_f32_16x16x32_bf16 v[90:93], v[154:157], v[178:181], v[90:93]
	v_mfma_f32_16x16x32_bf16 v[86:89], v[146:149], v[202:205], v[86:89]
	v_mfma_f32_16x16x32_bf16 v[82:85], v[154:157], v[202:205], v[82:85]
	v_mfma_f32_16x16x32_bf16 v[74:77], v[146:149], v[210:213], v[74:77]
	v_mfma_f32_16x16x32_bf16 v[66:69], v[154:157], v[210:213], v[66:69]
	v_mfma_f32_16x16x32_bf16 v[58:61], v[146:149], v[236:239], v[58:61]
	v_mfma_f32_16x16x32_bf16 v[50:53], v[154:157], v[236:239], v[50:53]
	v_mfma_f32_16x16x32_bf16 v[94:97], v[150:153], v[182:185], v[94:97]
	v_mfma_f32_16x16x32_bf16 v[90:93], v[158:161], v[182:185], v[90:93]
	v_mfma_f32_16x16x32_bf16 v[86:89], v[150:153], v[206:209], v[86:89]
	v_mfma_f32_16x16x32_bf16 v[82:85], v[158:161], v[206:209], v[82:85]
	v_mfma_f32_16x16x32_bf16 v[74:77], v[150:153], v[232:235], v[74:77]
	v_mfma_f32_16x16x32_bf16 v[66:69], v[158:161], v[232:235], v[66:69]
	v_mfma_f32_16x16x32_bf16 v[58:61], v[150:153], v[240:243], v[58:61]
	v_mfma_f32_16x16x32_bf16 v[50:53], v[158:161], v[240:243], v[50:53]
	s_setprio 0
	s_setprio 1
	v_mfma_f32_16x16x32_bf16 v[30:33], v[162:165], v[178:181], v[30:33]
	v_mfma_f32_16x16x32_bf16 v[26:29], v[170:173], v[178:181], v[26:29]
	v_mfma_f32_16x16x32_bf16 v[22:25], v[162:165], v[202:205], v[22:25]
	v_mfma_f32_16x16x32_bf16 v[18:21], v[170:173], v[202:205], v[18:21]
	v_mfma_f32_16x16x32_bf16 v[14:17], v[162:165], v[210:213], v[14:17]
	v_mfma_f32_16x16x32_bf16 v[10:13], v[170:173], v[210:213], v[10:13]
	v_mfma_f32_16x16x32_bf16 v[6:9], v[162:165], v[236:239], v[6:9]
	v_mfma_f32_16x16x32_bf16 v[2:5], v[170:173], v[236:239], v[2:5]
	v_mfma_f32_16x16x32_bf16 v[30:33], v[166:169], v[182:185], v[30:33]
	v_mfma_f32_16x16x32_bf16 v[26:29], v[174:177], v[182:185], v[26:29]
	v_mfma_f32_16x16x32_bf16 v[22:25], v[166:169], v[206:209], v[22:25]
	v_mfma_f32_16x16x32_bf16 v[18:21], v[174:177], v[206:209], v[18:21]
	v_mfma_f32_16x16x32_bf16 v[14:17], v[166:169], v[232:235], v[14:17]
	v_mfma_f32_16x16x32_bf16 v[10:13], v[174:177], v[232:235], v[10:13]
	v_mfma_f32_16x16x32_bf16 v[6:9], v[166:169], v[240:243], v[6:9]
	v_mfma_f32_16x16x32_bf16 v[2:5], v[174:177], v[240:243], v[2:5]
	s_setprio 0
	s_barrier
	s_add_i32 s57, 0, 0x18000
	v_add_u32_e32 v145, s57, v142
	s_add_i32 s58, 0, 0x1c000
	ds_read_b128 v[146:149], v145
	ds_read_b128 v[150:153], v145 offset:1024
	ds_read_b128 v[154:157], v145 offset:2048
	ds_read_b128 v[158:161], v145 offset:3072
	v_add_u32_e32 v145, s58, v142
	ds_read_b128 v[162:165], v145
	ds_read_b128 v[166:169], v145 offset:1024
	ds_read_b128 v[170:173], v145 offset:2048
	ds_read_b128 v[174:177], v145 offset:3072
	s_add_u32 s22, s28, 0x30000
	s_addc_u32 s23, s29, 0
	s_mov_b32 m0, s41
	v_lshl_add_u64 v[248:249], s[22:23], 0, v[136:137]
	ds_read_b128 v[178:181], v143 offset:32768
	ds_read_b128 v[182:185], v143 offset:33792
	ds_read_b128 v[202:205], v143 offset:34816
	ds_read_b128 v[206:209], v143 offset:35840
	ds_read_b128 v[210:213], v143 offset:36864
	ds_read_b128 v[232:235], v143 offset:37888
	ds_read_b128 v[236:239], v143 offset:38912
	ds_read_b128 v[240:243], v143 offset:39936
	global_load_lds_dwordx4 v[248:249], off
	v_lshl_add_u64 v[248:249], s[22:23], 0, v[132:133]
	s_mov_b32 m0, s42
	s_nop 0
	global_load_lds_dwordx4 v[248:249], off
	s_waitcnt vmcnt(8)
	s_waitcnt lgkmcnt(0)
	s_barrier
	s_setprio 1
	s_waitcnt lgkmcnt(0)
	v_mfma_f32_16x16x32_bf16 v[126:129], v[146:149], v[178:181], v[126:129]
	v_mfma_f32_16x16x32_bf16 v[122:125], v[154:157], v[178:181], v[122:125]
	v_mfma_f32_16x16x32_bf16 v[118:121], v[146:149], v[202:205], v[118:121]
	v_mfma_f32_16x16x32_bf16 v[114:117], v[154:157], v[202:205], v[114:117]
	v_mfma_f32_16x16x32_bf16 v[110:113], v[146:149], v[210:213], v[110:113]
	v_mfma_f32_16x16x32_bf16 v[106:109], v[154:157], v[210:213], v[106:109]
	v_mfma_f32_16x16x32_bf16 v[102:105], v[146:149], v[236:239], v[102:105]
	v_mfma_f32_16x16x32_bf16 v[98:101], v[154:157], v[236:239], v[98:101]
	v_mfma_f32_16x16x32_bf16 v[126:129], v[150:153], v[182:185], v[126:129]
	v_mfma_f32_16x16x32_bf16 v[122:125], v[158:161], v[182:185], v[122:125]
	v_mfma_f32_16x16x32_bf16 v[118:121], v[150:153], v[206:209], v[118:121]
	v_mfma_f32_16x16x32_bf16 v[114:117], v[158:161], v[206:209], v[114:117]
	v_mfma_f32_16x16x32_bf16 v[110:113], v[150:153], v[232:235], v[110:113]
	v_mfma_f32_16x16x32_bf16 v[106:109], v[158:161], v[232:235], v[106:109]
	v_mfma_f32_16x16x32_bf16 v[102:105], v[150:153], v[240:243], v[102:105]
	v_mfma_f32_16x16x32_bf16 v[98:101], v[158:161], v[240:243], v[98:101]
	s_setprio 0
	s_setprio 1
	v_mfma_f32_16x16x32_bf16 v[78:81], v[162:165], v[178:181], v[78:81]
	v_mfma_f32_16x16x32_bf16 v[70:73], v[170:173], v[178:181], v[70:73]
	v_mfma_f32_16x16x32_bf16 v[62:65], v[162:165], v[202:205], v[62:65]
	v_mfma_f32_16x16x32_bf16 v[54:57], v[170:173], v[202:205], v[54:57]
	v_mfma_f32_16x16x32_bf16 v[46:49], v[162:165], v[210:213], v[46:49]
	v_mfma_f32_16x16x32_bf16 v[42:45], v[170:173], v[210:213], v[42:45]
	v_mfma_f32_16x16x32_bf16 v[38:41], v[162:165], v[236:239], v[38:41]
	v_mfma_f32_16x16x32_bf16 v[34:37], v[170:173], v[236:239], v[34:37]
	v_mfma_f32_16x16x32_bf16 v[78:81], v[166:169], v[182:185], v[78:81]
	v_mfma_f32_16x16x32_bf16 v[70:73], v[174:177], v[182:185], v[70:73]
	v_mfma_f32_16x16x32_bf16 v[62:65], v[166:169], v[206:209], v[62:65]
	v_mfma_f32_16x16x32_bf16 v[54:57], v[174:177], v[206:209], v[54:57]
	v_mfma_f32_16x16x32_bf16 v[46:49], v[166:169], v[232:235], v[46:49]
	v_mfma_f32_16x16x32_bf16 v[42:45], v[174:177], v[232:235], v[42:45]
	v_mfma_f32_16x16x32_bf16 v[38:41], v[166:169], v[240:243], v[38:41]
	v_mfma_f32_16x16x32_bf16 v[34:37], v[174:177], v[240:243], v[34:37]
	s_setprio 0
	s_barrier
; #define PG8_STAGE(bufoff, gbase, voff) do { _Pragma("unroll") for (int _i = 0; _i < 2; ++_i) \
;         __builtin_amdgcn_global_load_lds((const unsigned*)((const char*)(gbase) + (voff)[_i]), (PG8_LAS unsigned*)(lds + (bufoff) + ldsw + _i * 8192), 16, 0, 0); } while (0)
; #define PG8_LDA(dst, b, h) do { _Pragma("unroll") for (int m = 0; m < 4; ++m) _Pragma("unroll") for (int k = 0; k < 2; ++k) dst[m][k] = *(const PG8_LAS bf16x8*)(lds + PG8_SA(b, h) + aoff + m * 2048 + k * 1024); } while (0)
; #define PG8_MMA(ai, bj, At, Bt) do { __builtin_amdgcn_s_setprio(1); _Pragma("unroll") for (int m = 0; m < 4; ++m) _Pragma("unroll") for (int n = 0; n < 2; ++n) _Pragma("unroll") for (int k = 0; k < 2; ++k) \
;         acc[ai][bj][m][n] = __builtin_amdgcn_mfma_f32_16x16x32_bf16(Bt[n][k], At[m][k], acc[ai][bj][m][n], 0, 0, 0); __builtin_amdgcn_s_setprio(0); } while (0)
; #define PG8_WAIT_V(n) asm volatile("s_waitcnt vmcnt(" #n ")" ::: "memory")
; #define PG8_WAIT_L(n) asm volatile("s_waitcnt lgkmcnt(" #n ")" ::: "memory")
; #define PG8_BAR __builtin_amdgcn_s_barrier()
; #define PG8_SCHED __builtin_amdgcn_sched_barrier(0)
; template <class Epi, class Sched, bool ALIGN_EPI = false, bool SP2 = false>
; __device__ __forceinline__ void gemm_phase(PG8_LAS unsigned char* lds, const Gemm g, const Sched& S, const Epi& E) {
;     ...
;         for (int t = 0; t < nt; t += 2) {
;     ...
;             PG8_LDA(At, 1, 1); PG8_STAGE(PG8_SB(1, 0), b3, voffB); PG8_STAGE(PG8_SB(1, 1), b3 + hstepB, voffB); PG8_STAGE(PG8_SA(1, 0), a3, voffA);
;             PG8_WAIT_V(8); PG8_WAIT_L(0); PG8_BAR; PG8_MMA(1, 0, At, B0); PG8_MMA(1, 1, At, B1); PG8_BAR; PG8_SCHED;
	s_add_i32 s22, s57, s38
	v_lshl_add_u64 v[186:187], v[186:187], 0, s[96:97]
	s_mov_b32 m0, s22
	ds_read_b128 v[178:181], v143 offset:49152
	ds_read_b128 v[182:185], v143 offset:50176
	ds_read_b128 v[202:205], v143 offset:51200
	ds_read_b128 v[206:209], v143 offset:52224
	ds_read_b128 v[210:213], v143 offset:53248
	ds_read_b128 v[232:235], v143 offset:54272
	ds_read_b128 v[236:239], v143 offset:55296
	ds_read_b128 v[240:243], v143 offset:56320
	global_load_lds_dwordx4 v[186:187], off
	s_add_i32 m0, s22, 0x2000
	s_add_u32 s22, s26, 0x20080
	v_lshl_add_u64 v[186:187], v[214:215], 0, s[96:97]
	s_addc_u32 s23, s27, 0
	s_add_i32 s26, s58, s38
	global_load_lds_dwordx4 v[186:187], off
	v_lshl_add_u64 v[186:187], s[22:23], 0, v[134:135]
	s_mov_b32 m0, s26
	s_nop 0
	global_load_lds_dwordx4 v[186:187], off
	v_lshl_add_u64 v[186:187], s[22:23], 0, v[130:131]
	s_add_i32 m0, s26, 0x2000
	s_nop 0
	global_load_lds_dwordx4 v[186:187], off
	v_lshl_add_u64 v[186:187], v[244:245], 0, s[96:97]
	s_mov_b32 m0, s43
	s_nop 0
	global_load_lds_dwordx4 v[186:187], off
	v_lshl_add_u64 v[186:187], v[246:247], 0, s[96:97]
	s_mov_b32 m0, s46
	s_nop 0
	global_load_lds_dwordx4 v[186:187], off
	s_waitcnt vmcnt(8)
	s_waitcnt lgkmcnt(0)
	s_barrier
	s_setprio 1
	s_waitcnt lgkmcnt(0)
	v_mfma_f32_16x16x32_bf16 v[94:97], v[146:149], v[178:181], v[94:97]
	v_mfma_f32_16x16x32_bf16 v[90:93], v[154:157], v[178:181], v[90:93]
	v_mfma_f32_16x16x32_bf16 v[86:89], v[146:149], v[202:205], v[86:89]
	v_mfma_f32_16x16x32_bf16 v[82:85], v[154:157], v[202:205], v[82:85]
	v_mfma_f32_16x16x32_bf16 v[74:77], v[146:149], v[210:213], v[74:77]
	v_mfma_f32_16x16x32_bf16 v[66:69], v[154:157], v[210:213], v[66:69]
	v_mfma_f32_16x16x32_bf16 v[58:61], v[146:149], v[236:239], v[58:61]
	v_mfma_f32_16x16x32_bf16 v[50:53], v[154:157], v[236:239], v[50:53]
	v_mfma_f32_16x16x32_bf16 v[94:97], v[150:153], v[182:185], v[94:97]
	v_mfma_f32_16x16x32_bf16 v[90:93], v[158:161], v[182:185], v[90:93]
	v_mfma_f32_16x16x32_bf16 v[86:89], v[150:153], v[206:209], v[86:89]
	v_mfma_f32_16x16x32_bf16 v[82:85], v[158:161], v[206:209], v[82:85]
	v_mfma_f32_16x16x32_bf16 v[74:77], v[150:153], v[232:235], v[74:77]
	v_mfma_f32_16x16x32_bf16 v[66:69], v[158:161], v[232:235], v[66:69]
	v_mfma_f32_16x16x32_bf16 v[58:61], v[150:153], v[240:243], v[58:61]
	v_mfma_f32_16x16x32_bf16 v[50:53], v[158:161], v[240:243], v[50:53]
	s_setprio 0
	s_setprio 1
	v_mfma_f32_16x16x32_bf16 v[30:33], v[162:165], v[178:181], v[30:33]
	v_mfma_f32_16x16x32_bf16 v[26:29], v[170:173], v[178:181], v[26:29]
	v_mfma_f32_16x16x32_bf16 v[22:25], v[162:165], v[202:205], v[22:25]
	v_mfma_f32_16x16x32_bf16 v[18:21], v[170:173], v[202:205], v[18:21]
	v_mfma_f32_16x16x32_bf16 v[14:17], v[162:165], v[210:213], v[14:17]
	v_mfma_f32_16x16x32_bf16 v[10:13], v[170:173], v[210:213], v[10:13]
	v_mfma_f32_16x16x32_bf16 v[6:9], v[162:165], v[236:239], v[6:9]
	v_mfma_f32_16x16x32_bf16 v[2:5], v[170:173], v[236:239], v[2:5]
	v_mfma_f32_16x16x32_bf16 v[30:33], v[166:169], v[182:185], v[30:33]
	v_mfma_f32_16x16x32_bf16 v[26:29], v[174:177], v[182:185], v[26:29]
	v_mfma_f32_16x16x32_bf16 v[22:25], v[166:169], v[206:209], v[22:25]
	v_mfma_f32_16x16x32_bf16 v[18:21], v[174:177], v[206:209], v[18:21]
	v_mfma_f32_16x16x32_bf16 v[14:17], v[166:169], v[232:235], v[14:17]
	v_mfma_f32_16x16x32_bf16 v[10:13], v[174:177], v[232:235], v[10:13]
	v_mfma_f32_16x16x32_bf16 v[6:9], v[166:169], v[240:243], v[6:9]
	v_mfma_f32_16x16x32_bf16 v[2:5], v[174:177], v[240:243], v[2:5]
	s_setprio 0
	s_add_i32 s56, s56, 2
	s_add_u32 s54, s54, 0x100
	s_addc_u32 s55, s55, 0
	s_cmp_gt_u32 s56, 5
	s_mov_b64 s[22:23], s[24:25]
	s_barrier
	s_cbranch_scc0 .LBB0_1160
	s_and_b64 vcc, exec, s[8:9]
	s_cbranch_vccz .LBB0_1163
	s_barrier

; #define PG8_STAGE(bufoff, gbase, voff) do { _Pragma("unroll") for (int _i = 0; _i < 2; ++_i) \
;         __builtin_amdgcn_global_load_lds((const unsigned*)((const char*)(gbase) + (voff)[_i]), (PG8_LAS unsigned*)(lds + (bufoff) + ldsw + _i * 8192), 16, 0, 0); } while (0)
; #define PG8_LDA(dst, b, h) do { _Pragma("unroll") for (int m = 0; m < 4; ++m) _Pragma("unroll") for (int k = 0; k < 2; ++k) dst[m][k] = *(const PG8_LAS bf16x8*)(lds + PG8_SA(b, h) + aoff + m * 2048 + k * 1024); } while (0)
; #define PG8_LDB(dst, b, h) do { _Pragma("unroll") for (int n = 0; n < 2; ++n) _Pragma("unroll") for (int k = 0; k < 2; ++k) dst[n][k] = *(const PG8_LAS bf16x8*)(lds + PG8_SB(b, h) + boff + n * 2048 + k * 1024); } while (0)
; #define PG8_MMA(ai, bj, At, Bt) do { __builtin_amdgcn_s_setprio(1); _Pragma("unroll") for (int m = 0; m < 4; ++m) _Pragma("unroll") for (int n = 0; n < 2; ++n) _Pragma("unroll") for (int k = 0; k < 2; ++k) \
;         acc[ai][bj][m][n] = __builtin_amdgcn_mfma_f32_16x16x32_bf16(Bt[n][k], At[m][k], acc[ai][bj][m][n], 0, 0, 0); __builtin_amdgcn_s_setprio(0); } while (0)
; #define PG8_WAIT_V(n) asm volatile("s_waitcnt vmcnt(" #n ")" ::: "memory")
; #define PG8_WAIT_L(n) asm volatile("s_waitcnt lgkmcnt(" #n ")" ::: "memory")
; template <class Epi, class Sched, bool ALIGN_EPI = false, bool SP2 = false>
; __device__ __forceinline__ void gemm_phase(PG8_LAS unsigned char* lds, const Gemm g, const Sched& S, const Epi& E) {
;     ...
;             const bool last = (t == nt - 2);
;             const char* a1 = cA + (size_t)(t + 1) * kstep;
;             const char* a2 = last ? nA : cA + (size_t)(t + 2) * kstep; const char* b2 = last ? nB : cB + (size_t)(t + 2) * kstep;
;             const char* a3 = a2 + kstep; const char* b3 = b2 + kstep;
;             if (last && has_next) S.a_ready(nxt);
;             if constexpr (SP2) {
;             PG8_LDB(B0, 0, 0); PG8_LDB(B1, 0, 1); PG8_SCHED; PG8_LDA(At, 0, 0); PG8_STAGE(PG8_SA(1, 1), a1 + hstepA, voffA);
;             PG8_WAIT_V(8); PG8_WAIT_L(0); PG8_BAR; PG8_MMA(0, 0, At, B0); PG8_MMA(0, 1, At, B1); PG8_BAR; PG8_SCHED;
;             PG8_LDA(At, 0, 1); PG8_STAGE(PG8_SB(0, 0), b2, voffB); PG8_STAGE(PG8_SB(0, 1), b2 + hstepB, voffB); PG8_STAGE(PG8_SA(0, 0), a2, voffA);
;             PG8_WAIT_V(8); PG8_WAIT_L(0); PG8_BAR; PG8_MMA(1, 0, At, B0); PG8_MMA(1, 1, At, B1); PG8_BAR; PG8_SCHED;
.LBB0_1190:
	s_add_u32 s24, s22, 0xfffc0080
	s_addc_u32 s25, s23, -1
	s_add_i32 s51, 0, 0x10000
	s_cmp_eq_u32 s50, 12
	s_cselect_b32 s27, s44, s25
	s_cselect_b32 s26, s45, s24
	s_cselect_b32 s25, s46, s49
	s_cselect_b32 s24, s47, s48
	s_add_i32 s54, 0, 0x14000
	v_add_u32_e32 v142, s51, v168
	v_add_u32_e32 v166, s54, v168
	ds_read_b128 v[130:133], v142
	ds_read_b128 v[134:137], v142 offset:1024
	ds_read_b128 v[138:141], v142 offset:2048
	ds_read_b128 v[142:145], v142 offset:3072
	ds_read_b128 v[158:161], v166
	ds_read_b128 v[162:165], v166 offset:1024
	ds_read_b128 v[172:175], v166 offset:2048
	ds_read_b128 v[176:179], v166 offset:3072
	v_lshl_add_u64 v[166:167], s[22:23], 0, v[154:155]
	s_add_i32 m0, s7, 0xc000
	ds_read_b128 v[180:183], v171
	ds_read_b128 v[184:187], v171 offset:1024
	ds_read_b128 v[202:205], v171 offset:2048
	ds_read_b128 v[206:209], v171 offset:3072
	ds_read_b128 v[210:213], v171 offset:4096
	ds_read_b128 v[232:235], v171 offset:5120
	ds_read_b128 v[236:239], v171 offset:6144
	ds_read_b128 v[240:243], v171 offset:7168
	global_load_lds_dwordx4 v[166:167], off
	v_lshl_add_u64 v[166:167], s[22:23], 0, v[156:157]
	s_add_i32 m0, s7, 0xe000
	s_nop 0
	global_load_lds_dwordx4 v[166:167], off
	s_waitcnt vmcnt(8)
	s_waitcnt lgkmcnt(0)
	s_barrier
	s_setprio 1
	s_waitcnt lgkmcnt(0)
	v_mfma_f32_16x16x32_bf16 v[126:129], v[130:133], v[180:183], v[126:129]
	v_mfma_f32_16x16x32_bf16 v[118:121], v[138:141], v[180:183], v[118:121]
	v_mfma_f32_16x16x32_bf16 v[110:113], v[130:133], v[202:205], v[110:113]
	v_mfma_f32_16x16x32_bf16 v[102:105], v[138:141], v[202:205], v[102:105]
	v_mfma_f32_16x16x32_bf16 v[94:97], v[130:133], v[210:213], v[94:97]
	v_mfma_f32_16x16x32_bf16 v[86:89], v[138:141], v[210:213], v[86:89]
	v_mfma_f32_16x16x32_bf16 v[78:81], v[130:133], v[236:239], v[78:81]
	v_mfma_f32_16x16x32_bf16 v[70:73], v[138:141], v[236:239], v[70:73]
	v_mfma_f32_16x16x32_bf16 v[126:129], v[134:137], v[184:187], v[126:129]
	v_mfma_f32_16x16x32_bf16 v[118:121], v[142:145], v[184:187], v[118:121]
	v_mfma_f32_16x16x32_bf16 v[110:113], v[134:137], v[206:209], v[110:113]
	v_mfma_f32_16x16x32_bf16 v[102:105], v[142:145], v[206:209], v[102:105]
	v_mfma_f32_16x16x32_bf16 v[94:97], v[134:137], v[232:235], v[94:97]
	v_mfma_f32_16x16x32_bf16 v[86:89], v[142:145], v[232:235], v[86:89]
	v_mfma_f32_16x16x32_bf16 v[78:81], v[134:137], v[240:243], v[78:81]
	v_mfma_f32_16x16x32_bf16 v[70:73], v[142:145], v[240:243], v[70:73]
	s_setprio 0
	s_setprio 1
	v_mfma_f32_16x16x32_bf16 v[122:125], v[158:161], v[180:183], v[122:125]
	v_mfma_f32_16x16x32_bf16 v[114:117], v[172:175], v[180:183], v[114:117]
	v_mfma_f32_16x16x32_bf16 v[106:109], v[158:161], v[202:205], v[106:109]
	v_mfma_f32_16x16x32_bf16 v[98:101], v[172:175], v[202:205], v[98:101]
	v_mfma_f32_16x16x32_bf16 v[90:93], v[158:161], v[210:213], v[90:93]
	v_mfma_f32_16x16x32_bf16 v[82:85], v[172:175], v[210:213], v[82:85]
	v_mfma_f32_16x16x32_bf16 v[74:77], v[158:161], v[236:239], v[74:77]
	v_mfma_f32_16x16x32_bf16 v[66:69], v[172:175], v[236:239], v[66:69]
	v_mfma_f32_16x16x32_bf16 v[122:125], v[162:165], v[184:187], v[122:125]
	v_mfma_f32_16x16x32_bf16 v[114:117], v[176:179], v[184:187], v[114:117]
	v_mfma_f32_16x16x32_bf16 v[106:109], v[162:165], v[206:209], v[106:109]
	v_mfma_f32_16x16x32_bf16 v[98:101], v[176:179], v[206:209], v[98:101]
	v_mfma_f32_16x16x32_bf16 v[90:93], v[162:165], v[232:235], v[90:93]
	v_mfma_f32_16x16x32_bf16 v[82:85], v[176:179], v[232:235], v[82:85]
	v_mfma_f32_16x16x32_bf16 v[74:77], v[162:165], v[240:243], v[74:77]
	v_mfma_f32_16x16x32_bf16 v[66:69], v[176:179], v[240:243], v[66:69]
	s_setprio 0
	s_barrier
	s_add_i32 s51, s51, s30
	v_lshl_add_u64 v[166:167], s[24:25], 0, v[150:151]
	s_mov_b32 m0, s51
	ds_read_b128 v[180:183], v171 offset:16384
	ds_read_b128 v[184:187], v171 offset:17408
	ds_read_b128 v[202:205], v171 offset:18432
	ds_read_b128 v[206:209], v171 offset:19456
	ds_read_b128 v[210:213], v171 offset:20480
	ds_read_b128 v[232:235], v171 offset:21504
	ds_read_b128 v[236:239], v171 offset:22528
	ds_read_b128 v[240:243], v171 offset:23552
	global_load_lds_dwordx4 v[166:167], off
	s_add_i32 m0, s51, 0x2000
	s_add_u32 s52, s24, 0x40000
	v_lshl_add_u64 v[214:215], s[24:25], 0, v[146:147]
	s_addc_u32 s53, s25, 0
	s_add_i32 s51, s54, s30
	global_load_lds_dwordx4 v[214:215], off
	v_lshl_add_u64 v[244:245], s[52:53], 0, v[150:151]
	s_mov_b32 m0, s51
	v_lshl_add_u64 v[246:247], s[26:27], 0, v[148:149]
	global_load_lds_dwordx4 v[244:245], off
	v_lshl_add_u64 v[244:245], s[52:53], 0, v[146:147]
	s_add_i32 m0, s51, 0x2000
	s_nop 0
	global_load_lds_dwordx4 v[244:245], off
	v_lshl_add_u64 v[244:245], s[26:27], 0, v[152:153]
	s_mov_b32 m0, s7
	s_nop 0
	global_load_lds_dwordx4 v[244:245], off
	s_mov_b32 m0, s36
	s_nop 0
	global_load_lds_dwordx4 v[246:247], off
	s_waitcnt vmcnt(8)
	s_waitcnt lgkmcnt(0)
	s_barrier
; #define PG8_STAGE(bufoff, gbase, voff) do { _Pragma("unroll") for (int _i = 0; _i < 2; ++_i) \
;         __builtin_amdgcn_global_load_lds((const unsigned*)((const char*)(gbase) + (voff)[_i]), (PG8_LAS unsigned*)(lds + (bufoff) + ldsw + _i * 8192), 16, 0, 0); } while (0)
; #define PG8_LDA(dst, b, h) do { _Pragma("unroll") for (int m = 0; m < 4; ++m) _Pragma("unroll") for (int k = 0; k < 2; ++k) dst[m][k] = *(const PG8_LAS bf16x8*)(lds + PG8_SA(b, h) + aoff + m * 2048 + k * 1024); } while (0)
; #define PG8_LDB(dst, b, h) do { _Pragma("unroll") for (int n = 0; n < 2; ++n) _Pragma("unroll") for (int k = 0; k < 2; ++k) dst[n][k] = *(const PG8_LAS bf16x8*)(lds + PG8_SB(b, h) + boff + n * 2048 + k * 1024); } while (0)
; #define PG8_MMA(ai, bj, At, Bt) do { __builtin_amdgcn_s_setprio(1); _Pragma("unroll") for (int m = 0; m < 4; ++m) _Pragma("unroll") for (int n = 0; n < 2; ++n) _Pragma("unroll") for (int k = 0; k < 2; ++k) \
;         acc[ai][bj][m][n] = __builtin_amdgcn_mfma_f32_16x16x32_bf16(Bt[n][k], At[m][k], acc[ai][bj][m][n], 0, 0, 0); __builtin_amdgcn_s_setprio(0); } while (0)
; #define PG8_WAIT_V(n) asm volatile("s_waitcnt vmcnt(" #n ")" ::: "memory")
; #define PG8_WAIT_L(n) asm volatile("s_waitcnt lgkmcnt(" #n ")" ::: "memory")
; #define PG8_BAR __builtin_amdgcn_s_barrier()
; #define PG8_SCHED __builtin_amdgcn_sched_barrier(0)
; template <class Epi, class Sched, bool ALIGN_EPI = false, bool SP2 = false>
; __device__ __forceinline__ void gemm_phase(PG8_LAS unsigned char* lds, const Gemm g, const Sched& S, const Epi& E) {
;     ...
;             PG8_WAIT_V(8); PG8_WAIT_L(0); PG8_BAR; PG8_MMA(1, 0, At, B0); PG8_MMA(1, 1, At, B1); PG8_BAR; PG8_SCHED;
;             PG8_LDB(B0, 1, 0); PG8_LDB(B1, 1, 1); PG8_SCHED; PG8_LDA(At, 1, 0); PG8_STAGE(PG8_SA(0, 1), a2 + hstepA, voffA);
;             PG8_WAIT_V(8); PG8_WAIT_L(0); PG8_BAR; PG8_MMA(0, 0, At, B0); PG8_MMA(0, 1, At, B1); PG8_BAR; PG8_SCHED;
;             PG8_LDA(At, 1, 1); PG8_STAGE(PG8_SB(1, 0), b3, voffB); PG8_STAGE(PG8_SB(1, 1), b3 + hstepB, voffB); PG8_STAGE(PG8_SA(1, 0), a3, voffA);
	s_setprio 1
	s_waitcnt lgkmcnt(0)
	v_mfma_f32_16x16x32_bf16 v[62:65], v[130:133], v[180:183], v[62:65]
	v_mfma_f32_16x16x32_bf16 v[54:57], v[138:141], v[180:183], v[54:57]
	v_mfma_f32_16x16x32_bf16 v[46:49], v[130:133], v[202:205], v[46:49]
	v_mfma_f32_16x16x32_bf16 v[38:41], v[138:141], v[202:205], v[38:41]
	v_mfma_f32_16x16x32_bf16 v[30:33], v[130:133], v[210:213], v[30:33]
	v_mfma_f32_16x16x32_bf16 v[22:25], v[138:141], v[210:213], v[22:25]
	v_mfma_f32_16x16x32_bf16 v[14:17], v[130:133], v[236:239], v[14:17]
	v_mfma_f32_16x16x32_bf16 v[6:9], v[138:141], v[236:239], v[6:9]
	v_mfma_f32_16x16x32_bf16 v[62:65], v[134:137], v[184:187], v[62:65]
	v_mfma_f32_16x16x32_bf16 v[54:57], v[142:145], v[184:187], v[54:57]
	v_mfma_f32_16x16x32_bf16 v[46:49], v[134:137], v[206:209], v[46:49]
	v_mfma_f32_16x16x32_bf16 v[38:41], v[142:145], v[206:209], v[38:41]
	v_mfma_f32_16x16x32_bf16 v[30:33], v[134:137], v[232:235], v[30:33]
	v_mfma_f32_16x16x32_bf16 v[22:25], v[142:145], v[232:235], v[22:25]
	v_mfma_f32_16x16x32_bf16 v[14:17], v[134:137], v[240:243], v[14:17]
	v_mfma_f32_16x16x32_bf16 v[6:9], v[142:145], v[240:243], v[6:9]
	s_setprio 0
	s_setprio 1
	v_mfma_f32_16x16x32_bf16 v[58:61], v[158:161], v[180:183], v[58:61]
	v_mfma_f32_16x16x32_bf16 v[50:53], v[172:175], v[180:183], v[50:53]
	v_mfma_f32_16x16x32_bf16 v[42:45], v[158:161], v[202:205], v[42:45]
	v_mfma_f32_16x16x32_bf16 v[34:37], v[172:175], v[202:205], v[34:37]
	v_mfma_f32_16x16x32_bf16 v[26:29], v[158:161], v[210:213], v[26:29]
	v_mfma_f32_16x16x32_bf16 v[18:21], v[172:175], v[210:213], v[18:21]
	v_mfma_f32_16x16x32_bf16 v[10:13], v[158:161], v[236:239], v[10:13]
	v_mfma_f32_16x16x32_bf16 v[2:5], v[172:175], v[236:239], v[2:5]
	v_mfma_f32_16x16x32_bf16 v[58:61], v[162:165], v[184:187], v[58:61]
	v_mfma_f32_16x16x32_bf16 v[50:53], v[176:179], v[184:187], v[50:53]
	v_mfma_f32_16x16x32_bf16 v[42:45], v[162:165], v[206:209], v[42:45]
	v_mfma_f32_16x16x32_bf16 v[34:37], v[176:179], v[206:209], v[34:37]
	v_mfma_f32_16x16x32_bf16 v[26:29], v[162:165], v[232:235], v[26:29]
	v_mfma_f32_16x16x32_bf16 v[18:21], v[176:179], v[232:235], v[18:21]
	v_mfma_f32_16x16x32_bf16 v[10:13], v[162:165], v[240:243], v[10:13]
	v_mfma_f32_16x16x32_bf16 v[2:5], v[176:179], v[240:243], v[2:5]
	s_setprio 0
	s_barrier
	s_add_i32 s51, 0, 0x18000
	s_add_i32 s52, 0, 0x1c000
	v_add_u32_e32 v142, s51, v168
	v_add_u32_e32 v176, s52, v168
	ds_read_b128 v[130:133], v142
	ds_read_b128 v[134:137], v142 offset:1024
	ds_read_b128 v[138:141], v142 offset:2048
	ds_read_b128 v[142:145], v142 offset:3072
	ds_read_b128 v[158:161], v176
	ds_read_b128 v[162:165], v176 offset:1024
	ds_read_b128 v[172:175], v176 offset:2048
	ds_read_b128 v[176:179], v176 offset:3072
	s_add_u32 s26, s26, 0x40000
	s_addc_u32 s27, s27, 0
	s_mov_b32 m0, s37
	v_lshl_add_u64 v[248:249], s[26:27], 0, v[152:153]
	ds_read_b128 v[180:183], v171 offset:32768
	ds_read_b128 v[184:187], v171 offset:33792
	ds_read_b128 v[202:205], v171 offset:34816
	ds_read_b128 v[206:209], v171 offset:35840
	ds_read_b128 v[210:213], v171 offset:36864
	ds_read_b128 v[232:235], v171 offset:37888
	ds_read_b128 v[236:239], v171 offset:38912
	ds_read_b128 v[240:243], v171 offset:39936
	global_load_lds_dwordx4 v[248:249], off
	v_lshl_add_u64 v[248:249], s[26:27], 0, v[148:149]
	s_mov_b32 m0, s38
	s_nop 0
	global_load_lds_dwordx4 v[248:249], off
	s_waitcnt vmcnt(8)
	s_waitcnt lgkmcnt(0)
	s_barrier
	s_setprio 1
	s_waitcnt lgkmcnt(0)
	v_mfma_f32_16x16x32_bf16 v[126:129], v[130:133], v[180:183], v[126:129]
	v_mfma_f32_16x16x32_bf16 v[118:121], v[138:141], v[180:183], v[118:121]
	v_mfma_f32_16x16x32_bf16 v[110:113], v[130:133], v[202:205], v[110:113]
	v_mfma_f32_16x16x32_bf16 v[102:105], v[138:141], v[202:205], v[102:105]
	v_mfma_f32_16x16x32_bf16 v[94:97], v[130:133], v[210:213], v[94:97]
	v_mfma_f32_16x16x32_bf16 v[86:89], v[138:141], v[210:213], v[86:89]
	v_mfma_f32_16x16x32_bf16 v[78:81], v[130:133], v[236:239], v[78:81]
	v_mfma_f32_16x16x32_bf16 v[70:73], v[138:141], v[236:239], v[70:73]
	v_mfma_f32_16x16x32_bf16 v[126:129], v[134:137], v[184:187], v[126:129]
	v_mfma_f32_16x16x32_bf16 v[118:121], v[142:145], v[184:187], v[118:121]
	v_mfma_f32_16x16x32_bf16 v[110:113], v[134:137], v[206:209], v[110:113]
	v_mfma_f32_16x16x32_bf16 v[102:105], v[142:145], v[206:209], v[102:105]
	v_mfma_f32_16x16x32_bf16 v[94:97], v[134:137], v[232:235], v[94:97]
	v_mfma_f32_16x16x32_bf16 v[86:89], v[142:145], v[232:235], v[86:89]
	v_mfma_f32_16x16x32_bf16 v[78:81], v[134:137], v[240:243], v[78:81]
	v_mfma_f32_16x16x32_bf16 v[70:73], v[142:145], v[240:243], v[70:73]
	s_setprio 0
	s_setprio 1
	v_mfma_f32_16x16x32_bf16 v[122:125], v[158:161], v[180:183], v[122:125]
	v_mfma_f32_16x16x32_bf16 v[114:117], v[172:175], v[180:183], v[114:117]
	v_mfma_f32_16x16x32_bf16 v[106:109], v[158:161], v[202:205], v[106:109]
	v_mfma_f32_16x16x32_bf16 v[98:101], v[172:175], v[202:205], v[98:101]
	v_mfma_f32_16x16x32_bf16 v[90:93], v[158:161], v[210:213], v[90:93]
	v_mfma_f32_16x16x32_bf16 v[82:85], v[172:175], v[210:213], v[82:85]
	v_mfma_f32_16x16x32_bf16 v[74:77], v[158:161], v[236:239], v[74:77]
	v_mfma_f32_16x16x32_bf16 v[66:69], v[172:175], v[236:239], v[66:69]
	v_mfma_f32_16x16x32_bf16 v[122:125], v[162:165], v[184:187], v[122:125]
	v_mfma_f32_16x16x32_bf16 v[114:117], v[176:179], v[184:187], v[114:117]
	v_mfma_f32_16x16x32_bf16 v[106:109], v[162:165], v[206:209], v[106:109]
	v_mfma_f32_16x16x32_bf16 v[98:101], v[176:179], v[206:209], v[98:101]
	v_mfma_f32_16x16x32_bf16 v[90:93], v[162:165], v[232:235], v[90:93]
	v_mfma_f32_16x16x32_bf16 v[82:85], v[176:179], v[232:235], v[82:85]
	v_mfma_f32_16x16x32_bf16 v[74:77], v[162:165], v[240:243], v[74:77]
	v_mfma_f32_16x16x32_bf16 v[66:69], v[176:179], v[240:243], v[66:69]
	s_setprio 0
	s_barrier
; #define PG8_STAGE(bufoff, gbase, voff) do { _Pragma("unroll") for (int _i = 0; _i < 2; ++_i) \
;         __builtin_amdgcn_global_load_lds((const unsigned*)((const char*)(gbase) + (voff)[_i]), (PG8_LAS unsigned*)(lds + (bufoff) + ldsw + _i * 8192), 16, 0, 0); } while (0)
; #define PG8_LDA(dst, b, h) do { _Pragma("unroll") for (int m = 0; m < 4; ++m) _Pragma("unroll") for (int k = 0; k < 2; ++k) dst[m][k] = *(const PG8_LAS bf16x8*)(lds + PG8_SA(b, h) + aoff + m * 2048 + k * 1024); } while (0)
; #define PG8_MMA(ai, bj, At, Bt) do { __builtin_amdgcn_s_setprio(1); _Pragma("unroll") for (int m = 0; m < 4; ++m) _Pragma("unroll") for (int n = 0; n < 2; ++n) _Pragma("unroll") for (int k = 0; k < 2; ++k) \
;         acc[ai][bj][m][n] = __builtin_amdgcn_mfma_f32_16x16x32_bf16(Bt[n][k], At[m][k], acc[ai][bj][m][n], 0, 0, 0); __builtin_amdgcn_s_setprio(0); } while (0)
; #define PG8_WAIT_V(n) asm volatile("s_waitcnt vmcnt(" #n ")" ::: "memory")
; #define PG8_WAIT_L(n) asm volatile("s_waitcnt lgkmcnt(" #n ")" ::: "memory")
; #define PG8_BAR __builtin_amdgcn_s_barrier()
; #define PG8_SCHED __builtin_amdgcn_sched_barrier(0)
; template <class Epi, class Sched, bool ALIGN_EPI = false, bool SP2 = false>
; __device__ __forceinline__ void gemm_phase(PG8_LAS unsigned char* lds, const Gemm g, const Sched& S, const Epi& E) {
;     ...
;         for (int t = 0; t < nt; t += 2) {
;     ...
;             PG8_LDA(At, 1, 1); PG8_STAGE(PG8_SB(1, 0), b3, voffB); PG8_STAGE(PG8_SB(1, 1), b3 + hstepB, voffB); PG8_STAGE(PG8_SA(1, 0), a3, voffA);
;             PG8_WAIT_V(8); PG8_WAIT_L(0); PG8_BAR; PG8_MMA(1, 0, At, B0); PG8_MMA(1, 1, At, B1); PG8_BAR; PG8_SCHED;
	s_add_i32 s26, s51, s30
	v_lshl_add_u64 v[166:167], v[166:167], 0, s[96:97]
	s_mov_b32 m0, s26
	ds_read_b128 v[180:183], v171 offset:49152
	ds_read_b128 v[184:187], v171 offset:50176
	ds_read_b128 v[202:205], v171 offset:51200
	ds_read_b128 v[206:209], v171 offset:52224
	ds_read_b128 v[210:213], v171 offset:53248
	ds_read_b128 v[232:235], v171 offset:54272
	ds_read_b128 v[236:239], v171 offset:55296
	ds_read_b128 v[240:243], v171 offset:56320
	global_load_lds_dwordx4 v[166:167], off
	s_add_i32 m0, s26, 0x2000
	s_add_u32 s24, s24, 0x40080
	v_lshl_add_u64 v[166:167], v[214:215], 0, s[96:97]
	s_addc_u32 s25, s25, 0
	s_add_i32 s26, s52, s30
	global_load_lds_dwordx4 v[166:167], off
	v_lshl_add_u64 v[166:167], s[24:25], 0, v[150:151]
	s_mov_b32 m0, s26
	s_nop 0
	global_load_lds_dwordx4 v[166:167], off
	v_lshl_add_u64 v[166:167], s[24:25], 0, v[146:147]
	s_add_i32 m0, s26, 0x2000
	s_nop 0
	global_load_lds_dwordx4 v[166:167], off
	v_lshl_add_u64 v[166:167], v[244:245], 0, s[96:97]
	s_mov_b32 m0, s39
	s_nop 0
	global_load_lds_dwordx4 v[166:167], off
	v_lshl_add_u64 v[166:167], v[246:247], 0, s[96:97]
	s_mov_b32 m0, s40
	s_nop 0
	global_load_lds_dwordx4 v[166:167], off
	s_waitcnt vmcnt(8)
	s_waitcnt lgkmcnt(0)
	s_barrier
	s_setprio 1
	s_waitcnt lgkmcnt(0)
	v_mfma_f32_16x16x32_bf16 v[62:65], v[130:133], v[180:183], v[62:65]
	v_mfma_f32_16x16x32_bf16 v[54:57], v[138:141], v[180:183], v[54:57]
	v_mfma_f32_16x16x32_bf16 v[46:49], v[130:133], v[202:205], v[46:49]
	v_mfma_f32_16x16x32_bf16 v[38:41], v[138:141], v[202:205], v[38:41]
	v_mfma_f32_16x16x32_bf16 v[30:33], v[130:133], v[210:213], v[30:33]
	v_mfma_f32_16x16x32_bf16 v[22:25], v[138:141], v[210:213], v[22:25]
	v_mfma_f32_16x16x32_bf16 v[14:17], v[130:133], v[236:239], v[14:17]
	v_mfma_f32_16x16x32_bf16 v[6:9], v[138:141], v[236:239], v[6:9]
	v_mfma_f32_16x16x32_bf16 v[62:65], v[134:137], v[184:187], v[62:65]
	v_mfma_f32_16x16x32_bf16 v[54:57], v[142:145], v[184:187], v[54:57]
	v_mfma_f32_16x16x32_bf16 v[46:49], v[134:137], v[206:209], v[46:49]
	v_mfma_f32_16x16x32_bf16 v[38:41], v[142:145], v[206:209], v[38:41]
	v_mfma_f32_16x16x32_bf16 v[30:33], v[134:137], v[232:235], v[30:33]
	v_mfma_f32_16x16x32_bf16 v[22:25], v[142:145], v[232:235], v[22:25]
	v_mfma_f32_16x16x32_bf16 v[14:17], v[134:137], v[240:243], v[14:17]
	v_mfma_f32_16x16x32_bf16 v[6:9], v[142:145], v[240:243], v[6:9]
	s_setprio 0
	s_setprio 1
	v_mfma_f32_16x16x32_bf16 v[58:61], v[158:161], v[180:183], v[58:61]
	v_mfma_f32_16x16x32_bf16 v[50:53], v[172:175], v[180:183], v[50:53]
	v_mfma_f32_16x16x32_bf16 v[42:45], v[158:161], v[202:205], v[42:45]
	v_mfma_f32_16x16x32_bf16 v[34:37], v[172:175], v[202:205], v[34:37]
	v_mfma_f32_16x16x32_bf16 v[26:29], v[158:161], v[210:213], v[26:29]
	v_mfma_f32_16x16x32_bf16 v[18:21], v[172:175], v[210:213], v[18:21]
	v_mfma_f32_16x16x32_bf16 v[10:13], v[158:161], v[236:239], v[10:13]
	v_mfma_f32_16x16x32_bf16 v[2:5], v[172:175], v[236:239], v[2:5]
	v_mfma_f32_16x16x32_bf16 v[58:61], v[162:165], v[184:187], v[58:61]
	v_mfma_f32_16x16x32_bf16 v[50:53], v[176:179], v[184:187], v[50:53]
	v_mfma_f32_16x16x32_bf16 v[42:45], v[162:165], v[206:209], v[42:45]
	v_mfma_f32_16x16x32_bf16 v[34:37], v[176:179], v[206:209], v[34:37]
	v_mfma_f32_16x16x32_bf16 v[26:29], v[162:165], v[232:235], v[26:29]
	v_mfma_f32_16x16x32_bf16 v[18:21], v[176:179], v[232:235], v[18:21]
	v_mfma_f32_16x16x32_bf16 v[10:13], v[162:165], v[240:243], v[10:13]
	v_mfma_f32_16x16x32_bf16 v[2:5], v[176:179], v[240:243], v[2:5]
	s_setprio 0
	s_add_i32 s50, s50, 2
	s_add_u32 s22, s22, 0x100
	s_addc_u32 s23, s23, 0
	s_add_u32 s48, s48, 0x100
	s_addc_u32 s49, s49, 0
	s_cmp_gt_u32 s50, 13
	s_barrier
	s_cbranch_scc0 .LBB0_1190
	s_and_b64 vcc, exec, s[18:19]
	s_cbranch_vccz .LBB0_1193
	s_barrier

; #define PG8_STAGE(bufoff, gbase, voff) do { _Pragma("unroll") for (int _i = 0; _i < 2; ++_i) \
;         __builtin_amdgcn_global_load_lds((const unsigned*)((const char*)(gbase) + (voff)[_i]), (PG8_LAS unsigned*)(lds + (bufoff) + ldsw + _i * 8192), 16, 0, 0); } while (0)
; #define PG8_LDA(dst, b, h) do { _Pragma("unroll") for (int m = 0; m < 4; ++m) _Pragma("unroll") for (int k = 0; k < 2; ++k) dst[m][k] = *(const PG8_LAS bf16x8*)(lds + PG8_SA(b, h) + aoff + m * 2048 + k * 1024); } while (0)
; #define PG8_LDB(dst, b, h) do { _Pragma("unroll") for (int n = 0; n < 2; ++n) _Pragma("unroll") for (int k = 0; k < 2; ++k) dst[n][k] = *(const PG8_LAS bf16x8*)(lds + PG8_SB(b, h) + boff + n * 2048 + k * 1024); } while (0)
; #define PG8_MMA(ai, bj, At, Bt) do { __builtin_amdgcn_s_setprio(1); _Pragma("unroll") for (int m = 0; m < 4; ++m) _Pragma("unroll") for (int n = 0; n < 2; ++n) _Pragma("unroll") for (int k = 0; k < 2; ++k) \
;         acc[ai][bj][m][n] = __builtin_amdgcn_mfma_f32_16x16x32_bf16(Bt[n][k], At[m][k], acc[ai][bj][m][n], 0, 0, 0); __builtin_amdgcn_s_setprio(0); } while (0)
; #define PG8_WAIT_V(n) asm volatile("s_waitcnt vmcnt(" #n ")" ::: "memory")
; #define PG8_WAIT_L(n) asm volatile("s_waitcnt lgkmcnt(" #n ")" ::: "memory")
; template <class Epi, class Sched, bool ALIGN_EPI = false, bool SP2 = false>
; __device__ __forceinline__ void gemm_phase(PG8_LAS unsigned char* lds, const Gemm g, const Sched& S, const Epi& E) {
;     ...
;             const bool last = (t == nt - 2);
;             const char* a1 = cA + (size_t)(t + 1) * kstep;
;             const char* a2 = last ? nA : cA + (size_t)(t + 2) * kstep; const char* b2 = last ? nB : cB + (size_t)(t + 2) * kstep;
;             const char* a3 = a2 + kstep; const char* b3 = b2 + kstep;
;             if (last && has_next) S.a_ready(nxt);
;             if constexpr (SP2) {
;             PG8_LDB(B0, 0, 0); PG8_LDB(B1, 0, 1); PG8_SCHED; PG8_LDA(At, 0, 0); PG8_STAGE(PG8_SA(1, 1), a1 + hstepA, voffA);
;             PG8_WAIT_V(8); PG8_WAIT_L(0); PG8_BAR; PG8_MMA(0, 0, At, B0); PG8_MMA(0, 1, At, B1); PG8_BAR; PG8_SCHED;
;             PG8_LDA(At, 0, 1); PG8_STAGE(PG8_SB(0, 0), b2, voffB); PG8_STAGE(PG8_SB(0, 1), b2 + hstepB, voffB); PG8_STAGE(PG8_SA(0, 0), a2, voffA);
;             PG8_WAIT_V(8); PG8_WAIT_L(0); PG8_BAR; PG8_MMA(1, 0, At, B0); PG8_MMA(1, 1, At, B1); PG8_BAR; PG8_SCHED;
.LBB0_1270:
	s_add_u32 s28, s26, 0xfffc0080
	s_addc_u32 s29, s27, -1
	s_add_i32 s52, 0, 0x10000
	s_cmp_eq_u32 s51, 12
	s_cselect_b32 s31, s17, s29
	s_cselect_b32 s30, s23, s28
	s_cselect_b32 s29, s15, s50
	s_cselect_b32 s28, s25, s49
	s_add_i32 s54, 0, 0x14000
	v_add_u32_e32 v142, s52, v186
	v_add_u32_e32 v172, s54, v186
	ds_read_b128 v[130:133], v142
	ds_read_b128 v[134:137], v142 offset:1024
	ds_read_b128 v[138:141], v142 offset:2048
	ds_read_b128 v[142:145], v142 offset:3072
	ds_read_b128 v[146:149], v172
	ds_read_b128 v[150:153], v172 offset:1024
	ds_read_b128 v[168:171], v172 offset:2048
	ds_read_b128 v[172:175], v172 offset:3072
	v_lshl_add_u64 v[184:185], s[26:27], 0, v[164:165]
	s_add_i32 m0, s39, 0xc000
	ds_read_b128 v[176:179], v200
	ds_read_b128 v[180:183], v200 offset:1024
	ds_read_b128 v[202:205], v200 offset:2048
	ds_read_b128 v[206:209], v200 offset:3072
	ds_read_b128 v[210:213], v200 offset:4096
	ds_read_b128 v[232:235], v200 offset:5120
	ds_read_b128 v[236:239], v200 offset:6144
	ds_read_b128 v[240:243], v200 offset:7168
	global_load_lds_dwordx4 v[184:185], off
	v_lshl_add_u64 v[184:185], s[26:27], 0, v[166:167]
	s_add_i32 m0, s39, 0xe000
	s_nop 0
	global_load_lds_dwordx4 v[184:185], off
	s_waitcnt vmcnt(8)
	s_waitcnt lgkmcnt(0)
	s_barrier
	s_setprio 1
	s_waitcnt lgkmcnt(0)
	v_mfma_f32_16x16x32_bf16 v[126:129], v[130:133], v[176:179], v[126:129]
	v_mfma_f32_16x16x32_bf16 v[122:125], v[138:141], v[176:179], v[122:125]
	v_mfma_f32_16x16x32_bf16 v[110:113], v[130:133], v[202:205], v[110:113]
	v_mfma_f32_16x16x32_bf16 v[106:109], v[138:141], v[202:205], v[106:109]
	v_mfma_f32_16x16x32_bf16 v[94:97], v[130:133], v[210:213], v[94:97]
	v_mfma_f32_16x16x32_bf16 v[90:93], v[138:141], v[210:213], v[90:93]
	v_mfma_f32_16x16x32_bf16 v[78:81], v[130:133], v[236:239], v[78:81]
	v_mfma_f32_16x16x32_bf16 v[74:77], v[138:141], v[236:239], v[74:77]
	v_mfma_f32_16x16x32_bf16 v[126:129], v[134:137], v[180:183], v[126:129]
	v_mfma_f32_16x16x32_bf16 v[122:125], v[142:145], v[180:183], v[122:125]
	v_mfma_f32_16x16x32_bf16 v[110:113], v[134:137], v[206:209], v[110:113]
	v_mfma_f32_16x16x32_bf16 v[106:109], v[142:145], v[206:209], v[106:109]
	v_mfma_f32_16x16x32_bf16 v[94:97], v[134:137], v[232:235], v[94:97]
	v_mfma_f32_16x16x32_bf16 v[90:93], v[142:145], v[232:235], v[90:93]
	v_mfma_f32_16x16x32_bf16 v[78:81], v[134:137], v[240:243], v[78:81]
	v_mfma_f32_16x16x32_bf16 v[74:77], v[142:145], v[240:243], v[74:77]
	s_setprio 0
	s_setprio 1
	v_mfma_f32_16x16x32_bf16 v[118:121], v[146:149], v[176:179], v[118:121]
	v_mfma_f32_16x16x32_bf16 v[114:117], v[168:171], v[176:179], v[114:117]
	v_mfma_f32_16x16x32_bf16 v[102:105], v[146:149], v[202:205], v[102:105]
	v_mfma_f32_16x16x32_bf16 v[98:101], v[168:171], v[202:205], v[98:101]
	v_mfma_f32_16x16x32_bf16 v[86:89], v[146:149], v[210:213], v[86:89]
	v_mfma_f32_16x16x32_bf16 v[82:85], v[168:171], v[210:213], v[82:85]
	v_mfma_f32_16x16x32_bf16 v[70:73], v[146:149], v[236:239], v[70:73]
	v_mfma_f32_16x16x32_bf16 v[66:69], v[168:171], v[236:239], v[66:69]
	v_mfma_f32_16x16x32_bf16 v[118:121], v[150:153], v[180:183], v[118:121]
	v_mfma_f32_16x16x32_bf16 v[114:117], v[172:175], v[180:183], v[114:117]
	v_mfma_f32_16x16x32_bf16 v[102:105], v[150:153], v[206:209], v[102:105]
	v_mfma_f32_16x16x32_bf16 v[98:101], v[172:175], v[206:209], v[98:101]
	v_mfma_f32_16x16x32_bf16 v[86:89], v[150:153], v[232:235], v[86:89]
	v_mfma_f32_16x16x32_bf16 v[82:85], v[172:175], v[232:235], v[82:85]
	v_mfma_f32_16x16x32_bf16 v[70:73], v[150:153], v[240:243], v[70:73]
	v_mfma_f32_16x16x32_bf16 v[66:69], v[172:175], v[240:243], v[66:69]
	s_setprio 0
	s_barrier
	s_add_i32 s52, s52, s38
	v_lshl_add_u64 v[184:185], s[28:29], 0, v[156:157]
	s_mov_b32 m0, s52
	ds_read_b128 v[176:179], v200 offset:16384
	ds_read_b128 v[180:183], v200 offset:17408
	ds_read_b128 v[202:205], v200 offset:18432
	ds_read_b128 v[206:209], v200 offset:19456
	ds_read_b128 v[210:213], v200 offset:20480
	ds_read_b128 v[232:235], v200 offset:21504
	ds_read_b128 v[236:239], v200 offset:22528
	ds_read_b128 v[240:243], v200 offset:23552
	global_load_lds_dwordx4 v[184:185], off
	s_add_i32 m0, s52, 0x2000
	s_add_u32 s52, s28, 0x40000
	v_lshl_add_u64 v[214:215], s[28:29], 0, v[160:161]
	s_addc_u32 s53, s29, 0
	s_add_i32 s54, s54, s38
	global_load_lds_dwordx4 v[214:215], off
	v_lshl_add_u64 v[244:245], s[52:53], 0, v[156:157]
	s_mov_b32 m0, s54
	v_lshl_add_u64 v[246:247], s[30:31], 0, v[158:159]
	global_load_lds_dwordx4 v[244:245], off
	v_lshl_add_u64 v[244:245], s[52:53], 0, v[160:161]
	s_add_i32 m0, s54, 0x2000
	s_nop 0
	global_load_lds_dwordx4 v[244:245], off
	v_lshl_add_u64 v[244:245], s[30:31], 0, v[154:155]
	s_mov_b32 m0, s39
	s_nop 0
	global_load_lds_dwordx4 v[244:245], off
	s_mov_b32 m0, s40
	s_nop 0
	global_load_lds_dwordx4 v[246:247], off
	s_waitcnt vmcnt(8)
	s_waitcnt lgkmcnt(0)
	s_barrier
; #define PG8_STAGE(bufoff, gbase, voff) do { _Pragma("unroll") for (int _i = 0; _i < 2; ++_i) \
;         __builtin_amdgcn_global_load_lds((const unsigned*)((const char*)(gbase) + (voff)[_i]), (PG8_LAS unsigned*)(lds + (bufoff) + ldsw + _i * 8192), 16, 0, 0); } while (0)
; #define PG8_LDA(dst, b, h) do { _Pragma("unroll") for (int m = 0; m < 4; ++m) _Pragma("unroll") for (int k = 0; k < 2; ++k) dst[m][k] = *(const PG8_LAS bf16x8*)(lds + PG8_SA(b, h) + aoff + m * 2048 + k * 1024); } while (0)
; #define PG8_LDB(dst, b, h) do { _Pragma("unroll") for (int n = 0; n < 2; ++n) _Pragma("unroll") for (int k = 0; k < 2; ++k) dst[n][k] = *(const PG8_LAS bf16x8*)(lds + PG8_SB(b, h) + boff + n * 2048 + k * 1024); } while (0)
; #define PG8_MMA(ai, bj, At, Bt) do { __builtin_amdgcn_s_setprio(1); _Pragma("unroll") for (int m = 0; m < 4; ++m) _Pragma("unroll") for (int n = 0; n < 2; ++n) _Pragma("unroll") for (int k = 0; k < 2; ++k) \
;         acc[ai][bj][m][n] = __builtin_amdgcn_mfma_f32_16x16x32_bf16(Bt[n][k], At[m][k], acc[ai][bj][m][n], 0, 0, 0); __builtin_amdgcn_s_setprio(0); } while (0)
; #define PG8_WAIT_V(n) asm volatile("s_waitcnt vmcnt(" #n ")" ::: "memory")
; #define PG8_WAIT_L(n) asm volatile("s_waitcnt lgkmcnt(" #n ")" ::: "memory")
; #define PG8_BAR __builtin_amdgcn_s_barrier()
; #define PG8_SCHED __builtin_amdgcn_sched_barrier(0)
; template <class Epi, class Sched, bool ALIGN_EPI = false, bool SP2 = false>
; __device__ __forceinline__ void gemm_phase(PG8_LAS unsigned char* lds, const Gemm g, const Sched& S, const Epi& E) {
;     ...
;             PG8_WAIT_V(8); PG8_WAIT_L(0); PG8_BAR; PG8_MMA(1, 0, At, B0); PG8_MMA(1, 1, At, B1); PG8_BAR; PG8_SCHED;
;             PG8_LDB(B0, 1, 0); PG8_LDB(B1, 1, 1); PG8_SCHED; PG8_LDA(At, 1, 0); PG8_STAGE(PG8_SA(0, 1), a2 + hstepA, voffA);
;             PG8_WAIT_V(8); PG8_WAIT_L(0); PG8_BAR; PG8_MMA(0, 0, At, B0); PG8_MMA(0, 1, At, B1); PG8_BAR; PG8_SCHED;
;             PG8_LDA(At, 1, 1); PG8_STAGE(PG8_SB(1, 0), b3, voffB); PG8_STAGE(PG8_SB(1, 1), b3 + hstepB, voffB); PG8_STAGE(PG8_SA(1, 0), a3, voffA);
	s_setprio 1
	s_waitcnt lgkmcnt(0)
	v_mfma_f32_16x16x32_bf16 v[62:65], v[130:133], v[176:179], v[62:65]
	v_mfma_f32_16x16x32_bf16 v[58:61], v[138:141], v[176:179], v[58:61]
	v_mfma_f32_16x16x32_bf16 v[46:49], v[130:133], v[202:205], v[46:49]
	v_mfma_f32_16x16x32_bf16 v[42:45], v[138:141], v[202:205], v[42:45]
	v_mfma_f32_16x16x32_bf16 v[30:33], v[130:133], v[210:213], v[30:33]
	v_mfma_f32_16x16x32_bf16 v[26:29], v[138:141], v[210:213], v[26:29]
	v_mfma_f32_16x16x32_bf16 v[14:17], v[130:133], v[236:239], v[14:17]
	v_mfma_f32_16x16x32_bf16 v[10:13], v[138:141], v[236:239], v[10:13]
	v_mfma_f32_16x16x32_bf16 v[62:65], v[134:137], v[180:183], v[62:65]
	v_mfma_f32_16x16x32_bf16 v[58:61], v[142:145], v[180:183], v[58:61]
	v_mfma_f32_16x16x32_bf16 v[46:49], v[134:137], v[206:209], v[46:49]
	v_mfma_f32_16x16x32_bf16 v[42:45], v[142:145], v[206:209], v[42:45]
	v_mfma_f32_16x16x32_bf16 v[30:33], v[134:137], v[232:235], v[30:33]
	v_mfma_f32_16x16x32_bf16 v[26:29], v[142:145], v[232:235], v[26:29]
	v_mfma_f32_16x16x32_bf16 v[14:17], v[134:137], v[240:243], v[14:17]
	v_mfma_f32_16x16x32_bf16 v[10:13], v[142:145], v[240:243], v[10:13]
	s_setprio 0
	s_setprio 1
	v_mfma_f32_16x16x32_bf16 v[54:57], v[146:149], v[176:179], v[54:57]
	v_mfma_f32_16x16x32_bf16 v[50:53], v[168:171], v[176:179], v[50:53]
	v_mfma_f32_16x16x32_bf16 v[38:41], v[146:149], v[202:205], v[38:41]
	v_mfma_f32_16x16x32_bf16 v[34:37], v[168:171], v[202:205], v[34:37]
	v_mfma_f32_16x16x32_bf16 v[22:25], v[146:149], v[210:213], v[22:25]
	v_mfma_f32_16x16x32_bf16 v[18:21], v[168:171], v[210:213], v[18:21]
	v_mfma_f32_16x16x32_bf16 v[6:9], v[146:149], v[236:239], v[6:9]
	v_mfma_f32_16x16x32_bf16 v[2:5], v[168:171], v[236:239], v[2:5]
	v_mfma_f32_16x16x32_bf16 v[54:57], v[150:153], v[180:183], v[54:57]
	v_mfma_f32_16x16x32_bf16 v[50:53], v[172:175], v[180:183], v[50:53]
	v_mfma_f32_16x16x32_bf16 v[38:41], v[150:153], v[206:209], v[38:41]
	v_mfma_f32_16x16x32_bf16 v[34:37], v[172:175], v[206:209], v[34:37]
	v_mfma_f32_16x16x32_bf16 v[22:25], v[150:153], v[232:235], v[22:25]
	v_mfma_f32_16x16x32_bf16 v[18:21], v[172:175], v[232:235], v[18:21]
	v_mfma_f32_16x16x32_bf16 v[6:9], v[150:153], v[240:243], v[6:9]
	v_mfma_f32_16x16x32_bf16 v[2:5], v[172:175], v[240:243], v[2:5]
	s_setprio 0
	s_barrier
	s_add_i32 s52, 0, 0x18000
	s_add_i32 s53, 0, 0x1c000
	v_add_u32_e32 v142, s52, v186
	v_add_u32_e32 v172, s53, v186
	ds_read_b128 v[130:133], v142
	ds_read_b128 v[134:137], v142 offset:1024
	ds_read_b128 v[138:141], v142 offset:2048
	ds_read_b128 v[142:145], v142 offset:3072
	ds_read_b128 v[146:149], v172
	ds_read_b128 v[150:153], v172 offset:1024
	ds_read_b128 v[168:171], v172 offset:2048
	ds_read_b128 v[172:175], v172 offset:3072
	s_add_u32 s30, s30, 0x40000
	s_addc_u32 s31, s31, 0
	s_mov_b32 m0, s41
	v_lshl_add_u64 v[248:249], s[30:31], 0, v[154:155]
	ds_read_b128 v[176:179], v200 offset:32768
	ds_read_b128 v[180:183], v200 offset:33792
	ds_read_b128 v[202:205], v200 offset:34816
	ds_read_b128 v[206:209], v200 offset:35840
	ds_read_b128 v[210:213], v200 offset:36864
	ds_read_b128 v[232:235], v200 offset:37888
	ds_read_b128 v[236:239], v200 offset:38912
	ds_read_b128 v[240:243], v200 offset:39936
	global_load_lds_dwordx4 v[248:249], off
	v_lshl_add_u64 v[248:249], s[30:31], 0, v[158:159]
	s_mov_b32 m0, s42
	s_nop 0
	global_load_lds_dwordx4 v[248:249], off
	s_waitcnt vmcnt(8)
	s_waitcnt lgkmcnt(0)
	s_barrier
	s_setprio 1
	s_waitcnt lgkmcnt(0)
	v_mfma_f32_16x16x32_bf16 v[126:129], v[130:133], v[176:179], v[126:129]
	v_mfma_f32_16x16x32_bf16 v[122:125], v[138:141], v[176:179], v[122:125]
	v_mfma_f32_16x16x32_bf16 v[110:113], v[130:133], v[202:205], v[110:113]
	v_mfma_f32_16x16x32_bf16 v[106:109], v[138:141], v[202:205], v[106:109]
	v_mfma_f32_16x16x32_bf16 v[94:97], v[130:133], v[210:213], v[94:97]
	v_mfma_f32_16x16x32_bf16 v[90:93], v[138:141], v[210:213], v[90:93]
	v_mfma_f32_16x16x32_bf16 v[78:81], v[130:133], v[236:239], v[78:81]
	v_mfma_f32_16x16x32_bf16 v[74:77], v[138:141], v[236:239], v[74:77]
	v_mfma_f32_16x16x32_bf16 v[126:129], v[134:137], v[180:183], v[126:129]
	v_mfma_f32_16x16x32_bf16 v[122:125], v[142:145], v[180:183], v[122:125]
	v_mfma_f32_16x16x32_bf16 v[110:113], v[134:137], v[206:209], v[110:113]
	v_mfma_f32_16x16x32_bf16 v[106:109], v[142:145], v[206:209], v[106:109]
	v_mfma_f32_16x16x32_bf16 v[94:97], v[134:137], v[232:235], v[94:97]
	v_mfma_f32_16x16x32_bf16 v[90:93], v[142:145], v[232:235], v[90:93]
	v_mfma_f32_16x16x32_bf16 v[78:81], v[134:137], v[240:243], v[78:81]
	v_mfma_f32_16x16x32_bf16 v[74:77], v[142:145], v[240:243], v[74:77]
	s_setprio 0
	s_setprio 1
	v_mfma_f32_16x16x32_bf16 v[118:121], v[146:149], v[176:179], v[118:121]
	v_mfma_f32_16x16x32_bf16 v[114:117], v[168:171], v[176:179], v[114:117]
	v_mfma_f32_16x16x32_bf16 v[102:105], v[146:149], v[202:205], v[102:105]
	v_mfma_f32_16x16x32_bf16 v[98:101], v[168:171], v[202:205], v[98:101]
	v_mfma_f32_16x16x32_bf16 v[86:89], v[146:149], v[210:213], v[86:89]
	v_mfma_f32_16x16x32_bf16 v[82:85], v[168:171], v[210:213], v[82:85]
	v_mfma_f32_16x16x32_bf16 v[70:73], v[146:149], v[236:239], v[70:73]
	v_mfma_f32_16x16x32_bf16 v[66:69], v[168:171], v[236:239], v[66:69]
	v_mfma_f32_16x16x32_bf16 v[118:121], v[150:153], v[180:183], v[118:121]
	v_mfma_f32_16x16x32_bf16 v[114:117], v[172:175], v[180:183], v[114:117]
	v_mfma_f32_16x16x32_bf16 v[102:105], v[150:153], v[206:209], v[102:105]
	v_mfma_f32_16x16x32_bf16 v[98:101], v[172:175], v[206:209], v[98:101]
	v_mfma_f32_16x16x32_bf16 v[86:89], v[150:153], v[232:235], v[86:89]
	v_mfma_f32_16x16x32_bf16 v[82:85], v[172:175], v[232:235], v[82:85]
	v_mfma_f32_16x16x32_bf16 v[70:73], v[150:153], v[240:243], v[70:73]
	v_mfma_f32_16x16x32_bf16 v[66:69], v[172:175], v[240:243], v[66:69]
	s_setprio 0
	s_barrier
; #define PG8_STAGE(bufoff, gbase, voff) do { _Pragma("unroll") for (int _i = 0; _i < 2; ++_i) \
;         __builtin_amdgcn_global_load_lds((const unsigned*)((const char*)(gbase) + (voff)[_i]), (PG8_LAS unsigned*)(lds + (bufoff) + ldsw + _i * 8192), 16, 0, 0); } while (0)
; #define PG8_LDA(dst, b, h) do { _Pragma("unroll") for (int m = 0; m < 4; ++m) _Pragma("unroll") for (int k = 0; k < 2; ++k) dst[m][k] = *(const PG8_LAS bf16x8*)(lds + PG8_SA(b, h) + aoff + m * 2048 + k * 1024); } while (0)
; #define PG8_MMA(ai, bj, At, Bt) do { __builtin_amdgcn_s_setprio(1); _Pragma("unroll") for (int m = 0; m < 4; ++m) _Pragma("unroll") for (int n = 0; n < 2; ++n) _Pragma("unroll") for (int k = 0; k < 2; ++k) \
;         acc[ai][bj][m][n] = __builtin_amdgcn_mfma_f32_16x16x32_bf16(Bt[n][k], At[m][k], acc[ai][bj][m][n], 0, 0, 0); __builtin_amdgcn_s_setprio(0); } while (0)
; #define PG8_WAIT_V(n) asm volatile("s_waitcnt vmcnt(" #n ")" ::: "memory")
; #define PG8_WAIT_L(n) asm volatile("s_waitcnt lgkmcnt(" #n ")" ::: "memory")
; #define PG8_BAR __builtin_amdgcn_s_barrier()
; #define PG8_SCHED __builtin_amdgcn_sched_barrier(0)
; template <class Epi, class Sched, bool ALIGN_EPI = false, bool SP2 = false>
; __device__ __forceinline__ void gemm_phase(PG8_LAS unsigned char* lds, const Gemm g, const Sched& S, const Epi& E) {
;     ...
;         for (int t = 0; t < nt; t += 2) {
;     ...
;             PG8_LDA(At, 1, 1); PG8_STAGE(PG8_SB(1, 0), b3, voffB); PG8_STAGE(PG8_SB(1, 1), b3 + hstepB, voffB); PG8_STAGE(PG8_SA(1, 0), a3, voffA);
;             PG8_WAIT_V(8); PG8_WAIT_L(0); PG8_BAR; PG8_MMA(1, 0, At, B0); PG8_MMA(1, 1, At, B1); PG8_BAR; PG8_SCHED;
	s_add_i32 s30, s52, s38
	v_lshl_add_u64 v[184:185], v[184:185], 0, s[96:97]
	s_mov_b32 m0, s30
	ds_read_b128 v[176:179], v200 offset:49152
	ds_read_b128 v[180:183], v200 offset:50176
	ds_read_b128 v[202:205], v200 offset:51200
	ds_read_b128 v[206:209], v200 offset:52224
	ds_read_b128 v[210:213], v200 offset:53248
	ds_read_b128 v[232:235], v200 offset:54272
	ds_read_b128 v[236:239], v200 offset:55296
	ds_read_b128 v[240:243], v200 offset:56320
	global_load_lds_dwordx4 v[184:185], off
	s_add_i32 m0, s30, 0x2000
	s_add_u32 s28, s28, 0x40080
	v_lshl_add_u64 v[184:185], v[214:215], 0, s[96:97]
	s_addc_u32 s29, s29, 0
	s_add_i32 s30, s53, s38
	global_load_lds_dwordx4 v[184:185], off
	v_lshl_add_u64 v[184:185], s[28:29], 0, v[156:157]
	s_mov_b32 m0, s30
	s_nop 0
	global_load_lds_dwordx4 v[184:185], off
	v_lshl_add_u64 v[184:185], s[28:29], 0, v[160:161]
	s_add_i32 m0, s30, 0x2000
	s_nop 0
	global_load_lds_dwordx4 v[184:185], off
	v_lshl_add_u64 v[184:185], v[244:245], 0, s[96:97]
	s_mov_b32 m0, s44
	s_nop 0
	global_load_lds_dwordx4 v[184:185], off
	v_lshl_add_u64 v[184:185], v[246:247], 0, s[96:97]
	s_mov_b32 m0, s45
	s_nop 0
	global_load_lds_dwordx4 v[184:185], off
	s_waitcnt vmcnt(8)
	s_waitcnt lgkmcnt(0)
	s_barrier
	s_setprio 1
	s_waitcnt lgkmcnt(0)
	v_mfma_f32_16x16x32_bf16 v[62:65], v[130:133], v[176:179], v[62:65]
	v_mfma_f32_16x16x32_bf16 v[58:61], v[138:141], v[176:179], v[58:61]
	v_mfma_f32_16x16x32_bf16 v[46:49], v[130:133], v[202:205], v[46:49]
	v_mfma_f32_16x16x32_bf16 v[42:45], v[138:141], v[202:205], v[42:45]
	v_mfma_f32_16x16x32_bf16 v[30:33], v[130:133], v[210:213], v[30:33]
	v_mfma_f32_16x16x32_bf16 v[26:29], v[138:141], v[210:213], v[26:29]
	v_mfma_f32_16x16x32_bf16 v[14:17], v[130:133], v[236:239], v[14:17]
	v_mfma_f32_16x16x32_bf16 v[10:13], v[138:141], v[236:239], v[10:13]
	v_mfma_f32_16x16x32_bf16 v[62:65], v[134:137], v[180:183], v[62:65]
	v_mfma_f32_16x16x32_bf16 v[58:61], v[142:145], v[180:183], v[58:61]
	v_mfma_f32_16x16x32_bf16 v[46:49], v[134:137], v[206:209], v[46:49]
	v_mfma_f32_16x16x32_bf16 v[42:45], v[142:145], v[206:209], v[42:45]
	v_mfma_f32_16x16x32_bf16 v[30:33], v[134:137], v[232:235], v[30:33]
	v_mfma_f32_16x16x32_bf16 v[26:29], v[142:145], v[232:235], v[26:29]
	v_mfma_f32_16x16x32_bf16 v[14:17], v[134:137], v[240:243], v[14:17]
	v_mfma_f32_16x16x32_bf16 v[10:13], v[142:145], v[240:243], v[10:13]
	s_setprio 0
	s_setprio 1
	v_mfma_f32_16x16x32_bf16 v[54:57], v[146:149], v[176:179], v[54:57]
	v_mfma_f32_16x16x32_bf16 v[50:53], v[168:171], v[176:179], v[50:53]
	v_mfma_f32_16x16x32_bf16 v[38:41], v[146:149], v[202:205], v[38:41]
	v_mfma_f32_16x16x32_bf16 v[34:37], v[168:171], v[202:205], v[34:37]
	v_mfma_f32_16x16x32_bf16 v[22:25], v[146:149], v[210:213], v[22:25]
	v_mfma_f32_16x16x32_bf16 v[18:21], v[168:171], v[210:213], v[18:21]
	v_mfma_f32_16x16x32_bf16 v[6:9], v[146:149], v[236:239], v[6:9]
	v_mfma_f32_16x16x32_bf16 v[2:5], v[168:171], v[236:239], v[2:5]
	v_mfma_f32_16x16x32_bf16 v[54:57], v[150:153], v[180:183], v[54:57]
	v_mfma_f32_16x16x32_bf16 v[50:53], v[172:175], v[180:183], v[50:53]
	v_mfma_f32_16x16x32_bf16 v[38:41], v[150:153], v[206:209], v[38:41]
	v_mfma_f32_16x16x32_bf16 v[34:37], v[172:175], v[206:209], v[34:37]
	v_mfma_f32_16x16x32_bf16 v[22:25], v[150:153], v[232:235], v[22:25]
	v_mfma_f32_16x16x32_bf16 v[18:21], v[172:175], v[232:235], v[18:21]
	v_mfma_f32_16x16x32_bf16 v[6:9], v[150:153], v[240:243], v[6:9]
	v_mfma_f32_16x16x32_bf16 v[2:5], v[172:175], v[240:243], v[2:5]
	s_setprio 0
	s_add_i32 s51, s51, 2
	s_add_u32 s26, s26, 0x100
	s_addc_u32 s27, s27, 0
	s_add_u32 s49, s49, 0x100
	s_addc_u32 s50, s50, 0
	s_cmp_gt_u32 s51, 13
	s_barrier
	s_cbranch_scc0 .LBB0_1270
	s_and_b64 vcc, exec, s[12:13]
	s_cbranch_vccz .LBB0_1273
	s_barrier

; #define PG8_STAGE(bufoff, gbase, voff) do { _Pragma("unroll") for (int _i = 0; _i < 2; ++_i) \
;         __builtin_amdgcn_global_load_lds((const unsigned*)((const char*)(gbase) + (voff)[_i]), (PG8_LAS unsigned*)(lds + (bufoff) + ldsw + _i * 8192), 16, 0, 0); } while (0)
; #define PG8_LDA(dst, b, h) do { _Pragma("unroll") for (int m = 0; m < 4; ++m) _Pragma("unroll") for (int k = 0; k < 2; ++k) dst[m][k] = *(const PG8_LAS bf16x8*)(lds + PG8_SA(b, h) + aoff + m * 2048 + k * 1024); } while (0)
; #define PG8_LDB(dst, b, h) do { _Pragma("unroll") for (int n = 0; n < 2; ++n) _Pragma("unroll") for (int k = 0; k < 2; ++k) dst[n][k] = *(const PG8_LAS bf16x8*)(lds + PG8_SB(b, h) + boff + n * 2048 + k * 1024); } while (0)
; #define PG8_MMA(ai, bj, At, Bt) do { __builtin_amdgcn_s_setprio(1); _Pragma("unroll") for (int m = 0; m < 4; ++m) _Pragma("unroll") for (int n = 0; n < 2; ++n) _Pragma("unroll") for (int k = 0; k < 2; ++k) \
;         acc[ai][bj][m][n] = __builtin_amdgcn_mfma_f32_16x16x32_bf16(Bt[n][k], At[m][k], acc[ai][bj][m][n], 0, 0, 0); __builtin_amdgcn_s_setprio(0); } while (0)
; #define PG8_WAIT_V(n) asm volatile("s_waitcnt vmcnt(" #n ")" ::: "memory")
; #define PG8_WAIT_L(n) asm volatile("s_waitcnt lgkmcnt(" #n ")" ::: "memory")
; template <class Epi, class Sched, bool ALIGN_EPI = false, bool SP2 = false>
; __device__ __forceinline__ void gemm_phase(PG8_LAS unsigned char* lds, const Gemm g, const Sched& S, const Epi& E) {
;     ...
;             const bool last = (t == nt - 2);
;             const char* a1 = cA + (size_t)(t + 1) * kstep;
;             const char* a2 = last ? nA : cA + (size_t)(t + 2) * kstep; const char* b2 = last ? nB : cB + (size_t)(t + 2) * kstep;
;             const char* a3 = a2 + kstep; const char* b3 = b2 + kstep;
;             if (last && has_next) S.a_ready(nxt);
;             if constexpr (SP2) {
;             PG8_LDB(B0, 0, 0); PG8_LDB(B1, 0, 1); PG8_SCHED; PG8_LDA(At, 0, 0); PG8_STAGE(PG8_SA(1, 1), a1 + hstepA, voffA);
;             PG8_WAIT_V(8); PG8_WAIT_L(0); PG8_BAR; PG8_MMA(0, 0, At, B0); PG8_MMA(0, 1, At, B1); PG8_BAR; PG8_SCHED;
;             PG8_LDA(At, 0, 1); PG8_STAGE(PG8_SB(0, 0), b2, voffB); PG8_STAGE(PG8_SB(0, 1), b2 + hstepB, voffB); PG8_STAGE(PG8_SA(0, 0), a2, voffA);
;             PG8_WAIT_V(8); PG8_WAIT_L(0); PG8_BAR; PG8_MMA(1, 0, At, B0); PG8_MMA(1, 1, At, B1); PG8_BAR; PG8_SCHED;
.LBB0_1354:
	s_add_u32 s24, s22, 0xfffc0080
	s_addc_u32 s25, s23, -1
	s_add_i32 s49, 0, 0x10000
	s_cmp_eq_u32 s48, 12
	s_cselect_b32 s27, s15, s25
	s_cselect_b32 s26, s21, s24
	v_add_u32_e32 v142, s49, v145
	s_cselect_b32 s25, s13, s47
	s_cselect_b32 s24, s45, s46
	s_add_i32 s52, 0, 0x14000
	ds_read_b128 v[150:153], v142
	ds_read_b128 v[154:157], v142 offset:1024
	ds_read_b128 v[158:161], v142 offset:2048
	ds_read_b128 v[162:165], v142 offset:3072
	v_add_u32_e32 v142, s52, v145
	ds_read_b128 v[166:169], v142
	ds_read_b128 v[170:173], v142 offset:1024
	ds_read_b128 v[174:177], v142 offset:2048
	ds_read_b128 v[178:181], v142 offset:3072
	v_lshl_add_u64 v[142:143], s[22:23], 0, v[138:139]
	s_add_i32 m0, s36, 0xc000
	ds_read_b128 v[182:185], v148
	ds_read_b128 v[202:205], v148 offset:1024
	ds_read_b128 v[206:209], v148 offset:2048
	ds_read_b128 v[210:213], v148 offset:3072
	ds_read_b128 v[232:235], v148 offset:4096
	ds_read_b128 v[236:239], v148 offset:5120
	ds_read_b128 v[240:243], v148 offset:6144
	ds_read_b128 v[244:247], v148 offset:7168
	global_load_lds_dwordx4 v[142:143], off
	v_lshl_add_u64 v[142:143], s[22:23], 0, v[140:141]
	s_add_i32 m0, s36, 0xe000
	s_nop 0
	global_load_lds_dwordx4 v[142:143], off
	s_waitcnt vmcnt(8)
	s_waitcnt lgkmcnt(0)
	s_barrier
	s_setprio 1
	s_waitcnt lgkmcnt(0)
	v_mfma_f32_16x16x32_bf16 v[126:129], v[150:153], v[182:185], v[126:129]
	v_mfma_f32_16x16x32_bf16 v[122:125], v[158:161], v[182:185], v[122:125]
	v_mfma_f32_16x16x32_bf16 v[114:117], v[150:153], v[206:209], v[114:117]
	v_mfma_f32_16x16x32_bf16 v[106:109], v[158:161], v[206:209], v[106:109]
	v_mfma_f32_16x16x32_bf16 v[98:101], v[150:153], v[232:235], v[98:101]
	v_mfma_f32_16x16x32_bf16 v[90:93], v[158:161], v[232:235], v[90:93]
	v_mfma_f32_16x16x32_bf16 v[78:81], v[150:153], v[240:243], v[78:81]
	v_mfma_f32_16x16x32_bf16 v[74:77], v[158:161], v[240:243], v[74:77]
	v_mfma_f32_16x16x32_bf16 v[126:129], v[154:157], v[202:205], v[126:129]
	v_mfma_f32_16x16x32_bf16 v[122:125], v[162:165], v[202:205], v[122:125]
	v_mfma_f32_16x16x32_bf16 v[114:117], v[154:157], v[210:213], v[114:117]
	v_mfma_f32_16x16x32_bf16 v[106:109], v[162:165], v[210:213], v[106:109]
	v_mfma_f32_16x16x32_bf16 v[98:101], v[154:157], v[236:239], v[98:101]
	v_mfma_f32_16x16x32_bf16 v[90:93], v[162:165], v[236:239], v[90:93]
	v_mfma_f32_16x16x32_bf16 v[78:81], v[154:157], v[244:247], v[78:81]
	v_mfma_f32_16x16x32_bf16 v[74:77], v[162:165], v[244:247], v[74:77]
	s_setprio 0
	s_setprio 1
	v_mfma_f32_16x16x32_bf16 v[118:121], v[166:169], v[182:185], v[118:121]
	v_mfma_f32_16x16x32_bf16 v[110:113], v[174:177], v[182:185], v[110:113]
	v_mfma_f32_16x16x32_bf16 v[102:105], v[166:169], v[206:209], v[102:105]
	v_mfma_f32_16x16x32_bf16 v[94:97], v[174:177], v[206:209], v[94:97]
	v_mfma_f32_16x16x32_bf16 v[86:89], v[166:169], v[232:235], v[86:89]
	v_mfma_f32_16x16x32_bf16 v[82:85], v[174:177], v[232:235], v[82:85]
	v_mfma_f32_16x16x32_bf16 v[70:73], v[166:169], v[240:243], v[70:73]
	v_mfma_f32_16x16x32_bf16 v[66:69], v[174:177], v[240:243], v[66:69]
	v_mfma_f32_16x16x32_bf16 v[118:121], v[170:173], v[202:205], v[118:121]
	v_mfma_f32_16x16x32_bf16 v[110:113], v[178:181], v[202:205], v[110:113]
	v_mfma_f32_16x16x32_bf16 v[102:105], v[170:173], v[210:213], v[102:105]
	v_mfma_f32_16x16x32_bf16 v[94:97], v[178:181], v[210:213], v[94:97]
	v_mfma_f32_16x16x32_bf16 v[86:89], v[170:173], v[236:239], v[86:89]
	v_mfma_f32_16x16x32_bf16 v[82:85], v[178:181], v[236:239], v[82:85]
	v_mfma_f32_16x16x32_bf16 v[70:73], v[170:173], v[244:247], v[70:73]
	v_mfma_f32_16x16x32_bf16 v[66:69], v[178:181], v[244:247], v[66:69]
	s_setprio 0
	s_barrier
	s_add_i32 s49, s49, s34
	v_lshl_add_u64 v[142:143], s[24:25], 0, v[134:135]
	s_mov_b32 m0, s49
	ds_read_b128 v[182:185], v148 offset:16384
	ds_read_b128 v[202:205], v148 offset:17408
	ds_read_b128 v[206:209], v148 offset:18432
	ds_read_b128 v[210:213], v148 offset:19456
	ds_read_b128 v[232:235], v148 offset:20480
	ds_read_b128 v[236:239], v148 offset:21504
	ds_read_b128 v[240:243], v148 offset:22528
	ds_read_b128 v[244:247], v148 offset:23552
	global_load_lds_dwordx4 v[142:143], off
	s_add_i32 m0, s49, 0x2000
	s_add_u32 s50, s24, 0x40000
	v_lshl_add_u64 v[186:187], s[24:25], 0, v[130:131]
	s_addc_u32 s51, s25, 0
	s_add_i32 s49, s52, s34
	global_load_lds_dwordx4 v[186:187], off
	v_lshl_add_u64 v[214:215], s[50:51], 0, v[134:135]
	s_mov_b32 m0, s49
	v_lshl_add_u64 v[248:249], s[26:27], 0, v[132:133]
	global_load_lds_dwordx4 v[214:215], off
	v_lshl_add_u64 v[214:215], s[50:51], 0, v[130:131]
	s_add_i32 m0, s49, 0x2000
	s_nop 0
	global_load_lds_dwordx4 v[214:215], off
	v_lshl_add_u64 v[214:215], s[26:27], 0, v[136:137]
	s_mov_b32 m0, s36
	s_nop 0
	global_load_lds_dwordx4 v[214:215], off
	s_mov_b32 m0, s37
	s_nop 0
	global_load_lds_dwordx4 v[248:249], off
	s_waitcnt vmcnt(8)
	s_waitcnt lgkmcnt(0)
	s_barrier
; #define PG8_STAGE(bufoff, gbase, voff) do { _Pragma("unroll") for (int _i = 0; _i < 2; ++_i) \
;         __builtin_amdgcn_global_load_lds((const unsigned*)((const char*)(gbase) + (voff)[_i]), (PG8_LAS unsigned*)(lds + (bufoff) + ldsw + _i * 8192), 16, 0, 0); } while (0)
; #define PG8_LDA(dst, b, h) do { _Pragma("unroll") for (int m = 0; m < 4; ++m) _Pragma("unroll") for (int k = 0; k < 2; ++k) dst[m][k] = *(const PG8_LAS bf16x8*)(lds + PG8_SA(b, h) + aoff + m * 2048 + k * 1024); } while (0)
; #define PG8_LDB(dst, b, h) do { _Pragma("unroll") for (int n = 0; n < 2; ++n) _Pragma("unroll") for (int k = 0; k < 2; ++k) dst[n][k] = *(const PG8_LAS bf16x8*)(lds + PG8_SB(b, h) + boff + n * 2048 + k * 1024); } while (0)
; #define PG8_MMA(ai, bj, At, Bt) do { __builtin_amdgcn_s_setprio(1); _Pragma("unroll") for (int m = 0; m < 4; ++m) _Pragma("unroll") for (int n = 0; n < 2; ++n) _Pragma("unroll") for (int k = 0; k < 2; ++k) \
;         acc[ai][bj][m][n] = __builtin_amdgcn_mfma_f32_16x16x32_bf16(Bt[n][k], At[m][k], acc[ai][bj][m][n], 0, 0, 0); __builtin_amdgcn_s_setprio(0); } while (0)
; #define PG8_WAIT_V(n) asm volatile("s_waitcnt vmcnt(" #n ")" ::: "memory")
; #define PG8_WAIT_L(n) asm volatile("s_waitcnt lgkmcnt(" #n ")" ::: "memory")
; #define PG8_BAR __builtin_amdgcn_s_barrier()
; #define PG8_SCHED __builtin_amdgcn_sched_barrier(0)
; template <class Epi, class Sched, bool ALIGN_EPI = false, bool SP2 = false>
; __device__ __forceinline__ void gemm_phase(PG8_LAS unsigned char* lds, const Gemm g, const Sched& S, const Epi& E) {
;     ...
;             PG8_WAIT_V(8); PG8_WAIT_L(0); PG8_BAR; PG8_MMA(1, 0, At, B0); PG8_MMA(1, 1, At, B1); PG8_BAR; PG8_SCHED;
;             PG8_LDB(B0, 1, 0); PG8_LDB(B1, 1, 1); PG8_SCHED; PG8_LDA(At, 1, 0); PG8_STAGE(PG8_SA(0, 1), a2 + hstepA, voffA);
;             PG8_WAIT_V(8); PG8_WAIT_L(0); PG8_BAR; PG8_MMA(0, 0, At, B0); PG8_MMA(0, 1, At, B1); PG8_BAR; PG8_SCHED;
;             PG8_LDA(At, 1, 1); PG8_STAGE(PG8_SB(1, 0), b3, voffB); PG8_STAGE(PG8_SB(1, 1), b3 + hstepB, voffB); PG8_STAGE(PG8_SA(1, 0), a3, voffA);
	s_setprio 1
	s_waitcnt lgkmcnt(0)
	v_mfma_f32_16x16x32_bf16 v[62:65], v[150:153], v[182:185], v[62:65]
	v_mfma_f32_16x16x32_bf16 v[58:61], v[158:161], v[182:185], v[58:61]
	v_mfma_f32_16x16x32_bf16 v[46:49], v[150:153], v[206:209], v[46:49]
	v_mfma_f32_16x16x32_bf16 v[42:45], v[158:161], v[206:209], v[42:45]
	v_mfma_f32_16x16x32_bf16 v[30:33], v[150:153], v[232:235], v[30:33]
	v_mfma_f32_16x16x32_bf16 v[26:29], v[158:161], v[232:235], v[26:29]
	v_mfma_f32_16x16x32_bf16 v[14:17], v[150:153], v[240:243], v[14:17]
	v_mfma_f32_16x16x32_bf16 v[10:13], v[158:161], v[240:243], v[10:13]
	v_mfma_f32_16x16x32_bf16 v[62:65], v[154:157], v[202:205], v[62:65]
	v_mfma_f32_16x16x32_bf16 v[58:61], v[162:165], v[202:205], v[58:61]
	v_mfma_f32_16x16x32_bf16 v[46:49], v[154:157], v[210:213], v[46:49]
	v_mfma_f32_16x16x32_bf16 v[42:45], v[162:165], v[210:213], v[42:45]
	v_mfma_f32_16x16x32_bf16 v[30:33], v[154:157], v[236:239], v[30:33]
	v_mfma_f32_16x16x32_bf16 v[26:29], v[162:165], v[236:239], v[26:29]
	v_mfma_f32_16x16x32_bf16 v[14:17], v[154:157], v[244:247], v[14:17]
	v_mfma_f32_16x16x32_bf16 v[10:13], v[162:165], v[244:247], v[10:13]
	s_setprio 0
	s_setprio 1
	v_mfma_f32_16x16x32_bf16 v[54:57], v[166:169], v[182:185], v[54:57]
	v_mfma_f32_16x16x32_bf16 v[50:53], v[174:177], v[182:185], v[50:53]
	v_mfma_f32_16x16x32_bf16 v[38:41], v[166:169], v[206:209], v[38:41]
	v_mfma_f32_16x16x32_bf16 v[34:37], v[174:177], v[206:209], v[34:37]
	v_mfma_f32_16x16x32_bf16 v[22:25], v[166:169], v[232:235], v[22:25]
	v_mfma_f32_16x16x32_bf16 v[18:21], v[174:177], v[232:235], v[18:21]
	v_mfma_f32_16x16x32_bf16 v[6:9], v[166:169], v[240:243], v[6:9]
	v_mfma_f32_16x16x32_bf16 v[2:5], v[174:177], v[240:243], v[2:5]
	v_mfma_f32_16x16x32_bf16 v[54:57], v[170:173], v[202:205], v[54:57]
	v_mfma_f32_16x16x32_bf16 v[50:53], v[178:181], v[202:205], v[50:53]
	v_mfma_f32_16x16x32_bf16 v[38:41], v[170:173], v[210:213], v[38:41]
	v_mfma_f32_16x16x32_bf16 v[34:37], v[178:181], v[210:213], v[34:37]
	v_mfma_f32_16x16x32_bf16 v[22:25], v[170:173], v[236:239], v[22:25]
	v_mfma_f32_16x16x32_bf16 v[18:21], v[178:181], v[236:239], v[18:21]
	v_mfma_f32_16x16x32_bf16 v[6:9], v[170:173], v[244:247], v[6:9]
	v_mfma_f32_16x16x32_bf16 v[2:5], v[178:181], v[244:247], v[2:5]
	s_setprio 0
	s_barrier
	s_add_i32 s49, 0, 0x18000
	v_add_u32_e32 v144, s49, v145
	s_add_i32 s50, 0, 0x1c000
	ds_read_b128 v[150:153], v144
	ds_read_b128 v[154:157], v144 offset:1024
	ds_read_b128 v[158:161], v144 offset:2048
	ds_read_b128 v[162:165], v144 offset:3072
	v_add_u32_e32 v144, s50, v145
	ds_read_b128 v[166:169], v144
	ds_read_b128 v[170:173], v144 offset:1024
	ds_read_b128 v[174:177], v144 offset:2048
	ds_read_b128 v[178:181], v144 offset:3072
	s_add_u32 s26, s26, 0x40000
	s_addc_u32 s27, s27, 0
	s_mov_b32 m0, s38
	v_lshl_add_u64 v[250:251], s[26:27], 0, v[136:137]
	ds_read_b128 v[182:185], v148 offset:32768
	ds_read_b128 v[202:205], v148 offset:33792
	ds_read_b128 v[206:209], v148 offset:34816
	ds_read_b128 v[210:213], v148 offset:35840
	ds_read_b128 v[232:235], v148 offset:36864
	ds_read_b128 v[236:239], v148 offset:37888
	ds_read_b128 v[240:243], v148 offset:38912
	ds_read_b128 v[244:247], v148 offset:39936
	global_load_lds_dwordx4 v[250:251], off
	v_lshl_add_u64 v[250:251], s[26:27], 0, v[132:133]
	s_mov_b32 m0, s39
	s_nop 0
	global_load_lds_dwordx4 v[250:251], off
	s_waitcnt vmcnt(8)
	s_waitcnt lgkmcnt(0)
	s_barrier
	s_setprio 1
	s_waitcnt lgkmcnt(0)
	v_mfma_f32_16x16x32_bf16 v[126:129], v[150:153], v[182:185], v[126:129]
	v_mfma_f32_16x16x32_bf16 v[122:125], v[158:161], v[182:185], v[122:125]
	v_mfma_f32_16x16x32_bf16 v[114:117], v[150:153], v[206:209], v[114:117]
	v_mfma_f32_16x16x32_bf16 v[106:109], v[158:161], v[206:209], v[106:109]
	v_mfma_f32_16x16x32_bf16 v[98:101], v[150:153], v[232:235], v[98:101]
	v_mfma_f32_16x16x32_bf16 v[90:93], v[158:161], v[232:235], v[90:93]
	v_mfma_f32_16x16x32_bf16 v[78:81], v[150:153], v[240:243], v[78:81]
	v_mfma_f32_16x16x32_bf16 v[74:77], v[158:161], v[240:243], v[74:77]
	v_mfma_f32_16x16x32_bf16 v[126:129], v[154:157], v[202:205], v[126:129]
	v_mfma_f32_16x16x32_bf16 v[122:125], v[162:165], v[202:205], v[122:125]
	v_mfma_f32_16x16x32_bf16 v[114:117], v[154:157], v[210:213], v[114:117]
	v_mfma_f32_16x16x32_bf16 v[106:109], v[162:165], v[210:213], v[106:109]
	v_mfma_f32_16x16x32_bf16 v[98:101], v[154:157], v[236:239], v[98:101]
	v_mfma_f32_16x16x32_bf16 v[90:93], v[162:165], v[236:239], v[90:93]
	v_mfma_f32_16x16x32_bf16 v[78:81], v[154:157], v[244:247], v[78:81]
	v_mfma_f32_16x16x32_bf16 v[74:77], v[162:165], v[244:247], v[74:77]
	s_setprio 0
	s_setprio 1
	v_mfma_f32_16x16x32_bf16 v[118:121], v[166:169], v[182:185], v[118:121]
	v_mfma_f32_16x16x32_bf16 v[110:113], v[174:177], v[182:185], v[110:113]
	v_mfma_f32_16x16x32_bf16 v[102:105], v[166:169], v[206:209], v[102:105]
	v_mfma_f32_16x16x32_bf16 v[94:97], v[174:177], v[206:209], v[94:97]
	v_mfma_f32_16x16x32_bf16 v[86:89], v[166:169], v[232:235], v[86:89]
	v_mfma_f32_16x16x32_bf16 v[82:85], v[174:177], v[232:235], v[82:85]
	v_mfma_f32_16x16x32_bf16 v[70:73], v[166:169], v[240:243], v[70:73]
	v_mfma_f32_16x16x32_bf16 v[66:69], v[174:177], v[240:243], v[66:69]
	v_mfma_f32_16x16x32_bf16 v[118:121], v[170:173], v[202:205], v[118:121]
	v_mfma_f32_16x16x32_bf16 v[110:113], v[178:181], v[202:205], v[110:113]
	v_mfma_f32_16x16x32_bf16 v[102:105], v[170:173], v[210:213], v[102:105]
	v_mfma_f32_16x16x32_bf16 v[94:97], v[178:181], v[210:213], v[94:97]
	v_mfma_f32_16x16x32_bf16 v[86:89], v[170:173], v[236:239], v[86:89]
	v_mfma_f32_16x16x32_bf16 v[82:85], v[178:181], v[236:239], v[82:85]
	v_mfma_f32_16x16x32_bf16 v[70:73], v[170:173], v[244:247], v[70:73]
	v_mfma_f32_16x16x32_bf16 v[66:69], v[178:181], v[244:247], v[66:69]
	s_setprio 0
	s_barrier
; #define PG8_STAGE(bufoff, gbase, voff) do { _Pragma("unroll") for (int _i = 0; _i < 2; ++_i) \
;         __builtin_amdgcn_global_load_lds((const unsigned*)((const char*)(gbase) + (voff)[_i]), (PG8_LAS unsigned*)(lds + (bufoff) + ldsw + _i * 8192), 16, 0, 0); } while (0)
; #define PG8_LDA(dst, b, h) do { _Pragma("unroll") for (int m = 0; m < 4; ++m) _Pragma("unroll") for (int k = 0; k < 2; ++k) dst[m][k] = *(const PG8_LAS bf16x8*)(lds + PG8_SA(b, h) + aoff + m * 2048 + k * 1024); } while (0)
; #define PG8_MMA(ai, bj, At, Bt) do { __builtin_amdgcn_s_setprio(1); _Pragma("unroll") for (int m = 0; m < 4; ++m) _Pragma("unroll") for (int n = 0; n < 2; ++n) _Pragma("unroll") for (int k = 0; k < 2; ++k) \
;         acc[ai][bj][m][n] = __builtin_amdgcn_mfma_f32_16x16x32_bf16(Bt[n][k], At[m][k], acc[ai][bj][m][n], 0, 0, 0); __builtin_amdgcn_s_setprio(0); } while (0)
; #define PG8_WAIT_V(n) asm volatile("s_waitcnt vmcnt(" #n ")" ::: "memory")
; #define PG8_WAIT_L(n) asm volatile("s_waitcnt lgkmcnt(" #n ")" ::: "memory")
; #define PG8_BAR __builtin_amdgcn_s_barrier()
; #define PG8_SCHED __builtin_amdgcn_sched_barrier(0)
; template <class Epi, class Sched, bool ALIGN_EPI = false, bool SP2 = false>
; __device__ __forceinline__ void gemm_phase(PG8_LAS unsigned char* lds, const Gemm g, const Sched& S, const Epi& E) {
;     ...
;         for (int t = 0; t < nt; t += 2) {
;     ...
;             PG8_LDA(At, 1, 1); PG8_STAGE(PG8_SB(1, 0), b3, voffB); PG8_STAGE(PG8_SB(1, 1), b3 + hstepB, voffB); PG8_STAGE(PG8_SA(1, 0), a3, voffA);
;             PG8_WAIT_V(8); PG8_WAIT_L(0); PG8_BAR; PG8_MMA(1, 0, At, B0); PG8_MMA(1, 1, At, B1); PG8_BAR; PG8_SCHED;
	s_add_i32 s26, s49, s34
	v_lshl_add_u64 v[142:143], v[142:143], 0, s[96:97]
	s_mov_b32 m0, s26
	ds_read_b128 v[182:185], v148 offset:49152
	ds_read_b128 v[202:205], v148 offset:50176
	ds_read_b128 v[206:209], v148 offset:51200
	ds_read_b128 v[210:213], v148 offset:52224
	ds_read_b128 v[232:235], v148 offset:53248
	ds_read_b128 v[236:239], v148 offset:54272
	ds_read_b128 v[240:243], v148 offset:55296
	ds_read_b128 v[244:247], v148 offset:56320
	global_load_lds_dwordx4 v[142:143], off
	s_add_i32 m0, s26, 0x2000
	s_add_u32 s24, s24, 0x40080
	v_lshl_add_u64 v[142:143], v[186:187], 0, s[96:97]
	s_addc_u32 s25, s25, 0
	s_add_i32 s26, s50, s34
	global_load_lds_dwordx4 v[142:143], off
	v_lshl_add_u64 v[142:143], s[24:25], 0, v[134:135]
	s_mov_b32 m0, s26
	s_nop 0
	global_load_lds_dwordx4 v[142:143], off
	v_lshl_add_u64 v[142:143], s[24:25], 0, v[130:131]
	s_add_i32 m0, s26, 0x2000
	s_nop 0
	global_load_lds_dwordx4 v[142:143], off
	v_lshl_add_u64 v[142:143], v[214:215], 0, s[96:97]
	s_mov_b32 m0, s40
	s_nop 0
	global_load_lds_dwordx4 v[142:143], off
	v_lshl_add_u64 v[142:143], v[248:249], 0, s[96:97]
	s_mov_b32 m0, s41
	s_nop 0
	global_load_lds_dwordx4 v[142:143], off
	s_waitcnt vmcnt(8)
	s_waitcnt lgkmcnt(0)
	s_barrier
	s_setprio 1
	s_waitcnt lgkmcnt(0)
	v_mfma_f32_16x16x32_bf16 v[62:65], v[150:153], v[182:185], v[62:65]
	v_mfma_f32_16x16x32_bf16 v[58:61], v[158:161], v[182:185], v[58:61]
	v_mfma_f32_16x16x32_bf16 v[46:49], v[150:153], v[206:209], v[46:49]
	v_mfma_f32_16x16x32_bf16 v[42:45], v[158:161], v[206:209], v[42:45]
	v_mfma_f32_16x16x32_bf16 v[30:33], v[150:153], v[232:235], v[30:33]
	v_mfma_f32_16x16x32_bf16 v[26:29], v[158:161], v[232:235], v[26:29]
	v_mfma_f32_16x16x32_bf16 v[14:17], v[150:153], v[240:243], v[14:17]
	v_mfma_f32_16x16x32_bf16 v[10:13], v[158:161], v[240:243], v[10:13]
	v_mfma_f32_16x16x32_bf16 v[62:65], v[154:157], v[202:205], v[62:65]
	v_mfma_f32_16x16x32_bf16 v[58:61], v[162:165], v[202:205], v[58:61]
	v_mfma_f32_16x16x32_bf16 v[46:49], v[154:157], v[210:213], v[46:49]
	v_mfma_f32_16x16x32_bf16 v[42:45], v[162:165], v[210:213], v[42:45]
	v_mfma_f32_16x16x32_bf16 v[30:33], v[154:157], v[236:239], v[30:33]
	v_mfma_f32_16x16x32_bf16 v[26:29], v[162:165], v[236:239], v[26:29]
	v_mfma_f32_16x16x32_bf16 v[14:17], v[154:157], v[244:247], v[14:17]
	v_mfma_f32_16x16x32_bf16 v[10:13], v[162:165], v[244:247], v[10:13]
	s_setprio 0
	s_setprio 1
	v_mfma_f32_16x16x32_bf16 v[54:57], v[166:169], v[182:185], v[54:57]
	v_mfma_f32_16x16x32_bf16 v[50:53], v[174:177], v[182:185], v[50:53]
	v_mfma_f32_16x16x32_bf16 v[38:41], v[166:169], v[206:209], v[38:41]
	v_mfma_f32_16x16x32_bf16 v[34:37], v[174:177], v[206:209], v[34:37]
	v_mfma_f32_16x16x32_bf16 v[22:25], v[166:169], v[232:235], v[22:25]
	v_mfma_f32_16x16x32_bf16 v[18:21], v[174:177], v[232:235], v[18:21]
	v_mfma_f32_16x16x32_bf16 v[6:9], v[166:169], v[240:243], v[6:9]
	v_mfma_f32_16x16x32_bf16 v[2:5], v[174:177], v[240:243], v[2:5]
	v_mfma_f32_16x16x32_bf16 v[54:57], v[170:173], v[202:205], v[54:57]
	v_mfma_f32_16x16x32_bf16 v[50:53], v[178:181], v[202:205], v[50:53]
	v_mfma_f32_16x16x32_bf16 v[38:41], v[170:173], v[210:213], v[38:41]
	v_mfma_f32_16x16x32_bf16 v[34:37], v[178:181], v[210:213], v[34:37]
	v_mfma_f32_16x16x32_bf16 v[22:25], v[170:173], v[236:239], v[22:25]
	v_mfma_f32_16x16x32_bf16 v[18:21], v[178:181], v[236:239], v[18:21]
	v_mfma_f32_16x16x32_bf16 v[6:9], v[170:173], v[244:247], v[6:9]
	v_mfma_f32_16x16x32_bf16 v[2:5], v[178:181], v[244:247], v[2:5]
	s_setprio 0
	s_add_i32 s48, s48, 2
	s_add_u32 s22, s22, 0x100
	s_addc_u32 s23, s23, 0
	s_add_u32 s46, s46, 0x100
	s_addc_u32 s47, s47, 0
	s_cmp_gt_u32 s48, 13
	s_barrier
	s_cbranch_scc0 .LBB0_1354
	s_and_b64 vcc, exec, s[10:11]
	s_cbranch_vccz .LBB0_1357
	s_barrier

; #define PG8_STAGE(bufoff, gbase, voff) do { _Pragma("unroll") for (int _i = 0; _i < 2; ++_i) \
;         __builtin_amdgcn_global_load_lds((const unsigned*)((const char*)(gbase) + (voff)[_i]), (PG8_LAS unsigned*)(lds + (bufoff) + ldsw + _i * 8192), 16, 0, 0); } while (0)
; #define PG8_LDA(dst, b, h) do { _Pragma("unroll") for (int m = 0; m < 4; ++m) _Pragma("unroll") for (int k = 0; k < 2; ++k) dst[m][k] = *(const PG8_LAS bf16x8*)(lds + PG8_SA(b, h) + aoff + m * 2048 + k * 1024); } while (0)
; #define PG8_LDB(dst, b, h) do { _Pragma("unroll") for (int n = 0; n < 2; ++n) _Pragma("unroll") for (int k = 0; k < 2; ++k) dst[n][k] = *(const PG8_LAS bf16x8*)(lds + PG8_SB(b, h) + boff + n * 2048 + k * 1024); } while (0)
; #define PG8_MMA(ai, bj, At, Bt) do { __builtin_amdgcn_s_setprio(1); _Pragma("unroll") for (int m = 0; m < 4; ++m) _Pragma("unroll") for (int n = 0; n < 2; ++n) _Pragma("unroll") for (int k = 0; k < 2; ++k) \
;         acc[ai][bj][m][n] = __builtin_amdgcn_mfma_f32_16x16x32_bf16(Bt[n][k], At[m][k], acc[ai][bj][m][n], 0, 0, 0); __builtin_amdgcn_s_setprio(0); } while (0)
; #define PG8_WAIT_V(n) asm volatile("s_waitcnt vmcnt(" #n ")" ::: "memory")
; #define PG8_WAIT_L(n) asm volatile("s_waitcnt lgkmcnt(" #n ")" ::: "memory")
; template <class Epi, class Sched, bool ALIGN_EPI = false, bool SP2 = false>
; __device__ __forceinline__ void gemm_phase(PG8_LAS unsigned char* lds, const Gemm g, const Sched& S, const Epi& E) {
;     ...
;             const bool last = (t == nt - 2);
;             const char* a1 = cA + (size_t)(t + 1) * kstep;
;             const char* a2 = last ? nA : cA + (size_t)(t + 2) * kstep; const char* b2 = last ? nB : cB + (size_t)(t + 2) * kstep;
;             const char* a3 = a2 + kstep; const char* b3 = b2 + kstep;
;             if (last && has_next) S.a_ready(nxt);
;             if constexpr (SP2) {
;             PG8_LDB(B0, 0, 0); PG8_LDB(B1, 0, 1); PG8_SCHED; PG8_LDA(At, 0, 0); PG8_STAGE(PG8_SA(1, 1), a1 + hstepA, voffA);
;             PG8_WAIT_V(8); PG8_WAIT_L(0); PG8_BAR; PG8_MMA(0, 0, At, B0); PG8_MMA(0, 1, At, B1); PG8_BAR; PG8_SCHED;
;             PG8_LDA(At, 0, 1); PG8_STAGE(PG8_SB(0, 0), b2, voffB); PG8_STAGE(PG8_SB(0, 1), b2 + hstepB, voffB); PG8_STAGE(PG8_SA(0, 0), a2, voffA);
;             PG8_WAIT_V(8); PG8_WAIT_L(0); PG8_BAR; PG8_MMA(1, 0, At, B0); PG8_MMA(1, 1, At, B1); PG8_BAR; PG8_SCHED;
.LBB0_1438:
	s_add_u32 s20, s18, 0x100
	s_addc_u32 s21, s19, 0
	s_add_i32 s50, 0, 0x10000
	s_cmp_eq_u32 s49, 40
	s_cselect_b32 s25, s9, s21
	s_cselect_b32 s24, s8, s20
	s_cselect_b32 s23, s17, s48
	s_cselect_b32 s22, s16, s47
	s_add_i32 s51, 0, 0x14000
	v_add_u32_e32 v142, s50, v186
	v_add_u32_e32 v172, s51, v186
	ds_read_b128 v[130:133], v142
	ds_read_b128 v[134:137], v142 offset:1024
	ds_read_b128 v[138:141], v142 offset:2048
	ds_read_b128 v[142:145], v142 offset:3072
	ds_read_b128 v[146:149], v172
	ds_read_b128 v[150:153], v172 offset:1024
	ds_read_b128 v[168:171], v172 offset:2048
	ds_read_b128 v[172:175], v172 offset:3072
	v_lshl_add_u64 v[184:185], s[18:19], 0, v[164:165]
	s_add_i32 m0, s31, 0xc000
	ds_read_b128 v[176:179], v200
	ds_read_b128 v[180:183], v200 offset:1024
	ds_read_b128 v[202:205], v200 offset:2048
	ds_read_b128 v[206:209], v200 offset:3072
	ds_read_b128 v[210:213], v200 offset:4096
	ds_read_b128 v[232:235], v200 offset:5120
	ds_read_b128 v[236:239], v200 offset:6144
	ds_read_b128 v[240:243], v200 offset:7168
	global_load_lds_dwordx4 v[184:185], off
	v_lshl_add_u64 v[184:185], s[18:19], 0, v[166:167]
	s_add_i32 m0, s31, 0xe000
	s_nop 0
	global_load_lds_dwordx4 v[184:185], off
	s_waitcnt vmcnt(8)
	s_waitcnt lgkmcnt(0)
	s_barrier
	s_setprio 1
	s_waitcnt lgkmcnt(0)
	v_mfma_f32_16x16x32_bf16 v[126:129], v[130:133], v[176:179], v[126:129]
	v_mfma_f32_16x16x32_bf16 v[122:125], v[138:141], v[176:179], v[122:125]
	v_mfma_f32_16x16x32_bf16 v[110:113], v[130:133], v[202:205], v[110:113]
	v_mfma_f32_16x16x32_bf16 v[106:109], v[138:141], v[202:205], v[106:109]
	v_mfma_f32_16x16x32_bf16 v[94:97], v[130:133], v[210:213], v[94:97]
	v_mfma_f32_16x16x32_bf16 v[90:93], v[138:141], v[210:213], v[90:93]
	v_mfma_f32_16x16x32_bf16 v[78:81], v[130:133], v[236:239], v[78:81]
	v_mfma_f32_16x16x32_bf16 v[74:77], v[138:141], v[236:239], v[74:77]
	v_mfma_f32_16x16x32_bf16 v[126:129], v[134:137], v[180:183], v[126:129]
	v_mfma_f32_16x16x32_bf16 v[122:125], v[142:145], v[180:183], v[122:125]
	v_mfma_f32_16x16x32_bf16 v[110:113], v[134:137], v[206:209], v[110:113]
	v_mfma_f32_16x16x32_bf16 v[106:109], v[142:145], v[206:209], v[106:109]
	v_mfma_f32_16x16x32_bf16 v[94:97], v[134:137], v[232:235], v[94:97]
	v_mfma_f32_16x16x32_bf16 v[90:93], v[142:145], v[232:235], v[90:93]
	v_mfma_f32_16x16x32_bf16 v[78:81], v[134:137], v[240:243], v[78:81]
	v_mfma_f32_16x16x32_bf16 v[74:77], v[142:145], v[240:243], v[74:77]
	s_setprio 0
	s_setprio 1
	v_mfma_f32_16x16x32_bf16 v[118:121], v[146:149], v[176:179], v[118:121]
	v_mfma_f32_16x16x32_bf16 v[114:117], v[168:171], v[176:179], v[114:117]
	v_mfma_f32_16x16x32_bf16 v[102:105], v[146:149], v[202:205], v[102:105]
	v_mfma_f32_16x16x32_bf16 v[98:101], v[168:171], v[202:205], v[98:101]
	v_mfma_f32_16x16x32_bf16 v[86:89], v[146:149], v[210:213], v[86:89]
	v_mfma_f32_16x16x32_bf16 v[82:85], v[168:171], v[210:213], v[82:85]
	v_mfma_f32_16x16x32_bf16 v[70:73], v[146:149], v[236:239], v[70:73]
	v_mfma_f32_16x16x32_bf16 v[66:69], v[168:171], v[236:239], v[66:69]
	v_mfma_f32_16x16x32_bf16 v[118:121], v[150:153], v[180:183], v[118:121]
	v_mfma_f32_16x16x32_bf16 v[114:117], v[172:175], v[180:183], v[114:117]
	v_mfma_f32_16x16x32_bf16 v[102:105], v[150:153], v[206:209], v[102:105]
	v_mfma_f32_16x16x32_bf16 v[98:101], v[172:175], v[206:209], v[98:101]
	v_mfma_f32_16x16x32_bf16 v[86:89], v[150:153], v[232:235], v[86:89]
	v_mfma_f32_16x16x32_bf16 v[82:85], v[172:175], v[232:235], v[82:85]
	v_mfma_f32_16x16x32_bf16 v[70:73], v[150:153], v[240:243], v[70:73]
	v_mfma_f32_16x16x32_bf16 v[66:69], v[172:175], v[240:243], v[66:69]
	s_setprio 0
	s_barrier
	s_add_i32 s18, s50, s30
	v_lshl_add_u64 v[184:185], s[22:23], 0, v[156:157]
	s_mov_b32 m0, s18
	ds_read_b128 v[176:179], v200 offset:16384
	ds_read_b128 v[180:183], v200 offset:17408
	ds_read_b128 v[202:205], v200 offset:18432
	ds_read_b128 v[206:209], v200 offset:19456
	ds_read_b128 v[210:213], v200 offset:20480
	ds_read_b128 v[232:235], v200 offset:21504
	ds_read_b128 v[236:239], v200 offset:22528
	ds_read_b128 v[240:243], v200 offset:23552
	global_load_lds_dwordx4 v[184:185], off
	s_add_i32 m0, s18, 0x2000
	s_add_u32 s18, s22, 0xb0000
	v_lshl_add_u64 v[214:215], s[22:23], 0, v[160:161]
	s_addc_u32 s19, s23, 0
	s_add_i32 s50, s51, s30
	global_load_lds_dwordx4 v[214:215], off
	v_lshl_add_u64 v[244:245], s[18:19], 0, v[156:157]
	s_mov_b32 m0, s50
	v_lshl_add_u64 v[246:247], s[24:25], 0, v[158:159]
	global_load_lds_dwordx4 v[244:245], off
	v_lshl_add_u64 v[244:245], s[18:19], 0, v[160:161]
	s_add_i32 m0, s50, 0x2000
	s_nop 0
	global_load_lds_dwordx4 v[244:245], off
	v_lshl_add_u64 v[244:245], s[24:25], 0, v[154:155]
	s_mov_b32 m0, s31
	s_nop 0
	global_load_lds_dwordx4 v[244:245], off
	s_mov_b32 m0, s34
	s_nop 0
	global_load_lds_dwordx4 v[246:247], off
	s_waitcnt vmcnt(8)
	s_waitcnt lgkmcnt(0)
	s_barrier
; #define PG8_STAGE(bufoff, gbase, voff) do { _Pragma("unroll") for (int _i = 0; _i < 2; ++_i) \
;         __builtin_amdgcn_global_load_lds((const unsigned*)((const char*)(gbase) + (voff)[_i]), (PG8_LAS unsigned*)(lds + (bufoff) + ldsw + _i * 8192), 16, 0, 0); } while (0)
; #define PG8_LDA(dst, b, h) do { _Pragma("unroll") for (int m = 0; m < 4; ++m) _Pragma("unroll") for (int k = 0; k < 2; ++k) dst[m][k] = *(const PG8_LAS bf16x8*)(lds + PG8_SA(b, h) + aoff + m * 2048 + k * 1024); } while (0)
; #define PG8_LDB(dst, b, h) do { _Pragma("unroll") for (int n = 0; n < 2; ++n) _Pragma("unroll") for (int k = 0; k < 2; ++k) dst[n][k] = *(const PG8_LAS bf16x8*)(lds + PG8_SB(b, h) + boff + n * 2048 + k * 1024); } while (0)
; #define PG8_MMA(ai, bj, At, Bt) do { __builtin_amdgcn_s_setprio(1); _Pragma("unroll") for (int m = 0; m < 4; ++m) _Pragma("unroll") for (int n = 0; n < 2; ++n) _Pragma("unroll") for (int k = 0; k < 2; ++k) \
;         acc[ai][bj][m][n] = __builtin_amdgcn_mfma_f32_16x16x32_bf16(Bt[n][k], At[m][k], acc[ai][bj][m][n], 0, 0, 0); __builtin_amdgcn_s_setprio(0); } while (0)
; #define PG8_WAIT_V(n) asm volatile("s_waitcnt vmcnt(" #n ")" ::: "memory")
; #define PG8_WAIT_L(n) asm volatile("s_waitcnt lgkmcnt(" #n ")" ::: "memory")
; #define PG8_BAR __builtin_amdgcn_s_barrier()
; #define PG8_SCHED __builtin_amdgcn_sched_barrier(0)
; template <class Epi, class Sched, bool ALIGN_EPI = false, bool SP2 = false>
; __device__ __forceinline__ void gemm_phase(PG8_LAS unsigned char* lds, const Gemm g, const Sched& S, const Epi& E) {
;     ...
;             PG8_WAIT_V(8); PG8_WAIT_L(0); PG8_BAR; PG8_MMA(1, 0, At, B0); PG8_MMA(1, 1, At, B1); PG8_BAR; PG8_SCHED;
;             PG8_LDB(B0, 1, 0); PG8_LDB(B1, 1, 1); PG8_SCHED; PG8_LDA(At, 1, 0); PG8_STAGE(PG8_SA(0, 1), a2 + hstepA, voffA);
;             PG8_WAIT_V(8); PG8_WAIT_L(0); PG8_BAR; PG8_MMA(0, 0, At, B0); PG8_MMA(0, 1, At, B1); PG8_BAR; PG8_SCHED;
;             PG8_LDA(At, 1, 1); PG8_STAGE(PG8_SB(1, 0), b3, voffB); PG8_STAGE(PG8_SB(1, 1), b3 + hstepB, voffB); PG8_STAGE(PG8_SA(1, 0), a3, voffA);
	s_setprio 1
	s_waitcnt lgkmcnt(0)
	v_mfma_f32_16x16x32_bf16 v[62:65], v[130:133], v[176:179], v[62:65]
	v_mfma_f32_16x16x32_bf16 v[58:61], v[138:141], v[176:179], v[58:61]
	v_mfma_f32_16x16x32_bf16 v[46:49], v[130:133], v[202:205], v[46:49]
	v_mfma_f32_16x16x32_bf16 v[42:45], v[138:141], v[202:205], v[42:45]
	v_mfma_f32_16x16x32_bf16 v[30:33], v[130:133], v[210:213], v[30:33]
	v_mfma_f32_16x16x32_bf16 v[26:29], v[138:141], v[210:213], v[26:29]
	v_mfma_f32_16x16x32_bf16 v[14:17], v[130:133], v[236:239], v[14:17]
	v_mfma_f32_16x16x32_bf16 v[10:13], v[138:141], v[236:239], v[10:13]
	v_mfma_f32_16x16x32_bf16 v[62:65], v[134:137], v[180:183], v[62:65]
	v_mfma_f32_16x16x32_bf16 v[58:61], v[142:145], v[180:183], v[58:61]
	v_mfma_f32_16x16x32_bf16 v[46:49], v[134:137], v[206:209], v[46:49]
	v_mfma_f32_16x16x32_bf16 v[42:45], v[142:145], v[206:209], v[42:45]
	v_mfma_f32_16x16x32_bf16 v[30:33], v[134:137], v[232:235], v[30:33]
	v_mfma_f32_16x16x32_bf16 v[26:29], v[142:145], v[232:235], v[26:29]
	v_mfma_f32_16x16x32_bf16 v[14:17], v[134:137], v[240:243], v[14:17]
	v_mfma_f32_16x16x32_bf16 v[10:13], v[142:145], v[240:243], v[10:13]
	s_setprio 0
	s_setprio 1
	v_mfma_f32_16x16x32_bf16 v[54:57], v[146:149], v[176:179], v[54:57]
	v_mfma_f32_16x16x32_bf16 v[50:53], v[168:171], v[176:179], v[50:53]
	v_mfma_f32_16x16x32_bf16 v[38:41], v[146:149], v[202:205], v[38:41]
	v_mfma_f32_16x16x32_bf16 v[34:37], v[168:171], v[202:205], v[34:37]
	v_mfma_f32_16x16x32_bf16 v[22:25], v[146:149], v[210:213], v[22:25]
	v_mfma_f32_16x16x32_bf16 v[18:21], v[168:171], v[210:213], v[18:21]
	v_mfma_f32_16x16x32_bf16 v[6:9], v[146:149], v[236:239], v[6:9]
	v_mfma_f32_16x16x32_bf16 v[2:5], v[168:171], v[236:239], v[2:5]
	v_mfma_f32_16x16x32_bf16 v[54:57], v[150:153], v[180:183], v[54:57]
	v_mfma_f32_16x16x32_bf16 v[50:53], v[172:175], v[180:183], v[50:53]
	v_mfma_f32_16x16x32_bf16 v[38:41], v[150:153], v[206:209], v[38:41]
	v_mfma_f32_16x16x32_bf16 v[34:37], v[172:175], v[206:209], v[34:37]
	v_mfma_f32_16x16x32_bf16 v[22:25], v[150:153], v[232:235], v[22:25]
	v_mfma_f32_16x16x32_bf16 v[18:21], v[172:175], v[232:235], v[18:21]
	v_mfma_f32_16x16x32_bf16 v[6:9], v[150:153], v[240:243], v[6:9]
	v_mfma_f32_16x16x32_bf16 v[2:5], v[172:175], v[240:243], v[2:5]
	s_setprio 0
	s_barrier
	s_add_i32 s50, 0, 0x18000
	s_add_i32 s51, 0, 0x1c000
	v_add_u32_e32 v142, s50, v186
	v_add_u32_e32 v172, s51, v186
	ds_read_b128 v[130:133], v142
	ds_read_b128 v[134:137], v142 offset:1024
	ds_read_b128 v[138:141], v142 offset:2048
	ds_read_b128 v[142:145], v142 offset:3072
	ds_read_b128 v[146:149], v172
	ds_read_b128 v[150:153], v172 offset:1024
	ds_read_b128 v[168:171], v172 offset:2048
	ds_read_b128 v[172:175], v172 offset:3072
	s_add_u32 s18, s24, 0xb0000
	s_addc_u32 s19, s25, 0
	s_mov_b32 m0, s35
	v_lshl_add_u64 v[248:249], s[18:19], 0, v[154:155]
	ds_read_b128 v[176:179], v200 offset:32768
	ds_read_b128 v[180:183], v200 offset:33792
	ds_read_b128 v[202:205], v200 offset:34816
	ds_read_b128 v[206:209], v200 offset:35840
	ds_read_b128 v[210:213], v200 offset:36864
	ds_read_b128 v[232:235], v200 offset:37888
	ds_read_b128 v[236:239], v200 offset:38912
	ds_read_b128 v[240:243], v200 offset:39936
	global_load_lds_dwordx4 v[248:249], off
	v_lshl_add_u64 v[248:249], s[18:19], 0, v[158:159]
	s_mov_b32 m0, s36
	s_nop 0
	global_load_lds_dwordx4 v[248:249], off
	s_waitcnt vmcnt(8)
	s_waitcnt lgkmcnt(0)
	s_barrier
	s_setprio 1
	s_waitcnt lgkmcnt(0)
	v_mfma_f32_16x16x32_bf16 v[126:129], v[130:133], v[176:179], v[126:129]
	v_mfma_f32_16x16x32_bf16 v[122:125], v[138:141], v[176:179], v[122:125]
	v_mfma_f32_16x16x32_bf16 v[110:113], v[130:133], v[202:205], v[110:113]
	v_mfma_f32_16x16x32_bf16 v[106:109], v[138:141], v[202:205], v[106:109]
	v_mfma_f32_16x16x32_bf16 v[94:97], v[130:133], v[210:213], v[94:97]
	v_mfma_f32_16x16x32_bf16 v[90:93], v[138:141], v[210:213], v[90:93]
	v_mfma_f32_16x16x32_bf16 v[78:81], v[130:133], v[236:239], v[78:81]
	v_mfma_f32_16x16x32_bf16 v[74:77], v[138:141], v[236:239], v[74:77]
	v_mfma_f32_16x16x32_bf16 v[126:129], v[134:137], v[180:183], v[126:129]
	v_mfma_f32_16x16x32_bf16 v[122:125], v[142:145], v[180:183], v[122:125]
	v_mfma_f32_16x16x32_bf16 v[110:113], v[134:137], v[206:209], v[110:113]
	v_mfma_f32_16x16x32_bf16 v[106:109], v[142:145], v[206:209], v[106:109]
	v_mfma_f32_16x16x32_bf16 v[94:97], v[134:137], v[232:235], v[94:97]
	v_mfma_f32_16x16x32_bf16 v[90:93], v[142:145], v[232:235], v[90:93]
	v_mfma_f32_16x16x32_bf16 v[78:81], v[134:137], v[240:243], v[78:81]
	v_mfma_f32_16x16x32_bf16 v[74:77], v[142:145], v[240:243], v[74:77]
	s_setprio 0
	s_setprio 1
	v_mfma_f32_16x16x32_bf16 v[118:121], v[146:149], v[176:179], v[118:121]
	v_mfma_f32_16x16x32_bf16 v[114:117], v[168:171], v[176:179], v[114:117]
	v_mfma_f32_16x16x32_bf16 v[102:105], v[146:149], v[202:205], v[102:105]
	v_mfma_f32_16x16x32_bf16 v[98:101], v[168:171], v[202:205], v[98:101]
	v_mfma_f32_16x16x32_bf16 v[86:89], v[146:149], v[210:213], v[86:89]
	v_mfma_f32_16x16x32_bf16 v[82:85], v[168:171], v[210:213], v[82:85]
	v_mfma_f32_16x16x32_bf16 v[70:73], v[146:149], v[236:239], v[70:73]
	v_mfma_f32_16x16x32_bf16 v[66:69], v[168:171], v[236:239], v[66:69]
	v_mfma_f32_16x16x32_bf16 v[118:121], v[150:153], v[180:183], v[118:121]
	v_mfma_f32_16x16x32_bf16 v[114:117], v[172:175], v[180:183], v[114:117]
	v_mfma_f32_16x16x32_bf16 v[102:105], v[150:153], v[206:209], v[102:105]
	v_mfma_f32_16x16x32_bf16 v[98:101], v[172:175], v[206:209], v[98:101]
	v_mfma_f32_16x16x32_bf16 v[86:89], v[150:153], v[232:235], v[86:89]
	v_mfma_f32_16x16x32_bf16 v[82:85], v[172:175], v[232:235], v[82:85]
	v_mfma_f32_16x16x32_bf16 v[70:73], v[150:153], v[240:243], v[70:73]
	v_mfma_f32_16x16x32_bf16 v[66:69], v[172:175], v[240:243], v[66:69]
	s_setprio 0
	s_barrier
; #define PG8_STAGE(bufoff, gbase, voff) do { _Pragma("unroll") for (int _i = 0; _i < 2; ++_i) \
;         __builtin_amdgcn_global_load_lds((const unsigned*)((const char*)(gbase) + (voff)[_i]), (PG8_LAS unsigned*)(lds + (bufoff) + ldsw + _i * 8192), 16, 0, 0); } while (0)
; #define PG8_LDA(dst, b, h) do { _Pragma("unroll") for (int m = 0; m < 4; ++m) _Pragma("unroll") for (int k = 0; k < 2; ++k) dst[m][k] = *(const PG8_LAS bf16x8*)(lds + PG8_SA(b, h) + aoff + m * 2048 + k * 1024); } while (0)
; #define PG8_MMA(ai, bj, At, Bt) do { __builtin_amdgcn_s_setprio(1); _Pragma("unroll") for (int m = 0; m < 4; ++m) _Pragma("unroll") for (int n = 0; n < 2; ++n) _Pragma("unroll") for (int k = 0; k < 2; ++k) \
;         acc[ai][bj][m][n] = __builtin_amdgcn_mfma_f32_16x16x32_bf16(Bt[n][k], At[m][k], acc[ai][bj][m][n], 0, 0, 0); __builtin_amdgcn_s_setprio(0); } while (0)
; #define PG8_WAIT_V(n) asm volatile("s_waitcnt vmcnt(" #n ")" ::: "memory")
; #define PG8_WAIT_L(n) asm volatile("s_waitcnt lgkmcnt(" #n ")" ::: "memory")
; #define PG8_BAR __builtin_amdgcn_s_barrier()
; #define PG8_SCHED __builtin_amdgcn_sched_barrier(0)
; template <class Epi, class Sched, bool ALIGN_EPI = false, bool SP2 = false>
; __device__ __forceinline__ void gemm_phase(PG8_LAS unsigned char* lds, const Gemm g, const Sched& S, const Epi& E) {
;     ...
;         for (int t = 0; t < nt; t += 2) {
;     ...
;             PG8_LDA(At, 1, 1); PG8_STAGE(PG8_SB(1, 0), b3, voffB); PG8_STAGE(PG8_SB(1, 1), b3 + hstepB, voffB); PG8_STAGE(PG8_SA(1, 0), a3, voffA);
;             PG8_WAIT_V(8); PG8_WAIT_L(0); PG8_BAR; PG8_MMA(1, 0, At, B0); PG8_MMA(1, 1, At, B1); PG8_BAR; PG8_SCHED;
	s_add_i32 s18, s50, s30
	v_lshl_add_u64 v[184:185], v[184:185], 0, s[96:97]
	s_mov_b32 m0, s18
	ds_read_b128 v[176:179], v200 offset:49152
	ds_read_b128 v[180:183], v200 offset:50176
	ds_read_b128 v[202:205], v200 offset:51200
	ds_read_b128 v[206:209], v200 offset:52224
	ds_read_b128 v[210:213], v200 offset:53248
	ds_read_b128 v[232:235], v200 offset:54272
	ds_read_b128 v[236:239], v200 offset:55296
	ds_read_b128 v[240:243], v200 offset:56320
	global_load_lds_dwordx4 v[184:185], off
	s_add_i32 m0, s18, 0x2000
	s_add_u32 s18, s22, 0xb0080
	v_lshl_add_u64 v[184:185], v[214:215], 0, s[96:97]
	s_addc_u32 s19, s23, 0
	s_add_i32 s22, s51, s30
	global_load_lds_dwordx4 v[184:185], off
	v_lshl_add_u64 v[184:185], s[18:19], 0, v[156:157]
	s_mov_b32 m0, s22
	s_nop 0
	global_load_lds_dwordx4 v[184:185], off
	v_lshl_add_u64 v[184:185], s[18:19], 0, v[160:161]
	s_add_i32 m0, s22, 0x2000
	s_nop 0
	global_load_lds_dwordx4 v[184:185], off
	v_lshl_add_u64 v[184:185], v[244:245], 0, s[96:97]
	s_mov_b32 m0, s38
	s_nop 0
	global_load_lds_dwordx4 v[184:185], off
	v_lshl_add_u64 v[184:185], v[246:247], 0, s[96:97]
	s_mov_b32 m0, s39
	s_nop 0
	global_load_lds_dwordx4 v[184:185], off
	s_waitcnt vmcnt(8)
	s_waitcnt lgkmcnt(0)
	s_barrier
	s_setprio 1
	s_waitcnt lgkmcnt(0)
	v_mfma_f32_16x16x32_bf16 v[62:65], v[130:133], v[176:179], v[62:65]
	v_mfma_f32_16x16x32_bf16 v[58:61], v[138:141], v[176:179], v[58:61]
	v_mfma_f32_16x16x32_bf16 v[46:49], v[130:133], v[202:205], v[46:49]
	v_mfma_f32_16x16x32_bf16 v[42:45], v[138:141], v[202:205], v[42:45]
	v_mfma_f32_16x16x32_bf16 v[30:33], v[130:133], v[210:213], v[30:33]
	v_mfma_f32_16x16x32_bf16 v[26:29], v[138:141], v[210:213], v[26:29]
	v_mfma_f32_16x16x32_bf16 v[14:17], v[130:133], v[236:239], v[14:17]
	v_mfma_f32_16x16x32_bf16 v[10:13], v[138:141], v[236:239], v[10:13]
	v_mfma_f32_16x16x32_bf16 v[62:65], v[134:137], v[180:183], v[62:65]
	v_mfma_f32_16x16x32_bf16 v[58:61], v[142:145], v[180:183], v[58:61]
	v_mfma_f32_16x16x32_bf16 v[46:49], v[134:137], v[206:209], v[46:49]
	v_mfma_f32_16x16x32_bf16 v[42:45], v[142:145], v[206:209], v[42:45]
	v_mfma_f32_16x16x32_bf16 v[30:33], v[134:137], v[232:235], v[30:33]
	v_mfma_f32_16x16x32_bf16 v[26:29], v[142:145], v[232:235], v[26:29]
	v_mfma_f32_16x16x32_bf16 v[14:17], v[134:137], v[240:243], v[14:17]
	v_mfma_f32_16x16x32_bf16 v[10:13], v[142:145], v[240:243], v[10:13]
	s_setprio 0
	s_setprio 1
	v_mfma_f32_16x16x32_bf16 v[54:57], v[146:149], v[176:179], v[54:57]
	v_mfma_f32_16x16x32_bf16 v[50:53], v[168:171], v[176:179], v[50:53]
	v_mfma_f32_16x16x32_bf16 v[38:41], v[146:149], v[202:205], v[38:41]
	v_mfma_f32_16x16x32_bf16 v[34:37], v[168:171], v[202:205], v[34:37]
	v_mfma_f32_16x16x32_bf16 v[22:25], v[146:149], v[210:213], v[22:25]
	v_mfma_f32_16x16x32_bf16 v[18:21], v[168:171], v[210:213], v[18:21]
	v_mfma_f32_16x16x32_bf16 v[6:9], v[146:149], v[236:239], v[6:9]
	v_mfma_f32_16x16x32_bf16 v[2:5], v[168:171], v[236:239], v[2:5]
	v_mfma_f32_16x16x32_bf16 v[54:57], v[150:153], v[180:183], v[54:57]
	v_mfma_f32_16x16x32_bf16 v[50:53], v[172:175], v[180:183], v[50:53]
	v_mfma_f32_16x16x32_bf16 v[38:41], v[150:153], v[206:209], v[38:41]
	v_mfma_f32_16x16x32_bf16 v[34:37], v[172:175], v[206:209], v[34:37]
	v_mfma_f32_16x16x32_bf16 v[22:25], v[150:153], v[232:235], v[22:25]
	v_mfma_f32_16x16x32_bf16 v[18:21], v[172:175], v[232:235], v[18:21]
	v_mfma_f32_16x16x32_bf16 v[6:9], v[150:153], v[240:243], v[6:9]
	v_mfma_f32_16x16x32_bf16 v[2:5], v[172:175], v[240:243], v[2:5]
	s_setprio 0
	s_add_i32 s49, s49, 2
	s_add_u32 s47, s47, 0x100
	s_addc_u32 s48, s48, 0
	s_cmp_gt_u32 s49, 41
	s_mov_b64 s[18:19], s[20:21]
	s_barrier
	s_cbranch_scc0 .LBB0_1438
	s_and_b64 vcc, exec, s[14:15]
	s_cbranch_vccz .LBB0_1441
	s_barrier
